# scan: one normalisation block per 32-step chunk (staging waves hand the running log-decay sum to each other through LDS); scan waves rescale once per chunk instead of every 8 steps
# speedup vs baseline: 1.0114x; 1.0114x over previous
.Lsc_item:
	v_lshlrev_b32_e32 v164, 2, v0
	v_add_u32_e32 v164, 139776, v164
	v_xor_b32_e32 v164, 16, v164
	ds_write_b32 v164, v169
	v_and_b32_e32 v163, 3, v0
	v_lshlrev_b32_e32 v163, 2, v163
	v_add_u32_e32 v163, 139808, v163
	ds_write_b32 v163, v169
	s_waitcnt lgkmcnt(0)
	s_barrier
	s_cmp_ge_u32 s7, 4
	s_cbranch_scc1 .Lsc_G
	v_lshlrev_b32_e32 v27, 2, v173
	v_and_b32_e32 v27, 60, v27
	v_lshlrev_b32_e32 v7, 2, v0
	v_bfe_u32 v1, v173, 4, 2
	v_or_b32_e32 v37, v7, v1
	v_lshlrev_b32_e32 v37, 6, v37
	v_and_b32_e32 v36, 15, v173
	v_lshl_add_u32 v37, v36, 2, v37
	v_add_u32_e32 v37, 74240, v37
	v_and_b32_e32 v34, 15, v173
	v_lshlrev_b32_e32 v34, 4, v34
	v_or_b32_e32 v35, v7, v1
	v_mul_u32_u24_e32 v35, 144, v35
	v_add_u32_e32 v35, 69632, v35
	v_mov_b32_e32 v8, 0
	v_mov_b32_e32 v9, 0
	v_mov_b32_e32 v10, 0
	v_mov_b32_e32 v11, 0
	v_add_u32_e32 v48, 34816, v34
	v_add_u32_e32 v49, 2304, v35
	v_add_u32_e32 v50, 32768, v37
	v_mov_b32_e32 v51, 0
	v_mov_b32_e32 v52, 139776
	v_mov_b32_e32 v53, v164
	s_mov_b32 s6, 0
	s_mov_b32 s55, 0x100000

.Lsc_S_loop:
	s_waitcnt lgkmcnt(3)
	v_pk_fma_f32 v[10:11], v[80:81], v[30:31], v[16:17] op_sel_hi:[1,0,1] neg_lo:[0,1,0] neg_hi:[0,1,0]
	v_pk_fma_f32 v[8:9], v[82:83], v[30:31], v[18:19] op_sel_hi:[1,0,1] neg_lo:[0,1,0] neg_hi:[0,1,0]
	v_pk_mul_f32 v[24:25], v[10:11], v[84:85] op_sel:[0,0] op_sel_hi:[0,1]
	v_pk_fma_f32 v[24:25], v[10:11], v[86:87], v[24:25] op_sel:[1,0,0] op_sel_hi:[1,1,1]
	v_pk_fma_f32 v[24:25], v[8:9], v[88:89], v[24:25] op_sel:[0,0,0] op_sel_hi:[0,1,1]
	v_pk_fma_f32 v[24:25], v[8:9], v[90:91], v[24:25] op_sel:[1,0,0] op_sel_hi:[1,1,1]
	v_pk_fma_f32 v[16:17], v[92:93], v[156:157], v[10:11] op_sel:[0,1,0] op_sel_hi:[1,1,1]
	v_pk_fma_f32 v[18:19], v[94:95], v[156:157], v[8:9] op_sel:[0,1,0] op_sel_hi:[1,1,1]
	v_add_f32_dpp v15, v24, v24 row_ror:8 row_mask:0xf bank_mask:0xf bound_ctrl:1
	ds_read_b128 v[124:127], v34 offset:3072
	s_nop 0
	v_add_f32_dpp v15, v15, v15 row_ror:4 row_mask:0xf bank_mask:0xf bound_ctrl:1
	ds_read_b128 v[128:131], v34 offset:3328
	ds_read_b128 v[132:135], v34 offset:3584
	v_add_f32_dpp v15, v15, v15 row_ror:2 row_mask:0xf bank_mask:0xf bound_ctrl:1
	ds_read_b128 v[136:139], v34 offset:3840
	ds_read_b128 v[160:163], v35 offset:16
	v_add_f32_dpp v30, v15, v15 row_ror:1 row_mask:0xf bank_mask:0xf bound_ctrl:1
	v_pk_fma_f32 v[10:11], v[96:97], v[30:31], v[16:17] op_sel_hi:[1,0,1] neg_lo:[0,1,0] neg_hi:[0,1,0]
	v_pk_fma_f32 v[8:9], v[98:99], v[30:31], v[18:19] op_sel_hi:[1,0,1] neg_lo:[0,1,0] neg_hi:[0,1,0]
	v_pk_mul_f32 v[26:27], v[10:11], v[100:101] op_sel:[0,0] op_sel_hi:[0,1]
	v_pk_fma_f32 v[26:27], v[10:11], v[102:103], v[26:27] op_sel:[1,0,0] op_sel_hi:[1,1,1]
	v_pk_fma_f32 v[26:27], v[8:9], v[104:105], v[26:27] op_sel:[0,0,0] op_sel_hi:[0,1,1]
	v_pk_fma_f32 v[26:27], v[8:9], v[106:107], v[26:27] op_sel:[1,0,0] op_sel_hi:[1,1,1]
	v_pk_fma_f32 v[16:17], v[108:109], v[158:159], v[10:11] op_sel_hi:[1,0,1]
	v_pk_fma_f32 v[18:19], v[110:111], v[158:159], v[8:9] op_sel_hi:[1,0,1]
	v_add_f32_dpp v15, v26, v26 row_ror:8 row_mask:0xf bank_mask:0xf bound_ctrl:1
	ds_read_b128 v[76:79], v34 offset:4096
	s_nop 0
	v_add_f32_dpp v15, v15, v15 row_ror:4 row_mask:0xf bank_mask:0xf bound_ctrl:1
	ds_read_b128 v[80:83], v34 offset:4352
	ds_read_b128 v[84:87], v34 offset:4608
	v_add_f32_dpp v15, v15, v15 row_ror:2 row_mask:0xf bank_mask:0xf bound_ctrl:1
	ds_read_b128 v[88:91], v34 offset:4864
	ds_write2st64_b32 v37, v25, v27 offset0:0 offset1:4
	v_add_f32_dpp v30, v15, v15 row_ror:1 row_mask:0xf bank_mask:0xf bound_ctrl:1
	s_waitcnt lgkmcnt(4)
	v_pk_fma_f32 v[10:11], v[112:113], v[30:31], v[16:17] op_sel_hi:[1,0,1] neg_lo:[0,1,0] neg_hi:[0,1,0]
	v_pk_fma_f32 v[8:9], v[114:115], v[30:31], v[18:19] op_sel_hi:[1,0,1] neg_lo:[0,1,0] neg_hi:[0,1,0]
	v_pk_mul_f32 v[24:25], v[10:11], v[116:117] op_sel:[0,0] op_sel_hi:[0,1]
	v_pk_fma_f32 v[24:25], v[10:11], v[118:119], v[24:25] op_sel:[1,0,0] op_sel_hi:[1,1,1]
	v_pk_fma_f32 v[24:25], v[8:9], v[120:121], v[24:25] op_sel:[0,0,0] op_sel_hi:[0,1,1]
	v_pk_fma_f32 v[24:25], v[8:9], v[122:123], v[24:25] op_sel:[1,0,0] op_sel_hi:[1,1,1]
	v_pk_fma_f32 v[16:17], v[124:125], v[158:159], v[10:11] op_sel:[0,1,0] op_sel_hi:[1,1,1]
	v_pk_fma_f32 v[18:19], v[126:127], v[158:159], v[8:9] op_sel:[0,1,0] op_sel_hi:[1,1,1]
	v_add_f32_dpp v15, v24, v24 row_ror:8 row_mask:0xf bank_mask:0xf bound_ctrl:1
	ds_read_b128 v[92:95], v34 offset:5120
	s_nop 0
	v_add_f32_dpp v15, v15, v15 row_ror:4 row_mask:0xf bank_mask:0xf bound_ctrl:1
	ds_read_b128 v[96:99], v34 offset:5376
	ds_read_b128 v[100:103], v34 offset:5632
	v_add_f32_dpp v15, v15, v15 row_ror:2 row_mask:0xf bank_mask:0xf bound_ctrl:1
	ds_read_b128 v[104:107], v34 offset:5888
	s_nop 0
	v_add_f32_dpp v30, v15, v15 row_ror:1 row_mask:0xf bank_mask:0xf bound_ctrl:1
	v_pk_fma_f32 v[10:11], v[128:129], v[30:31], v[16:17] op_sel_hi:[1,0,1] neg_lo:[0,1,0] neg_hi:[0,1,0]
	v_pk_fma_f32 v[8:9], v[130:131], v[30:31], v[18:19] op_sel_hi:[1,0,1] neg_lo:[0,1,0] neg_hi:[0,1,0]
	v_pk_mul_f32 v[26:27], v[10:11], v[132:133] op_sel:[0,0] op_sel_hi:[0,1]
	v_pk_fma_f32 v[26:27], v[10:11], v[134:135], v[26:27] op_sel:[1,0,0] op_sel_hi:[1,1,1]
	v_pk_fma_f32 v[26:27], v[8:9], v[136:137], v[26:27] op_sel:[0,0,0] op_sel_hi:[0,1,1]
	v_pk_fma_f32 v[26:27], v[8:9], v[138:139], v[26:27] op_sel:[1,0,0] op_sel_hi:[1,1,1]
	v_pk_fma_f32 v[16:17], v[76:77], v[160:161], v[10:11] op_sel_hi:[1,0,1]
	v_pk_fma_f32 v[18:19], v[78:79], v[160:161], v[8:9] op_sel_hi:[1,0,1]
	v_add_f32_dpp v15, v26, v26 row_ror:8 row_mask:0xf bank_mask:0xf bound_ctrl:1
	ds_read_b128 v[108:111], v34 offset:6144
	s_nop 0
	v_add_f32_dpp v15, v15, v15 row_ror:4 row_mask:0xf bank_mask:0xf bound_ctrl:1
	ds_read_b128 v[112:115], v34 offset:6400
	ds_read_b128 v[116:119], v34 offset:6656
	v_add_f32_dpp v15, v15, v15 row_ror:2 row_mask:0xf bank_mask:0xf bound_ctrl:1
	ds_read_b128 v[120:123], v34 offset:6912
	ds_write2st64_b32 v37, v25, v27 offset0:8 offset1:12
	v_add_f32_dpp v30, v15, v15 row_ror:1 row_mask:0xf bank_mask:0xf bound_ctrl:1
	s_waitcnt lgkmcnt(4)
	v_pk_fma_f32 v[10:11], v[80:81], v[30:31], v[16:17] op_sel_hi:[1,0,1] neg_lo:[0,1,0] neg_hi:[0,1,0]
	v_pk_fma_f32 v[8:9], v[82:83], v[30:31], v[18:19] op_sel_hi:[1,0,1] neg_lo:[0,1,0] neg_hi:[0,1,0]
	v_pk_mul_f32 v[24:25], v[10:11], v[84:85] op_sel:[0,0] op_sel_hi:[0,1]
	v_pk_fma_f32 v[24:25], v[10:11], v[86:87], v[24:25] op_sel:[1,0,0] op_sel_hi:[1,1,1]
	v_pk_fma_f32 v[24:25], v[8:9], v[88:89], v[24:25] op_sel:[0,0,0] op_sel_hi:[0,1,1]
	v_pk_fma_f32 v[24:25], v[8:9], v[90:91], v[24:25] op_sel:[1,0,0] op_sel_hi:[1,1,1]
	v_pk_fma_f32 v[16:17], v[92:93], v[160:161], v[10:11] op_sel:[0,1,0] op_sel_hi:[1,1,1]
	v_pk_fma_f32 v[18:19], v[94:95], v[160:161], v[8:9] op_sel:[0,1,0] op_sel_hi:[1,1,1]
	v_add_f32_dpp v15, v24, v24 row_ror:8 row_mask:0xf bank_mask:0xf bound_ctrl:1
	ds_read_b128 v[124:127], v34 offset:7168
	s_nop 0
	v_add_f32_dpp v15, v15, v15 row_ror:4 row_mask:0xf bank_mask:0xf bound_ctrl:1
	ds_read_b128 v[128:131], v34 offset:7424
	ds_read_b128 v[132:135], v34 offset:7680
	v_add_f32_dpp v15, v15, v15 row_ror:2 row_mask:0xf bank_mask:0xf bound_ctrl:1
	ds_read_b128 v[136:139], v34 offset:7936
	ds_read_b128 v[156:159], v35 offset:32
	v_add_f32_dpp v30, v15, v15 row_ror:1 row_mask:0xf bank_mask:0xf bound_ctrl:1
	v_pk_fma_f32 v[10:11], v[96:97], v[30:31], v[16:17] op_sel_hi:[1,0,1] neg_lo:[0,1,0] neg_hi:[0,1,0]
	v_pk_fma_f32 v[8:9], v[98:99], v[30:31], v[18:19] op_sel_hi:[1,0,1] neg_lo:[0,1,0] neg_hi:[0,1,0]
	v_pk_mul_f32 v[26:27], v[10:11], v[100:101] op_sel:[0,0] op_sel_hi:[0,1]
	v_pk_fma_f32 v[26:27], v[10:11], v[102:103], v[26:27] op_sel:[1,0,0] op_sel_hi:[1,1,1]
	v_pk_fma_f32 v[26:27], v[8:9], v[104:105], v[26:27] op_sel:[0,0,0] op_sel_hi:[0,1,1]
	v_pk_fma_f32 v[26:27], v[8:9], v[106:107], v[26:27] op_sel:[1,0,0] op_sel_hi:[1,1,1]
	v_pk_fma_f32 v[16:17], v[108:109], v[162:163], v[10:11] op_sel_hi:[1,0,1]
	v_pk_fma_f32 v[18:19], v[110:111], v[162:163], v[8:9] op_sel_hi:[1,0,1]
	v_add_f32_dpp v15, v26, v26 row_ror:8 row_mask:0xf bank_mask:0xf bound_ctrl:1
	ds_read_b128 v[76:79], v34 offset:8192
	s_nop 0
	v_add_f32_dpp v15, v15, v15 row_ror:4 row_mask:0xf bank_mask:0xf bound_ctrl:1
	ds_read_b128 v[80:83], v34 offset:8448
	ds_read_b128 v[84:87], v34 offset:8704
	v_add_f32_dpp v15, v15, v15 row_ror:2 row_mask:0xf bank_mask:0xf bound_ctrl:1
	ds_read_b128 v[88:91], v34 offset:8960
	ds_write2st64_b32 v37, v25, v27 offset0:16 offset1:20
	v_add_f32_dpp v30, v15, v15 row_ror:1 row_mask:0xf bank_mask:0xf bound_ctrl:1
	s_waitcnt lgkmcnt(4)
	v_pk_fma_f32 v[10:11], v[112:113], v[30:31], v[16:17] op_sel_hi:[1,0,1] neg_lo:[0,1,0] neg_hi:[0,1,0]
	v_pk_fma_f32 v[8:9], v[114:115], v[30:31], v[18:19] op_sel_hi:[1,0,1] neg_lo:[0,1,0] neg_hi:[0,1,0]
	v_pk_mul_f32 v[24:25], v[10:11], v[116:117] op_sel:[0,0] op_sel_hi:[0,1]
	v_pk_fma_f32 v[24:25], v[10:11], v[118:119], v[24:25] op_sel:[1,0,0] op_sel_hi:[1,1,1]
	v_pk_fma_f32 v[24:25], v[8:9], v[120:121], v[24:25] op_sel:[0,0,0] op_sel_hi:[0,1,1]
	v_pk_fma_f32 v[24:25], v[8:9], v[122:123], v[24:25] op_sel:[1,0,0] op_sel_hi:[1,1,1]
	v_pk_fma_f32 v[16:17], v[124:125], v[162:163], v[10:11] op_sel:[0,1,0] op_sel_hi:[1,1,1]
	v_pk_fma_f32 v[18:19], v[126:127], v[162:163], v[8:9] op_sel:[0,1,0] op_sel_hi:[1,1,1]
	v_add_f32_dpp v15, v24, v24 row_ror:8 row_mask:0xf bank_mask:0xf bound_ctrl:1
	ds_read_b128 v[92:95], v34 offset:9216
	s_nop 0
	v_add_f32_dpp v15, v15, v15 row_ror:4 row_mask:0xf bank_mask:0xf bound_ctrl:1
	ds_read_b128 v[96:99], v34 offset:9472
	ds_read_b128 v[100:103], v34 offset:9728
	v_add_f32_dpp v15, v15, v15 row_ror:2 row_mask:0xf bank_mask:0xf bound_ctrl:1
	ds_read_b128 v[104:107], v34 offset:9984
	s_nop 0
	v_add_f32_dpp v30, v15, v15 row_ror:1 row_mask:0xf bank_mask:0xf bound_ctrl:1
	v_pk_fma_f32 v[10:11], v[128:129], v[30:31], v[16:17] op_sel_hi:[1,0,1] neg_lo:[0,1,0] neg_hi:[0,1,0]
	v_pk_fma_f32 v[8:9], v[130:131], v[30:31], v[18:19] op_sel_hi:[1,0,1] neg_lo:[0,1,0] neg_hi:[0,1,0]
	v_pk_mul_f32 v[26:27], v[10:11], v[132:133] op_sel:[0,0] op_sel_hi:[0,1]
	v_pk_fma_f32 v[26:27], v[10:11], v[134:135], v[26:27] op_sel:[1,0,0] op_sel_hi:[1,1,1]
	v_pk_fma_f32 v[26:27], v[8:9], v[136:137], v[26:27] op_sel:[0,0,0] op_sel_hi:[0,1,1]
	v_pk_fma_f32 v[26:27], v[8:9], v[138:139], v[26:27] op_sel:[1,0,0] op_sel_hi:[1,1,1]
	v_pk_fma_f32 v[16:17], v[76:77], v[156:157], v[10:11] op_sel_hi:[1,0,1]
	v_pk_fma_f32 v[18:19], v[78:79], v[156:157], v[8:9] op_sel_hi:[1,0,1]
	v_add_f32_dpp v15, v26, v26 row_ror:8 row_mask:0xf bank_mask:0xf bound_ctrl:1
	ds_read_b128 v[108:111], v34 offset:10240
	s_nop 0
	v_add_f32_dpp v15, v15, v15 row_ror:4 row_mask:0xf bank_mask:0xf bound_ctrl:1
	ds_read_b128 v[112:115], v34 offset:10496
	ds_read_b128 v[116:119], v34 offset:10752
	v_add_f32_dpp v15, v15, v15 row_ror:2 row_mask:0xf bank_mask:0xf bound_ctrl:1
	ds_read_b128 v[120:123], v34 offset:11008
	ds_write2st64_b32 v37, v25, v27 offset0:24 offset1:28
	v_add_f32_dpp v30, v15, v15 row_ror:1 row_mask:0xf bank_mask:0xf bound_ctrl:1
	s_waitcnt lgkmcnt(4)
	v_pk_fma_f32 v[10:11], v[80:81], v[30:31], v[16:17] op_sel_hi:[1,0,1] neg_lo:[0,1,0] neg_hi:[0,1,0]
	v_pk_fma_f32 v[8:9], v[82:83], v[30:31], v[18:19] op_sel_hi:[1,0,1] neg_lo:[0,1,0] neg_hi:[0,1,0]
	v_pk_mul_f32 v[24:25], v[10:11], v[84:85] op_sel:[0,0] op_sel_hi:[0,1]
	v_pk_fma_f32 v[24:25], v[10:11], v[86:87], v[24:25] op_sel:[1,0,0] op_sel_hi:[1,1,1]
	v_pk_fma_f32 v[24:25], v[8:9], v[88:89], v[24:25] op_sel:[0,0,0] op_sel_hi:[0,1,1]
	v_pk_fma_f32 v[24:25], v[8:9], v[90:91], v[24:25] op_sel:[1,0,0] op_sel_hi:[1,1,1]
	v_pk_fma_f32 v[16:17], v[92:93], v[156:157], v[10:11] op_sel:[0,1,0] op_sel_hi:[1,1,1]
	v_pk_fma_f32 v[18:19], v[94:95], v[156:157], v[8:9] op_sel:[0,1,0] op_sel_hi:[1,1,1]
	v_add_f32_dpp v15, v24, v24 row_ror:8 row_mask:0xf bank_mask:0xf bound_ctrl:1
	ds_read_b128 v[124:127], v34 offset:11264
	s_nop 0
	v_add_f32_dpp v15, v15, v15 row_ror:4 row_mask:0xf bank_mask:0xf bound_ctrl:1
	ds_read_b128 v[128:131], v34 offset:11520
	ds_read_b128 v[132:135], v34 offset:11776
	v_add_f32_dpp v15, v15, v15 row_ror:2 row_mask:0xf bank_mask:0xf bound_ctrl:1
	ds_read_b128 v[136:139], v34 offset:12032
	ds_read_b128 v[160:163], v35 offset:48
	v_add_f32_dpp v30, v15, v15 row_ror:1 row_mask:0xf bank_mask:0xf bound_ctrl:1
	v_pk_fma_f32 v[10:11], v[96:97], v[30:31], v[16:17] op_sel_hi:[1,0,1] neg_lo:[0,1,0] neg_hi:[0,1,0]
	v_pk_fma_f32 v[8:9], v[98:99], v[30:31], v[18:19] op_sel_hi:[1,0,1] neg_lo:[0,1,0] neg_hi:[0,1,0]
	v_pk_mul_f32 v[26:27], v[10:11], v[100:101] op_sel:[0,0] op_sel_hi:[0,1]
	v_pk_fma_f32 v[26:27], v[10:11], v[102:103], v[26:27] op_sel:[1,0,0] op_sel_hi:[1,1,1]
	v_pk_fma_f32 v[26:27], v[8:9], v[104:105], v[26:27] op_sel:[0,0,0] op_sel_hi:[0,1,1]
	v_pk_fma_f32 v[26:27], v[8:9], v[106:107], v[26:27] op_sel:[1,0,0] op_sel_hi:[1,1,1]
	v_pk_fma_f32 v[16:17], v[108:109], v[158:159], v[10:11] op_sel_hi:[1,0,1]
	v_pk_fma_f32 v[18:19], v[110:111], v[158:159], v[8:9] op_sel_hi:[1,0,1]
	v_add_f32_dpp v15, v26, v26 row_ror:8 row_mask:0xf bank_mask:0xf bound_ctrl:1
	ds_read_b128 v[76:79], v34 offset:12288
	s_nop 0
	v_add_f32_dpp v15, v15, v15 row_ror:4 row_mask:0xf bank_mask:0xf bound_ctrl:1
	ds_read_b128 v[80:83], v34 offset:12544
	ds_read_b128 v[84:87], v34 offset:12800
	v_add_f32_dpp v15, v15, v15 row_ror:2 row_mask:0xf bank_mask:0xf bound_ctrl:1
	ds_read_b128 v[88:91], v34 offset:13056
	ds_write2st64_b32 v37, v25, v27 offset0:32 offset1:36
	v_add_f32_dpp v30, v15, v15 row_ror:1 row_mask:0xf bank_mask:0xf bound_ctrl:1
	s_waitcnt lgkmcnt(4)
	v_pk_fma_f32 v[10:11], v[112:113], v[30:31], v[16:17] op_sel_hi:[1,0,1] neg_lo:[0,1,0] neg_hi:[0,1,0]
	v_pk_fma_f32 v[8:9], v[114:115], v[30:31], v[18:19] op_sel_hi:[1,0,1] neg_lo:[0,1,0] neg_hi:[0,1,0]
	v_pk_mul_f32 v[24:25], v[10:11], v[116:117] op_sel:[0,0] op_sel_hi:[0,1]
	v_pk_fma_f32 v[24:25], v[10:11], v[118:119], v[24:25] op_sel:[1,0,0] op_sel_hi:[1,1,1]
	v_pk_fma_f32 v[24:25], v[8:9], v[120:121], v[24:25] op_sel:[0,0,0] op_sel_hi:[0,1,1]
	v_pk_fma_f32 v[24:25], v[8:9], v[122:123], v[24:25] op_sel:[1,0,0] op_sel_hi:[1,1,1]
	v_pk_fma_f32 v[16:17], v[124:125], v[158:159], v[10:11] op_sel:[0,1,0] op_sel_hi:[1,1,1]
	v_pk_fma_f32 v[18:19], v[126:127], v[158:159], v[8:9] op_sel:[0,1,0] op_sel_hi:[1,1,1]
	v_add_f32_dpp v15, v24, v24 row_ror:8 row_mask:0xf bank_mask:0xf bound_ctrl:1
	ds_read_b128 v[92:95], v34 offset:13312
	s_nop 0
	v_add_f32_dpp v15, v15, v15 row_ror:4 row_mask:0xf bank_mask:0xf bound_ctrl:1
	ds_read_b128 v[96:99], v34 offset:13568
	ds_read_b128 v[100:103], v34 offset:13824
	v_add_f32_dpp v15, v15, v15 row_ror:2 row_mask:0xf bank_mask:0xf bound_ctrl:1
	ds_read_b128 v[104:107], v34 offset:14080
	s_nop 0
	v_add_f32_dpp v30, v15, v15 row_ror:1 row_mask:0xf bank_mask:0xf bound_ctrl:1
	v_pk_fma_f32 v[10:11], v[128:129], v[30:31], v[16:17] op_sel_hi:[1,0,1] neg_lo:[0,1,0] neg_hi:[0,1,0]
	v_pk_fma_f32 v[8:9], v[130:131], v[30:31], v[18:19] op_sel_hi:[1,0,1] neg_lo:[0,1,0] neg_hi:[0,1,0]
	v_pk_mul_f32 v[26:27], v[10:11], v[132:133] op_sel:[0,0] op_sel_hi:[0,1]
	v_pk_fma_f32 v[26:27], v[10:11], v[134:135], v[26:27] op_sel:[1,0,0] op_sel_hi:[1,1,1]
	v_pk_fma_f32 v[26:27], v[8:9], v[136:137], v[26:27] op_sel:[0,0,0] op_sel_hi:[0,1,1]
	v_pk_fma_f32 v[26:27], v[8:9], v[138:139], v[26:27] op_sel:[1,0,0] op_sel_hi:[1,1,1]
	v_pk_fma_f32 v[16:17], v[76:77], v[160:161], v[10:11] op_sel_hi:[1,0,1]
	v_pk_fma_f32 v[18:19], v[78:79], v[160:161], v[8:9] op_sel_hi:[1,0,1]
	v_add_f32_dpp v15, v26, v26 row_ror:8 row_mask:0xf bank_mask:0xf bound_ctrl:1
	ds_read_b128 v[108:111], v34 offset:14336
	s_nop 0
	v_add_f32_dpp v15, v15, v15 row_ror:4 row_mask:0xf bank_mask:0xf bound_ctrl:1
	ds_read_b128 v[112:115], v34 offset:14592
	ds_read_b128 v[116:119], v34 offset:14848
	v_add_f32_dpp v15, v15, v15 row_ror:2 row_mask:0xf bank_mask:0xf bound_ctrl:1
	ds_read_b128 v[120:123], v34 offset:15104
	ds_write2st64_b32 v37, v25, v27 offset0:40 offset1:44
	v_add_f32_dpp v30, v15, v15 row_ror:1 row_mask:0xf bank_mask:0xf bound_ctrl:1
	s_waitcnt lgkmcnt(4)
	v_pk_fma_f32 v[10:11], v[80:81], v[30:31], v[16:17] op_sel_hi:[1,0,1] neg_lo:[0,1,0] neg_hi:[0,1,0]
	v_pk_fma_f32 v[8:9], v[82:83], v[30:31], v[18:19] op_sel_hi:[1,0,1] neg_lo:[0,1,0] neg_hi:[0,1,0]
	v_pk_mul_f32 v[24:25], v[10:11], v[84:85] op_sel:[0,0] op_sel_hi:[0,1]
	v_pk_fma_f32 v[24:25], v[10:11], v[86:87], v[24:25] op_sel:[1,0,0] op_sel_hi:[1,1,1]
	v_pk_fma_f32 v[24:25], v[8:9], v[88:89], v[24:25] op_sel:[0,0,0] op_sel_hi:[0,1,1]
	v_pk_fma_f32 v[24:25], v[8:9], v[90:91], v[24:25] op_sel:[1,0,0] op_sel_hi:[1,1,1]
	v_pk_fma_f32 v[16:17], v[92:93], v[160:161], v[10:11] op_sel:[0,1,0] op_sel_hi:[1,1,1]
	v_pk_fma_f32 v[18:19], v[94:95], v[160:161], v[8:9] op_sel:[0,1,0] op_sel_hi:[1,1,1]
	v_add_f32_dpp v15, v24, v24 row_ror:8 row_mask:0xf bank_mask:0xf bound_ctrl:1
	ds_read_b128 v[124:127], v34 offset:15360
	s_nop 0
	v_add_f32_dpp v15, v15, v15 row_ror:4 row_mask:0xf bank_mask:0xf bound_ctrl:1
	ds_read_b128 v[128:131], v34 offset:15616
	ds_read_b128 v[132:135], v34 offset:15872
	v_add_f32_dpp v15, v15, v15 row_ror:2 row_mask:0xf bank_mask:0xf bound_ctrl:1
	ds_read_b128 v[136:139], v34 offset:16128
	ds_read_b128 v[156:159], v35 offset:64
	v_add_f32_dpp v30, v15, v15 row_ror:1 row_mask:0xf bank_mask:0xf bound_ctrl:1
	v_pk_fma_f32 v[10:11], v[96:97], v[30:31], v[16:17] op_sel_hi:[1,0,1] neg_lo:[0,1,0] neg_hi:[0,1,0]
	v_pk_fma_f32 v[8:9], v[98:99], v[30:31], v[18:19] op_sel_hi:[1,0,1] neg_lo:[0,1,0] neg_hi:[0,1,0]
	v_pk_mul_f32 v[26:27], v[10:11], v[100:101] op_sel:[0,0] op_sel_hi:[0,1]
	v_pk_fma_f32 v[26:27], v[10:11], v[102:103], v[26:27] op_sel:[1,0,0] op_sel_hi:[1,1,1]
	v_pk_fma_f32 v[26:27], v[8:9], v[104:105], v[26:27] op_sel:[0,0,0] op_sel_hi:[0,1,1]
	v_pk_fma_f32 v[26:27], v[8:9], v[106:107], v[26:27] op_sel:[1,0,0] op_sel_hi:[1,1,1]
	v_pk_fma_f32 v[16:17], v[108:109], v[162:163], v[10:11] op_sel_hi:[1,0,1]
	v_pk_fma_f32 v[18:19], v[110:111], v[162:163], v[8:9] op_sel_hi:[1,0,1]
	v_add_f32_dpp v15, v26, v26 row_ror:8 row_mask:0xf bank_mask:0xf bound_ctrl:1
	ds_read_b128 v[76:79], v34 offset:16384
	s_nop 0
	v_add_f32_dpp v15, v15, v15 row_ror:4 row_mask:0xf bank_mask:0xf bound_ctrl:1
	ds_read_b128 v[80:83], v34 offset:16640
	ds_read_b128 v[84:87], v34 offset:16896
	v_add_f32_dpp v15, v15, v15 row_ror:2 row_mask:0xf bank_mask:0xf bound_ctrl:1
	ds_read_b128 v[88:91], v34 offset:17152
	ds_write2st64_b32 v37, v25, v27 offset0:48 offset1:52
	v_add_f32_dpp v30, v15, v15 row_ror:1 row_mask:0xf bank_mask:0xf bound_ctrl:1
	s_waitcnt lgkmcnt(4)
	v_pk_fma_f32 v[10:11], v[112:113], v[30:31], v[16:17] op_sel_hi:[1,0,1] neg_lo:[0,1,0] neg_hi:[0,1,0]
	v_pk_fma_f32 v[8:9], v[114:115], v[30:31], v[18:19] op_sel_hi:[1,0,1] neg_lo:[0,1,0] neg_hi:[0,1,0]
	v_pk_mul_f32 v[24:25], v[10:11], v[116:117] op_sel:[0,0] op_sel_hi:[0,1]
	v_pk_fma_f32 v[24:25], v[10:11], v[118:119], v[24:25] op_sel:[1,0,0] op_sel_hi:[1,1,1]
	v_pk_fma_f32 v[24:25], v[8:9], v[120:121], v[24:25] op_sel:[0,0,0] op_sel_hi:[0,1,1]
	v_pk_fma_f32 v[24:25], v[8:9], v[122:123], v[24:25] op_sel:[1,0,0] op_sel_hi:[1,1,1]
	v_pk_fma_f32 v[16:17], v[124:125], v[162:163], v[10:11] op_sel:[0,1,0] op_sel_hi:[1,1,1]
	v_pk_fma_f32 v[18:19], v[126:127], v[162:163], v[8:9] op_sel:[0,1,0] op_sel_hi:[1,1,1]
	v_add_f32_dpp v15, v24, v24 row_ror:8 row_mask:0xf bank_mask:0xf bound_ctrl:1
	ds_read_b128 v[92:95], v34 offset:17408
	s_nop 0
	v_add_f32_dpp v15, v15, v15 row_ror:4 row_mask:0xf bank_mask:0xf bound_ctrl:1
	ds_read_b128 v[96:99], v34 offset:17664
	ds_read_b128 v[100:103], v34 offset:17920
	v_add_f32_dpp v15, v15, v15 row_ror:2 row_mask:0xf bank_mask:0xf bound_ctrl:1
	ds_read_b128 v[104:107], v34 offset:18176
	s_nop 0
	v_add_f32_dpp v30, v15, v15 row_ror:1 row_mask:0xf bank_mask:0xf bound_ctrl:1
	v_pk_fma_f32 v[10:11], v[128:129], v[30:31], v[16:17] op_sel_hi:[1,0,1] neg_lo:[0,1,0] neg_hi:[0,1,0]
	v_pk_fma_f32 v[8:9], v[130:131], v[30:31], v[18:19] op_sel_hi:[1,0,1] neg_lo:[0,1,0] neg_hi:[0,1,0]
	v_pk_mul_f32 v[26:27], v[10:11], v[132:133] op_sel:[0,0] op_sel_hi:[0,1]
	v_pk_fma_f32 v[26:27], v[10:11], v[134:135], v[26:27] op_sel:[1,0,0] op_sel_hi:[1,1,1]
	v_pk_fma_f32 v[26:27], v[8:9], v[136:137], v[26:27] op_sel:[0,0,0] op_sel_hi:[0,1,1]
	v_pk_fma_f32 v[26:27], v[8:9], v[138:139], v[26:27] op_sel:[1,0,0] op_sel_hi:[1,1,1]
	v_pk_fma_f32 v[16:17], v[76:77], v[156:157], v[10:11] op_sel_hi:[1,0,1]
	v_pk_fma_f32 v[18:19], v[78:79], v[156:157], v[8:9] op_sel_hi:[1,0,1]
	v_add_f32_dpp v15, v26, v26 row_ror:8 row_mask:0xf bank_mask:0xf bound_ctrl:1
	ds_read_b128 v[108:111], v34 offset:18432
	s_nop 0
	v_add_f32_dpp v15, v15, v15 row_ror:4 row_mask:0xf bank_mask:0xf bound_ctrl:1
	ds_read_b128 v[112:115], v34 offset:18688
	ds_read_b128 v[116:119], v34 offset:18944
	v_add_f32_dpp v15, v15, v15 row_ror:2 row_mask:0xf bank_mask:0xf bound_ctrl:1
	ds_read_b128 v[120:123], v34 offset:19200
	ds_write2st64_b32 v37, v25, v27 offset0:56 offset1:60
	v_add_f32_dpp v30, v15, v15 row_ror:1 row_mask:0xf bank_mask:0xf bound_ctrl:1
	s_waitcnt lgkmcnt(4)
	v_pk_fma_f32 v[10:11], v[80:81], v[30:31], v[16:17] op_sel_hi:[1,0,1] neg_lo:[0,1,0] neg_hi:[0,1,0]
	v_pk_fma_f32 v[8:9], v[82:83], v[30:31], v[18:19] op_sel_hi:[1,0,1] neg_lo:[0,1,0] neg_hi:[0,1,0]
	v_pk_mul_f32 v[24:25], v[10:11], v[84:85] op_sel:[0,0] op_sel_hi:[0,1]
	v_pk_fma_f32 v[24:25], v[10:11], v[86:87], v[24:25] op_sel:[1,0,0] op_sel_hi:[1,1,1]
	v_pk_fma_f32 v[24:25], v[8:9], v[88:89], v[24:25] op_sel:[0,0,0] op_sel_hi:[0,1,1]
	v_pk_fma_f32 v[24:25], v[8:9], v[90:91], v[24:25] op_sel:[1,0,0] op_sel_hi:[1,1,1]
	v_pk_fma_f32 v[16:17], v[92:93], v[156:157], v[10:11] op_sel:[0,1,0] op_sel_hi:[1,1,1]
	v_pk_fma_f32 v[18:19], v[94:95], v[156:157], v[8:9] op_sel:[0,1,0] op_sel_hi:[1,1,1]
	v_add_f32_dpp v15, v24, v24 row_ror:8 row_mask:0xf bank_mask:0xf bound_ctrl:1
	ds_read_b128 v[124:127], v34 offset:19456
	s_nop 0
	v_add_f32_dpp v15, v15, v15 row_ror:4 row_mask:0xf bank_mask:0xf bound_ctrl:1
	ds_read_b128 v[128:131], v34 offset:19712
	ds_read_b128 v[132:135], v34 offset:19968
	v_add_f32_dpp v15, v15, v15 row_ror:2 row_mask:0xf bank_mask:0xf bound_ctrl:1
	ds_read_b128 v[136:139], v34 offset:20224
	ds_read_b128 v[160:163], v35 offset:80
	v_add_f32_dpp v30, v15, v15 row_ror:1 row_mask:0xf bank_mask:0xf bound_ctrl:1
	v_pk_fma_f32 v[10:11], v[96:97], v[30:31], v[16:17] op_sel_hi:[1,0,1] neg_lo:[0,1,0] neg_hi:[0,1,0]
	v_pk_fma_f32 v[8:9], v[98:99], v[30:31], v[18:19] op_sel_hi:[1,0,1] neg_lo:[0,1,0] neg_hi:[0,1,0]
	v_pk_mul_f32 v[26:27], v[10:11], v[100:101] op_sel:[0,0] op_sel_hi:[0,1]
	v_pk_fma_f32 v[26:27], v[10:11], v[102:103], v[26:27] op_sel:[1,0,0] op_sel_hi:[1,1,1]
	v_pk_fma_f32 v[26:27], v[8:9], v[104:105], v[26:27] op_sel:[0,0,0] op_sel_hi:[0,1,1]
	v_pk_fma_f32 v[26:27], v[8:9], v[106:107], v[26:27] op_sel:[1,0,0] op_sel_hi:[1,1,1]
	v_pk_fma_f32 v[16:17], v[108:109], v[158:159], v[10:11] op_sel_hi:[1,0,1]
	v_pk_fma_f32 v[18:19], v[110:111], v[158:159], v[8:9] op_sel_hi:[1,0,1]
	v_add_f32_dpp v15, v26, v26 row_ror:8 row_mask:0xf bank_mask:0xf bound_ctrl:1
	ds_read_b128 v[76:79], v34 offset:20480
	s_nop 0
	v_add_f32_dpp v15, v15, v15 row_ror:4 row_mask:0xf bank_mask:0xf bound_ctrl:1
	ds_read_b128 v[80:83], v34 offset:20736
	ds_read_b128 v[84:87], v34 offset:20992
	v_add_f32_dpp v15, v15, v15 row_ror:2 row_mask:0xf bank_mask:0xf bound_ctrl:1
	ds_read_b128 v[88:91], v34 offset:21248
	ds_write2st64_b32 v37, v25, v27 offset0:64 offset1:68
	v_add_f32_dpp v30, v15, v15 row_ror:1 row_mask:0xf bank_mask:0xf bound_ctrl:1
	s_waitcnt lgkmcnt(4)
	v_pk_fma_f32 v[10:11], v[112:113], v[30:31], v[16:17] op_sel_hi:[1,0,1] neg_lo:[0,1,0] neg_hi:[0,1,0]
	v_pk_fma_f32 v[8:9], v[114:115], v[30:31], v[18:19] op_sel_hi:[1,0,1] neg_lo:[0,1,0] neg_hi:[0,1,0]
	v_pk_mul_f32 v[24:25], v[10:11], v[116:117] op_sel:[0,0] op_sel_hi:[0,1]
	v_pk_fma_f32 v[24:25], v[10:11], v[118:119], v[24:25] op_sel:[1,0,0] op_sel_hi:[1,1,1]
	v_pk_fma_f32 v[24:25], v[8:9], v[120:121], v[24:25] op_sel:[0,0,0] op_sel_hi:[0,1,1]
	v_pk_fma_f32 v[24:25], v[8:9], v[122:123], v[24:25] op_sel:[1,0,0] op_sel_hi:[1,1,1]
	v_pk_fma_f32 v[16:17], v[124:125], v[158:159], v[10:11] op_sel:[0,1,0] op_sel_hi:[1,1,1]
	v_pk_fma_f32 v[18:19], v[126:127], v[158:159], v[8:9] op_sel:[0,1,0] op_sel_hi:[1,1,1]
	v_add_f32_dpp v15, v24, v24 row_ror:8 row_mask:0xf bank_mask:0xf bound_ctrl:1
	ds_read_b128 v[92:95], v34 offset:21504
	s_nop 0
	v_add_f32_dpp v15, v15, v15 row_ror:4 row_mask:0xf bank_mask:0xf bound_ctrl:1
	ds_read_b128 v[96:99], v34 offset:21760
	ds_read_b128 v[100:103], v34 offset:22016
	v_add_f32_dpp v15, v15, v15 row_ror:2 row_mask:0xf bank_mask:0xf bound_ctrl:1
	ds_read_b128 v[104:107], v34 offset:22272
	s_nop 0
	v_add_f32_dpp v30, v15, v15 row_ror:1 row_mask:0xf bank_mask:0xf bound_ctrl:1
	v_pk_fma_f32 v[10:11], v[128:129], v[30:31], v[16:17] op_sel_hi:[1,0,1] neg_lo:[0,1,0] neg_hi:[0,1,0]
	v_pk_fma_f32 v[8:9], v[130:131], v[30:31], v[18:19] op_sel_hi:[1,0,1] neg_lo:[0,1,0] neg_hi:[0,1,0]
	v_pk_mul_f32 v[26:27], v[10:11], v[132:133] op_sel:[0,0] op_sel_hi:[0,1]
	v_pk_fma_f32 v[26:27], v[10:11], v[134:135], v[26:27] op_sel:[1,0,0] op_sel_hi:[1,1,1]
	v_pk_fma_f32 v[26:27], v[8:9], v[136:137], v[26:27] op_sel:[0,0,0] op_sel_hi:[0,1,1]
	v_pk_fma_f32 v[26:27], v[8:9], v[138:139], v[26:27] op_sel:[1,0,0] op_sel_hi:[1,1,1]
	v_pk_fma_f32 v[16:17], v[76:77], v[160:161], v[10:11] op_sel_hi:[1,0,1]
	v_pk_fma_f32 v[18:19], v[78:79], v[160:161], v[8:9] op_sel_hi:[1,0,1]
	v_add_f32_dpp v15, v26, v26 row_ror:8 row_mask:0xf bank_mask:0xf bound_ctrl:1
	ds_read_b128 v[108:111], v34 offset:22528
	s_nop 0
	v_add_f32_dpp v15, v15, v15 row_ror:4 row_mask:0xf bank_mask:0xf bound_ctrl:1
	ds_read_b128 v[112:115], v34 offset:22784
	ds_read_b128 v[116:119], v34 offset:23040
	v_add_f32_dpp v15, v15, v15 row_ror:2 row_mask:0xf bank_mask:0xf bound_ctrl:1
	ds_read_b128 v[120:123], v34 offset:23296
	ds_write2st64_b32 v37, v25, v27 offset0:72 offset1:76
	v_add_f32_dpp v30, v15, v15 row_ror:1 row_mask:0xf bank_mask:0xf bound_ctrl:1
	s_waitcnt lgkmcnt(4)
	v_pk_fma_f32 v[10:11], v[80:81], v[30:31], v[16:17] op_sel_hi:[1,0,1] neg_lo:[0,1,0] neg_hi:[0,1,0]
	v_pk_fma_f32 v[8:9], v[82:83], v[30:31], v[18:19] op_sel_hi:[1,0,1] neg_lo:[0,1,0] neg_hi:[0,1,0]
	v_pk_mul_f32 v[24:25], v[10:11], v[84:85] op_sel:[0,0] op_sel_hi:[0,1]
	v_pk_fma_f32 v[24:25], v[10:11], v[86:87], v[24:25] op_sel:[1,0,0] op_sel_hi:[1,1,1]
	v_pk_fma_f32 v[24:25], v[8:9], v[88:89], v[24:25] op_sel:[0,0,0] op_sel_hi:[0,1,1]
	v_pk_fma_f32 v[24:25], v[8:9], v[90:91], v[24:25] op_sel:[1,0,0] op_sel_hi:[1,1,1]
	v_pk_fma_f32 v[16:17], v[92:93], v[160:161], v[10:11] op_sel:[0,1,0] op_sel_hi:[1,1,1]
	v_pk_fma_f32 v[18:19], v[94:95], v[160:161], v[8:9] op_sel:[0,1,0] op_sel_hi:[1,1,1]
	v_add_f32_dpp v15, v24, v24 row_ror:8 row_mask:0xf bank_mask:0xf bound_ctrl:1
	ds_read_b128 v[124:127], v34 offset:23552
	s_nop 0
	v_add_f32_dpp v15, v15, v15 row_ror:4 row_mask:0xf bank_mask:0xf bound_ctrl:1
	ds_read_b128 v[128:131], v34 offset:23808
	ds_read_b128 v[132:135], v34 offset:24064
	v_add_f32_dpp v15, v15, v15 row_ror:2 row_mask:0xf bank_mask:0xf bound_ctrl:1
	ds_read_b128 v[136:139], v34 offset:24320
	ds_read_b128 v[156:159], v35 offset:96
	v_add_f32_dpp v30, v15, v15 row_ror:1 row_mask:0xf bank_mask:0xf bound_ctrl:1
	v_pk_fma_f32 v[10:11], v[96:97], v[30:31], v[16:17] op_sel_hi:[1,0,1] neg_lo:[0,1,0] neg_hi:[0,1,0]
	v_pk_fma_f32 v[8:9], v[98:99], v[30:31], v[18:19] op_sel_hi:[1,0,1] neg_lo:[0,1,0] neg_hi:[0,1,0]
	v_pk_mul_f32 v[26:27], v[10:11], v[100:101] op_sel:[0,0] op_sel_hi:[0,1]
	v_pk_fma_f32 v[26:27], v[10:11], v[102:103], v[26:27] op_sel:[1,0,0] op_sel_hi:[1,1,1]
	v_pk_fma_f32 v[26:27], v[8:9], v[104:105], v[26:27] op_sel:[0,0,0] op_sel_hi:[0,1,1]
	v_pk_fma_f32 v[26:27], v[8:9], v[106:107], v[26:27] op_sel:[1,0,0] op_sel_hi:[1,1,1]
	v_pk_fma_f32 v[16:17], v[108:109], v[162:163], v[10:11] op_sel_hi:[1,0,1]
	v_pk_fma_f32 v[18:19], v[110:111], v[162:163], v[8:9] op_sel_hi:[1,0,1]
	v_add_f32_dpp v15, v26, v26 row_ror:8 row_mask:0xf bank_mask:0xf bound_ctrl:1
	ds_read_b128 v[76:79], v34 offset:24576
	s_nop 0
	v_add_f32_dpp v15, v15, v15 row_ror:4 row_mask:0xf bank_mask:0xf bound_ctrl:1
	ds_read_b128 v[80:83], v34 offset:24832
	ds_read_b128 v[84:87], v34 offset:25088
	v_add_f32_dpp v15, v15, v15 row_ror:2 row_mask:0xf bank_mask:0xf bound_ctrl:1
	ds_read_b128 v[88:91], v34 offset:25344
	ds_write2st64_b32 v37, v25, v27 offset0:80 offset1:84
	v_add_f32_dpp v30, v15, v15 row_ror:1 row_mask:0xf bank_mask:0xf bound_ctrl:1
	s_waitcnt lgkmcnt(4)
	v_pk_fma_f32 v[10:11], v[112:113], v[30:31], v[16:17] op_sel_hi:[1,0,1] neg_lo:[0,1,0] neg_hi:[0,1,0]
	v_pk_fma_f32 v[8:9], v[114:115], v[30:31], v[18:19] op_sel_hi:[1,0,1] neg_lo:[0,1,0] neg_hi:[0,1,0]
	v_pk_mul_f32 v[24:25], v[10:11], v[116:117] op_sel:[0,0] op_sel_hi:[0,1]
	v_pk_fma_f32 v[24:25], v[10:11], v[118:119], v[24:25] op_sel:[1,0,0] op_sel_hi:[1,1,1]
	v_pk_fma_f32 v[24:25], v[8:9], v[120:121], v[24:25] op_sel:[0,0,0] op_sel_hi:[0,1,1]
	v_pk_fma_f32 v[24:25], v[8:9], v[122:123], v[24:25] op_sel:[1,0,0] op_sel_hi:[1,1,1]
	v_pk_fma_f32 v[16:17], v[124:125], v[162:163], v[10:11] op_sel:[0,1,0] op_sel_hi:[1,1,1]
	v_pk_fma_f32 v[18:19], v[126:127], v[162:163], v[8:9] op_sel:[0,1,0] op_sel_hi:[1,1,1]
	v_add_f32_dpp v15, v24, v24 row_ror:8 row_mask:0xf bank_mask:0xf bound_ctrl:1
	ds_read_b128 v[92:95], v34 offset:25600
	s_nop 0
	v_add_f32_dpp v15, v15, v15 row_ror:4 row_mask:0xf bank_mask:0xf bound_ctrl:1
	ds_read_b128 v[96:99], v34 offset:25856
	ds_read_b128 v[100:103], v34 offset:26112
	v_add_f32_dpp v15, v15, v15 row_ror:2 row_mask:0xf bank_mask:0xf bound_ctrl:1
	ds_read_b128 v[104:107], v34 offset:26368
	s_nop 0
	v_add_f32_dpp v30, v15, v15 row_ror:1 row_mask:0xf bank_mask:0xf bound_ctrl:1
	v_pk_fma_f32 v[10:11], v[128:129], v[30:31], v[16:17] op_sel_hi:[1,0,1] neg_lo:[0,1,0] neg_hi:[0,1,0]
	v_pk_fma_f32 v[8:9], v[130:131], v[30:31], v[18:19] op_sel_hi:[1,0,1] neg_lo:[0,1,0] neg_hi:[0,1,0]
	v_pk_mul_f32 v[26:27], v[10:11], v[132:133] op_sel:[0,0] op_sel_hi:[0,1]
	v_pk_fma_f32 v[26:27], v[10:11], v[134:135], v[26:27] op_sel:[1,0,0] op_sel_hi:[1,1,1]
	v_pk_fma_f32 v[26:27], v[8:9], v[136:137], v[26:27] op_sel:[0,0,0] op_sel_hi:[0,1,1]
	v_pk_fma_f32 v[26:27], v[8:9], v[138:139], v[26:27] op_sel:[1,0,0] op_sel_hi:[1,1,1]
	v_pk_fma_f32 v[16:17], v[76:77], v[156:157], v[10:11] op_sel_hi:[1,0,1]
	v_pk_fma_f32 v[18:19], v[78:79], v[156:157], v[8:9] op_sel_hi:[1,0,1]
	v_add_f32_dpp v15, v26, v26 row_ror:8 row_mask:0xf bank_mask:0xf bound_ctrl:1
	ds_read_b128 v[108:111], v34 offset:26624
	s_nop 0
	v_add_f32_dpp v15, v15, v15 row_ror:4 row_mask:0xf bank_mask:0xf bound_ctrl:1
	ds_read_b128 v[112:115], v34 offset:26880
	ds_read_b128 v[116:119], v34 offset:27136
	v_add_f32_dpp v15, v15, v15 row_ror:2 row_mask:0xf bank_mask:0xf bound_ctrl:1
	ds_read_b128 v[120:123], v34 offset:27392
	ds_write2st64_b32 v37, v25, v27 offset0:88 offset1:92
	v_add_f32_dpp v30, v15, v15 row_ror:1 row_mask:0xf bank_mask:0xf bound_ctrl:1
	s_waitcnt lgkmcnt(4)
	v_pk_fma_f32 v[10:11], v[80:81], v[30:31], v[16:17] op_sel_hi:[1,0,1] neg_lo:[0,1,0] neg_hi:[0,1,0]
	v_pk_fma_f32 v[8:9], v[82:83], v[30:31], v[18:19] op_sel_hi:[1,0,1] neg_lo:[0,1,0] neg_hi:[0,1,0]
	v_pk_mul_f32 v[24:25], v[10:11], v[84:85] op_sel:[0,0] op_sel_hi:[0,1]
	v_pk_fma_f32 v[24:25], v[10:11], v[86:87], v[24:25] op_sel:[1,0,0] op_sel_hi:[1,1,1]
	v_pk_fma_f32 v[24:25], v[8:9], v[88:89], v[24:25] op_sel:[0,0,0] op_sel_hi:[0,1,1]
	v_pk_fma_f32 v[24:25], v[8:9], v[90:91], v[24:25] op_sel:[1,0,0] op_sel_hi:[1,1,1]
	v_pk_fma_f32 v[16:17], v[92:93], v[156:157], v[10:11] op_sel:[0,1,0] op_sel_hi:[1,1,1]
	v_pk_fma_f32 v[18:19], v[94:95], v[156:157], v[8:9] op_sel:[0,1,0] op_sel_hi:[1,1,1]
	v_add_f32_dpp v15, v24, v24 row_ror:8 row_mask:0xf bank_mask:0xf bound_ctrl:1
	ds_read_b128 v[124:127], v34 offset:27648
	s_nop 0
	v_add_f32_dpp v15, v15, v15 row_ror:4 row_mask:0xf bank_mask:0xf bound_ctrl:1
	ds_read_b128 v[128:131], v34 offset:27904
	ds_read_b128 v[132:135], v34 offset:28160
	v_add_f32_dpp v15, v15, v15 row_ror:2 row_mask:0xf bank_mask:0xf bound_ctrl:1
	ds_read_b128 v[136:139], v34 offset:28416
	ds_read_b128 v[160:163], v35 offset:112
	v_add_f32_dpp v30, v15, v15 row_ror:1 row_mask:0xf bank_mask:0xf bound_ctrl:1
	v_pk_fma_f32 v[10:11], v[96:97], v[30:31], v[16:17] op_sel_hi:[1,0,1] neg_lo:[0,1,0] neg_hi:[0,1,0]
	v_pk_fma_f32 v[8:9], v[98:99], v[30:31], v[18:19] op_sel_hi:[1,0,1] neg_lo:[0,1,0] neg_hi:[0,1,0]
	v_pk_mul_f32 v[26:27], v[10:11], v[100:101] op_sel:[0,0] op_sel_hi:[0,1]
	v_pk_fma_f32 v[26:27], v[10:11], v[102:103], v[26:27] op_sel:[1,0,0] op_sel_hi:[1,1,1]
	v_pk_fma_f32 v[26:27], v[8:9], v[104:105], v[26:27] op_sel:[0,0,0] op_sel_hi:[0,1,1]
	v_pk_fma_f32 v[26:27], v[8:9], v[106:107], v[26:27] op_sel:[1,0,0] op_sel_hi:[1,1,1]
	v_pk_fma_f32 v[16:17], v[108:109], v[158:159], v[10:11] op_sel_hi:[1,0,1]
	v_pk_fma_f32 v[18:19], v[110:111], v[158:159], v[8:9] op_sel_hi:[1,0,1]
	v_add_f32_dpp v15, v26, v26 row_ror:8 row_mask:0xf bank_mask:0xf bound_ctrl:1
	ds_read_b128 v[76:79], v34 offset:28672
	s_nop 0
	v_add_f32_dpp v15, v15, v15 row_ror:4 row_mask:0xf bank_mask:0xf bound_ctrl:1
	ds_read_b128 v[80:83], v34 offset:28928
	ds_read_b128 v[84:87], v34 offset:29184
	v_add_f32_dpp v15, v15, v15 row_ror:2 row_mask:0xf bank_mask:0xf bound_ctrl:1
	ds_read_b128 v[88:91], v34 offset:29440
	ds_write2st64_b32 v37, v25, v27 offset0:96 offset1:100
	v_add_f32_dpp v30, v15, v15 row_ror:1 row_mask:0xf bank_mask:0xf bound_ctrl:1
	ds_read_b128 v[56:59], v52
	s_waitcnt lgkmcnt(5)
	v_pk_fma_f32 v[10:11], v[112:113], v[30:31], v[16:17] op_sel_hi:[1,0,1] neg_lo:[0,1,0] neg_hi:[0,1,0]
	v_pk_fma_f32 v[8:9], v[114:115], v[30:31], v[18:19] op_sel_hi:[1,0,1] neg_lo:[0,1,0] neg_hi:[0,1,0]
	v_pk_mul_f32 v[24:25], v[10:11], v[116:117] op_sel:[0,0] op_sel_hi:[0,1]
	v_pk_fma_f32 v[24:25], v[10:11], v[118:119], v[24:25] op_sel:[1,0,0] op_sel_hi:[1,1,1]
	v_pk_fma_f32 v[24:25], v[8:9], v[120:121], v[24:25] op_sel:[0,0,0] op_sel_hi:[0,1,1]
	v_pk_fma_f32 v[24:25], v[8:9], v[122:123], v[24:25] op_sel:[1,0,0] op_sel_hi:[1,1,1]
	v_pk_fma_f32 v[16:17], v[124:125], v[158:159], v[10:11] op_sel:[0,1,0] op_sel_hi:[1,1,1]
	v_pk_fma_f32 v[18:19], v[126:127], v[158:159], v[8:9] op_sel:[0,1,0] op_sel_hi:[1,1,1]
	v_add_f32_dpp v15, v24, v24 row_ror:8 row_mask:0xf bank_mask:0xf bound_ctrl:1
	ds_read_b128 v[92:95], v34 offset:29696
	s_nop 0
	v_add_f32_dpp v15, v15, v15 row_ror:4 row_mask:0xf bank_mask:0xf bound_ctrl:1
	ds_read_b128 v[96:99], v34 offset:29952
	ds_read_b128 v[100:103], v34 offset:30208
	v_add_f32_dpp v15, v15, v15 row_ror:2 row_mask:0xf bank_mask:0xf bound_ctrl:1
	ds_read_b128 v[104:107], v34 offset:30464
	s_nop 0
	v_add_f32_dpp v30, v15, v15 row_ror:1 row_mask:0xf bank_mask:0xf bound_ctrl:1
	s_waitcnt lgkmcnt(4)
	v_min_u32_e32 v56, v56, v57
	v_min3_u32 v56, v56, v58, v59
	v_pk_fma_f32 v[10:11], v[128:129], v[30:31], v[16:17] op_sel_hi:[1,0,1] neg_lo:[0,1,0] neg_hi:[0,1,0]
	v_pk_fma_f32 v[8:9], v[130:131], v[30:31], v[18:19] op_sel_hi:[1,0,1] neg_lo:[0,1,0] neg_hi:[0,1,0]
	v_pk_mul_f32 v[26:27], v[10:11], v[132:133] op_sel:[0,0] op_sel_hi:[0,1]
	v_pk_fma_f32 v[26:27], v[10:11], v[134:135], v[26:27] op_sel:[1,0,0] op_sel_hi:[1,1,1]
	v_pk_fma_f32 v[26:27], v[8:9], v[136:137], v[26:27] op_sel:[0,0,0] op_sel_hi:[0,1,1]
	v_pk_fma_f32 v[26:27], v[8:9], v[138:139], v[26:27] op_sel:[1,0,0] op_sel_hi:[1,1,1]
	v_pk_fma_f32 v[16:17], v[76:77], v[160:161], v[10:11] op_sel_hi:[1,0,1]
	v_pk_fma_f32 v[18:19], v[78:79], v[160:161], v[8:9] op_sel_hi:[1,0,1]
	v_add_f32_dpp v15, v26, v26 row_ror:8 row_mask:0xf bank_mask:0xf bound_ctrl:1
	ds_read_b128 v[108:111], v34 offset:30720
	s_nop 0
	v_add_f32_dpp v15, v15, v15 row_ror:4 row_mask:0xf bank_mask:0xf bound_ctrl:1
	ds_read_b128 v[112:115], v34 offset:30976
	ds_read_b128 v[116:119], v34 offset:31232
	v_add_f32_dpp v15, v15, v15 row_ror:2 row_mask:0xf bank_mask:0xf bound_ctrl:1
	ds_read_b128 v[120:123], v34 offset:31488
	ds_read_b128 v[140:143], v34 offset:34560
	ds_write2st64_b32 v37, v25, v27 offset0:104 offset1:108
	v_add_f32_dpp v30, v15, v15 row_ror:1 row_mask:0xf bank_mask:0xf bound_ctrl:1
	s_waitcnt lgkmcnt(5)
	v_pk_fma_f32 v[10:11], v[80:81], v[30:31], v[16:17] op_sel_hi:[1,0,1] neg_lo:[0,1,0] neg_hi:[0,1,0]
	v_pk_fma_f32 v[8:9], v[82:83], v[30:31], v[18:19] op_sel_hi:[1,0,1] neg_lo:[0,1,0] neg_hi:[0,1,0]
	v_pk_mul_f32 v[24:25], v[10:11], v[84:85] op_sel:[0,0] op_sel_hi:[0,1]
	v_pk_fma_f32 v[24:25], v[10:11], v[86:87], v[24:25] op_sel:[1,0,0] op_sel_hi:[1,1,1]
	v_pk_fma_f32 v[24:25], v[8:9], v[88:89], v[24:25] op_sel:[0,0,0] op_sel_hi:[0,1,1]
	v_pk_fma_f32 v[24:25], v[8:9], v[90:91], v[24:25] op_sel:[1,0,0] op_sel_hi:[1,1,1]
	v_pk_fma_f32 v[16:17], v[92:93], v[160:161], v[10:11] op_sel:[0,1,0] op_sel_hi:[1,1,1]
	v_pk_fma_f32 v[18:19], v[94:95], v[160:161], v[8:9] op_sel:[0,1,0] op_sel_hi:[1,1,1]
	v_add_f32_dpp v15, v24, v24 row_ror:8 row_mask:0xf bank_mask:0xf bound_ctrl:1
	ds_read_b128 v[124:127], v34 offset:31744
	s_nop 0
	v_add_f32_dpp v15, v15, v15 row_ror:4 row_mask:0xf bank_mask:0xf bound_ctrl:1
	ds_read_b128 v[128:131], v34 offset:32000
	ds_read_b128 v[132:135], v34 offset:32256
	v_add_f32_dpp v15, v15, v15 row_ror:2 row_mask:0xf bank_mask:0xf bound_ctrl:1
	ds_read_b128 v[136:139], v34 offset:32512
	s_nop 0
	v_add_f32_dpp v30, v15, v15 row_ror:1 row_mask:0xf bank_mask:0xf bound_ctrl:1
	v_readfirstlane_b32 s54, v56
	s_add_u32 s64, s6, 2
	s_cmp_lt_u32 s54, s64
	s_cbranch_scc1 .Lss_spin_0
.Lss_ok_0:
	v_pk_fma_f32 v[10:11], v[96:97], v[30:31], v[16:17] op_sel_hi:[1,0,1] neg_lo:[0,1,0] neg_hi:[0,1,0]
	v_pk_fma_f32 v[8:9], v[98:99], v[30:31], v[18:19] op_sel_hi:[1,0,1] neg_lo:[0,1,0] neg_hi:[0,1,0]
	v_pk_mul_f32 v[26:27], v[10:11], v[100:101] op_sel:[0,0] op_sel_hi:[0,1]
	v_pk_fma_f32 v[26:27], v[10:11], v[102:103], v[26:27] op_sel:[1,0,0] op_sel_hi:[1,1,1]
	v_pk_fma_f32 v[26:27], v[8:9], v[104:105], v[26:27] op_sel:[0,0,0] op_sel_hi:[0,1,1]
	v_pk_fma_f32 v[26:27], v[8:9], v[106:107], v[26:27] op_sel:[1,0,0] op_sel_hi:[1,1,1]
	v_pk_fma_f32 v[16:17], v[108:109], v[162:163], v[10:11] op_sel_hi:[1,0,1]
	v_pk_fma_f32 v[18:19], v[110:111], v[162:163], v[8:9] op_sel_hi:[1,0,1]
	v_add_f32_dpp v15, v26, v26 row_ror:8 row_mask:0xf bank_mask:0xf bound_ctrl:1
	ds_read_b128 v[76:79], v48 offset:0
	s_nop 0
	v_add_f32_dpp v15, v15, v15 row_ror:4 row_mask:0xf bank_mask:0xf bound_ctrl:1
	ds_read_b128 v[80:83], v48 offset:256
	ds_read_b128 v[84:87], v48 offset:512
	v_add_f32_dpp v15, v15, v15 row_ror:2 row_mask:0xf bank_mask:0xf bound_ctrl:1
	ds_read_b128 v[88:91], v48 offset:768
	ds_read_b128 v[144:147], v48 offset:32768
	ds_write2st64_b32 v37, v25, v27 offset0:112 offset1:116
	v_add_f32_dpp v30, v15, v15 row_ror:1 row_mask:0xf bank_mask:0xf bound_ctrl:1
	ds_read_b128 v[156:159], v49 offset:0
	s_waitcnt lgkmcnt(6)
	v_pk_fma_f32 v[10:11], v[112:113], v[30:31], v[16:17] op_sel_hi:[1,0,1] neg_lo:[0,1,0] neg_hi:[0,1,0]
	v_pk_fma_f32 v[8:9], v[114:115], v[30:31], v[18:19] op_sel_hi:[1,0,1] neg_lo:[0,1,0] neg_hi:[0,1,0]
	v_pk_mul_f32 v[24:25], v[10:11], v[116:117] op_sel:[0,0] op_sel_hi:[0,1]
	v_pk_fma_f32 v[24:25], v[10:11], v[118:119], v[24:25] op_sel:[1,0,0] op_sel_hi:[1,1,1]
	v_pk_fma_f32 v[24:25], v[8:9], v[120:121], v[24:25] op_sel:[0,0,0] op_sel_hi:[0,1,1]
	v_pk_fma_f32 v[24:25], v[8:9], v[122:123], v[24:25] op_sel:[1,0,0] op_sel_hi:[1,1,1]
	v_pk_fma_f32 v[16:17], v[124:125], v[162:163], v[10:11] op_sel:[0,1,0] op_sel_hi:[1,1,1]
	v_pk_fma_f32 v[18:19], v[126:127], v[162:163], v[8:9] op_sel:[0,1,0] op_sel_hi:[1,1,1]
	v_add_f32_dpp v15, v24, v24 row_ror:8 row_mask:0xf bank_mask:0xf bound_ctrl:1
	ds_read_b128 v[92:95], v48 offset:1024
	s_nop 0
	v_add_f32_dpp v15, v15, v15 row_ror:4 row_mask:0xf bank_mask:0xf bound_ctrl:1
	ds_read_b128 v[96:99], v48 offset:1280
	ds_read_b128 v[100:103], v48 offset:1536
	v_add_f32_dpp v15, v15, v15 row_ror:2 row_mask:0xf bank_mask:0xf bound_ctrl:1
	ds_read_b128 v[104:107], v48 offset:1792
	s_nop 0
	v_add_f32_dpp v30, v15, v15 row_ror:1 row_mask:0xf bank_mask:0xf bound_ctrl:1
	v_pk_fma_f32 v[10:11], v[128:129], v[30:31], v[16:17] op_sel_hi:[1,0,1] neg_lo:[0,1,0] neg_hi:[0,1,0]
	v_pk_fma_f32 v[8:9], v[130:131], v[30:31], v[18:19] op_sel_hi:[1,0,1] neg_lo:[0,1,0] neg_hi:[0,1,0]
	v_pk_mul_f32 v[26:27], v[10:11], v[132:133] op_sel:[0,0] op_sel_hi:[0,1]
	v_pk_fma_f32 v[26:27], v[10:11], v[134:135], v[26:27] op_sel:[1,0,0] op_sel_hi:[1,1,1]
	v_pk_fma_f32 v[26:27], v[8:9], v[136:137], v[26:27] op_sel:[0,0,0] op_sel_hi:[0,1,1]
	v_pk_fma_f32 v[26:27], v[8:9], v[138:139], v[26:27] op_sel:[1,0,0] op_sel_hi:[1,1,1]
	ds_write2st64_b32 v37, v25, v27 offset0:120 offset1:124
	v_pk_mul_f32 v[10:11], v[10:11], v[140:141]
	v_pk_mul_f32 v[8:9], v[8:9], v[142:143]
	s_waitcnt lgkmcnt(7)
	v_pk_mul_f32 v[24:25], v[10:11], v[144:145]
	v_pk_fma_f32 v[24:25], v[8:9], v[146:147], v[24:25]
	v_add_f32_e32 v24, v24, v25
	s_waitcnt lgkmcnt(5)
	v_pk_fma_f32 v[16:17], v[76:77], v[156:157], v[10:11] op_sel_hi:[1,0,1]
	v_pk_fma_f32 v[18:19], v[78:79], v[156:157], v[8:9] op_sel_hi:[1,0,1]
	v_add_f32_dpp v15, v24, v24 row_ror:8 row_mask:0xf bank_mask:0xf bound_ctrl:1
	v_add_u32_e32 v51, 1, v51
	s_add_u32 s6, s6, 1
	v_add_f32_dpp v15, v15, v15 row_ror:4 row_mask:0xf bank_mask:0xf bound_ctrl:1
	ds_write_b32 v53, v51
	ds_read_b128 v[108:111], v48 offset:2048
	v_add_f32_dpp v15, v15, v15 row_ror:2 row_mask:0xf bank_mask:0xf bound_ctrl:1
	ds_read_b128 v[112:115], v48 offset:2304
	ds_read_b128 v[116:119], v48 offset:2560
	v_add_f32_dpp v30, v15, v15 row_ror:1 row_mask:0xf bank_mask:0xf bound_ctrl:1
	ds_read_b128 v[120:123], v48 offset:2816
	s_waitcnt lgkmcnt(3)
	v_pk_fma_f32 v[10:11], v[80:81], v[30:31], v[16:17] op_sel_hi:[1,0,1] neg_lo:[0,1,0] neg_hi:[0,1,0]
	v_pk_fma_f32 v[8:9], v[82:83], v[30:31], v[18:19] op_sel_hi:[1,0,1] neg_lo:[0,1,0] neg_hi:[0,1,0]
	v_pk_mul_f32 v[24:25], v[10:11], v[84:85] op_sel:[0,0] op_sel_hi:[0,1]
	v_pk_fma_f32 v[24:25], v[10:11], v[86:87], v[24:25] op_sel:[1,0,0] op_sel_hi:[1,1,1]
	v_pk_fma_f32 v[24:25], v[8:9], v[88:89], v[24:25] op_sel:[0,0,0] op_sel_hi:[0,1,1]
	v_pk_fma_f32 v[24:25], v[8:9], v[90:91], v[24:25] op_sel:[1,0,0] op_sel_hi:[1,1,1]
	v_pk_fma_f32 v[16:17], v[92:93], v[156:157], v[10:11] op_sel:[0,1,0] op_sel_hi:[1,1,1]
	v_pk_fma_f32 v[18:19], v[94:95], v[156:157], v[8:9] op_sel:[0,1,0] op_sel_hi:[1,1,1]
	v_add_f32_dpp v15, v24, v24 row_ror:8 row_mask:0xf bank_mask:0xf bound_ctrl:1
	ds_read_b128 v[124:127], v48 offset:3072
	s_nop 0
	v_add_f32_dpp v15, v15, v15 row_ror:4 row_mask:0xf bank_mask:0xf bound_ctrl:1
	ds_read_b128 v[128:131], v48 offset:3328
	ds_read_b128 v[132:135], v48 offset:3584
	v_add_f32_dpp v15, v15, v15 row_ror:2 row_mask:0xf bank_mask:0xf bound_ctrl:1
	ds_read_b128 v[136:139], v48 offset:3840
	ds_read_b128 v[160:163], v49 offset:16
	v_add_f32_dpp v30, v15, v15 row_ror:1 row_mask:0xf bank_mask:0xf bound_ctrl:1
	v_pk_fma_f32 v[10:11], v[96:97], v[30:31], v[16:17] op_sel_hi:[1,0,1] neg_lo:[0,1,0] neg_hi:[0,1,0]
	v_pk_fma_f32 v[8:9], v[98:99], v[30:31], v[18:19] op_sel_hi:[1,0,1] neg_lo:[0,1,0] neg_hi:[0,1,0]
	v_pk_mul_f32 v[26:27], v[10:11], v[100:101] op_sel:[0,0] op_sel_hi:[0,1]
	v_pk_fma_f32 v[26:27], v[10:11], v[102:103], v[26:27] op_sel:[1,0,0] op_sel_hi:[1,1,1]
	v_pk_fma_f32 v[26:27], v[8:9], v[104:105], v[26:27] op_sel:[0,0,0] op_sel_hi:[0,1,1]
	v_pk_fma_f32 v[26:27], v[8:9], v[106:107], v[26:27] op_sel:[1,0,0] op_sel_hi:[1,1,1]
	v_pk_fma_f32 v[16:17], v[108:109], v[158:159], v[10:11] op_sel_hi:[1,0,1]
	v_pk_fma_f32 v[18:19], v[110:111], v[158:159], v[8:9] op_sel_hi:[1,0,1]
	v_add_f32_dpp v15, v26, v26 row_ror:8 row_mask:0xf bank_mask:0xf bound_ctrl:1
	ds_read_b128 v[76:79], v48 offset:4096
	s_nop 0
	v_add_f32_dpp v15, v15, v15 row_ror:4 row_mask:0xf bank_mask:0xf bound_ctrl:1
	ds_read_b128 v[80:83], v48 offset:4352
	ds_read_b128 v[84:87], v48 offset:4608
	v_add_f32_dpp v15, v15, v15 row_ror:2 row_mask:0xf bank_mask:0xf bound_ctrl:1
	ds_read_b128 v[88:91], v48 offset:4864
	ds_write2st64_b32 v50, v25, v27 offset0:0 offset1:4
	v_add_f32_dpp v30, v15, v15 row_ror:1 row_mask:0xf bank_mask:0xf bound_ctrl:1
	s_waitcnt lgkmcnt(4)
	v_pk_fma_f32 v[10:11], v[112:113], v[30:31], v[16:17] op_sel_hi:[1,0,1] neg_lo:[0,1,0] neg_hi:[0,1,0]
	v_pk_fma_f32 v[8:9], v[114:115], v[30:31], v[18:19] op_sel_hi:[1,0,1] neg_lo:[0,1,0] neg_hi:[0,1,0]
	v_pk_mul_f32 v[24:25], v[10:11], v[116:117] op_sel:[0,0] op_sel_hi:[0,1]
	v_pk_fma_f32 v[24:25], v[10:11], v[118:119], v[24:25] op_sel:[1,0,0] op_sel_hi:[1,1,1]
	v_pk_fma_f32 v[24:25], v[8:9], v[120:121], v[24:25] op_sel:[0,0,0] op_sel_hi:[0,1,1]
	v_pk_fma_f32 v[24:25], v[8:9], v[122:123], v[24:25] op_sel:[1,0,0] op_sel_hi:[1,1,1]
	v_pk_fma_f32 v[16:17], v[124:125], v[158:159], v[10:11] op_sel:[0,1,0] op_sel_hi:[1,1,1]
	v_pk_fma_f32 v[18:19], v[126:127], v[158:159], v[8:9] op_sel:[0,1,0] op_sel_hi:[1,1,1]
	v_add_f32_dpp v15, v24, v24 row_ror:8 row_mask:0xf bank_mask:0xf bound_ctrl:1
	ds_read_b128 v[92:95], v48 offset:5120
	s_nop 0
	v_add_f32_dpp v15, v15, v15 row_ror:4 row_mask:0xf bank_mask:0xf bound_ctrl:1
	ds_read_b128 v[96:99], v48 offset:5376
	ds_read_b128 v[100:103], v48 offset:5632
	v_add_f32_dpp v15, v15, v15 row_ror:2 row_mask:0xf bank_mask:0xf bound_ctrl:1
	ds_read_b128 v[104:107], v48 offset:5888
	s_nop 0
	v_add_f32_dpp v30, v15, v15 row_ror:1 row_mask:0xf bank_mask:0xf bound_ctrl:1
	v_pk_fma_f32 v[10:11], v[128:129], v[30:31], v[16:17] op_sel_hi:[1,0,1] neg_lo:[0,1,0] neg_hi:[0,1,0]
	v_pk_fma_f32 v[8:9], v[130:131], v[30:31], v[18:19] op_sel_hi:[1,0,1] neg_lo:[0,1,0] neg_hi:[0,1,0]
	v_pk_mul_f32 v[26:27], v[10:11], v[132:133] op_sel:[0,0] op_sel_hi:[0,1]
	v_pk_fma_f32 v[26:27], v[10:11], v[134:135], v[26:27] op_sel:[1,0,0] op_sel_hi:[1,1,1]
	v_pk_fma_f32 v[26:27], v[8:9], v[136:137], v[26:27] op_sel:[0,0,0] op_sel_hi:[0,1,1]
	v_pk_fma_f32 v[26:27], v[8:9], v[138:139], v[26:27] op_sel:[1,0,0] op_sel_hi:[1,1,1]
	v_pk_fma_f32 v[16:17], v[76:77], v[160:161], v[10:11] op_sel_hi:[1,0,1]
	v_pk_fma_f32 v[18:19], v[78:79], v[160:161], v[8:9] op_sel_hi:[1,0,1]
	v_add_f32_dpp v15, v26, v26 row_ror:8 row_mask:0xf bank_mask:0xf bound_ctrl:1
	ds_read_b128 v[108:111], v48 offset:6144
	s_nop 0
	v_add_f32_dpp v15, v15, v15 row_ror:4 row_mask:0xf bank_mask:0xf bound_ctrl:1
	ds_read_b128 v[112:115], v48 offset:6400
	ds_read_b128 v[116:119], v48 offset:6656
	v_add_f32_dpp v15, v15, v15 row_ror:2 row_mask:0xf bank_mask:0xf bound_ctrl:1
	ds_read_b128 v[120:123], v48 offset:6912
	ds_write2st64_b32 v50, v25, v27 offset0:8 offset1:12
	v_add_f32_dpp v30, v15, v15 row_ror:1 row_mask:0xf bank_mask:0xf bound_ctrl:1
	s_waitcnt lgkmcnt(4)
	v_pk_fma_f32 v[10:11], v[80:81], v[30:31], v[16:17] op_sel_hi:[1,0,1] neg_lo:[0,1,0] neg_hi:[0,1,0]
	v_pk_fma_f32 v[8:9], v[82:83], v[30:31], v[18:19] op_sel_hi:[1,0,1] neg_lo:[0,1,0] neg_hi:[0,1,0]
	v_pk_mul_f32 v[24:25], v[10:11], v[84:85] op_sel:[0,0] op_sel_hi:[0,1]
	v_pk_fma_f32 v[24:25], v[10:11], v[86:87], v[24:25] op_sel:[1,0,0] op_sel_hi:[1,1,1]
	v_pk_fma_f32 v[24:25], v[8:9], v[88:89], v[24:25] op_sel:[0,0,0] op_sel_hi:[0,1,1]
	v_pk_fma_f32 v[24:25], v[8:9], v[90:91], v[24:25] op_sel:[1,0,0] op_sel_hi:[1,1,1]
	v_pk_fma_f32 v[16:17], v[92:93], v[160:161], v[10:11] op_sel:[0,1,0] op_sel_hi:[1,1,1]
	v_pk_fma_f32 v[18:19], v[94:95], v[160:161], v[8:9] op_sel:[0,1,0] op_sel_hi:[1,1,1]
	v_add_f32_dpp v15, v24, v24 row_ror:8 row_mask:0xf bank_mask:0xf bound_ctrl:1
	ds_read_b128 v[124:127], v48 offset:7168
	s_nop 0
	v_add_f32_dpp v15, v15, v15 row_ror:4 row_mask:0xf bank_mask:0xf bound_ctrl:1
	ds_read_b128 v[128:131], v48 offset:7424
	ds_read_b128 v[132:135], v48 offset:7680
	v_add_f32_dpp v15, v15, v15 row_ror:2 row_mask:0xf bank_mask:0xf bound_ctrl:1
	ds_read_b128 v[136:139], v48 offset:7936
	ds_read_b128 v[156:159], v49 offset:32
	v_add_f32_dpp v30, v15, v15 row_ror:1 row_mask:0xf bank_mask:0xf bound_ctrl:1
	v_pk_fma_f32 v[10:11], v[96:97], v[30:31], v[16:17] op_sel_hi:[1,0,1] neg_lo:[0,1,0] neg_hi:[0,1,0]
	v_pk_fma_f32 v[8:9], v[98:99], v[30:31], v[18:19] op_sel_hi:[1,0,1] neg_lo:[0,1,0] neg_hi:[0,1,0]
	v_pk_mul_f32 v[26:27], v[10:11], v[100:101] op_sel:[0,0] op_sel_hi:[0,1]
	v_pk_fma_f32 v[26:27], v[10:11], v[102:103], v[26:27] op_sel:[1,0,0] op_sel_hi:[1,1,1]
	v_pk_fma_f32 v[26:27], v[8:9], v[104:105], v[26:27] op_sel:[0,0,0] op_sel_hi:[0,1,1]
	v_pk_fma_f32 v[26:27], v[8:9], v[106:107], v[26:27] op_sel:[1,0,0] op_sel_hi:[1,1,1]
	v_pk_fma_f32 v[16:17], v[108:109], v[162:163], v[10:11] op_sel_hi:[1,0,1]
	v_pk_fma_f32 v[18:19], v[110:111], v[162:163], v[8:9] op_sel_hi:[1,0,1]
	v_add_f32_dpp v15, v26, v26 row_ror:8 row_mask:0xf bank_mask:0xf bound_ctrl:1
	ds_read_b128 v[76:79], v48 offset:8192
	s_nop 0
	v_add_f32_dpp v15, v15, v15 row_ror:4 row_mask:0xf bank_mask:0xf bound_ctrl:1
	ds_read_b128 v[80:83], v48 offset:8448
	ds_read_b128 v[84:87], v48 offset:8704
	v_add_f32_dpp v15, v15, v15 row_ror:2 row_mask:0xf bank_mask:0xf bound_ctrl:1
	ds_read_b128 v[88:91], v48 offset:8960
	ds_write2st64_b32 v50, v25, v27 offset0:16 offset1:20
	v_add_f32_dpp v30, v15, v15 row_ror:1 row_mask:0xf bank_mask:0xf bound_ctrl:1
	s_waitcnt lgkmcnt(4)
	v_pk_fma_f32 v[10:11], v[112:113], v[30:31], v[16:17] op_sel_hi:[1,0,1] neg_lo:[0,1,0] neg_hi:[0,1,0]
	v_pk_fma_f32 v[8:9], v[114:115], v[30:31], v[18:19] op_sel_hi:[1,0,1] neg_lo:[0,1,0] neg_hi:[0,1,0]
	v_pk_mul_f32 v[24:25], v[10:11], v[116:117] op_sel:[0,0] op_sel_hi:[0,1]
	v_pk_fma_f32 v[24:25], v[10:11], v[118:119], v[24:25] op_sel:[1,0,0] op_sel_hi:[1,1,1]
	v_pk_fma_f32 v[24:25], v[8:9], v[120:121], v[24:25] op_sel:[0,0,0] op_sel_hi:[0,1,1]
	v_pk_fma_f32 v[24:25], v[8:9], v[122:123], v[24:25] op_sel:[1,0,0] op_sel_hi:[1,1,1]
	v_pk_fma_f32 v[16:17], v[124:125], v[162:163], v[10:11] op_sel:[0,1,0] op_sel_hi:[1,1,1]
	v_pk_fma_f32 v[18:19], v[126:127], v[162:163], v[8:9] op_sel:[0,1,0] op_sel_hi:[1,1,1]
	v_add_f32_dpp v15, v24, v24 row_ror:8 row_mask:0xf bank_mask:0xf bound_ctrl:1
	ds_read_b128 v[92:95], v48 offset:9216
	s_nop 0
	v_add_f32_dpp v15, v15, v15 row_ror:4 row_mask:0xf bank_mask:0xf bound_ctrl:1
	ds_read_b128 v[96:99], v48 offset:9472
	ds_read_b128 v[100:103], v48 offset:9728
	v_add_f32_dpp v15, v15, v15 row_ror:2 row_mask:0xf bank_mask:0xf bound_ctrl:1
	ds_read_b128 v[104:107], v48 offset:9984
	s_nop 0
	v_add_f32_dpp v30, v15, v15 row_ror:1 row_mask:0xf bank_mask:0xf bound_ctrl:1
	v_pk_fma_f32 v[10:11], v[128:129], v[30:31], v[16:17] op_sel_hi:[1,0,1] neg_lo:[0,1,0] neg_hi:[0,1,0]
	v_pk_fma_f32 v[8:9], v[130:131], v[30:31], v[18:19] op_sel_hi:[1,0,1] neg_lo:[0,1,0] neg_hi:[0,1,0]
	v_pk_mul_f32 v[26:27], v[10:11], v[132:133] op_sel:[0,0] op_sel_hi:[0,1]
	v_pk_fma_f32 v[26:27], v[10:11], v[134:135], v[26:27] op_sel:[1,0,0] op_sel_hi:[1,1,1]
	v_pk_fma_f32 v[26:27], v[8:9], v[136:137], v[26:27] op_sel:[0,0,0] op_sel_hi:[0,1,1]
	v_pk_fma_f32 v[26:27], v[8:9], v[138:139], v[26:27] op_sel:[1,0,0] op_sel_hi:[1,1,1]
	v_pk_fma_f32 v[16:17], v[76:77], v[156:157], v[10:11] op_sel_hi:[1,0,1]
	v_pk_fma_f32 v[18:19], v[78:79], v[156:157], v[8:9] op_sel_hi:[1,0,1]
	v_add_f32_dpp v15, v26, v26 row_ror:8 row_mask:0xf bank_mask:0xf bound_ctrl:1
	ds_read_b128 v[108:111], v48 offset:10240
	s_nop 0
	v_add_f32_dpp v15, v15, v15 row_ror:4 row_mask:0xf bank_mask:0xf bound_ctrl:1
	ds_read_b128 v[112:115], v48 offset:10496
	ds_read_b128 v[116:119], v48 offset:10752
	v_add_f32_dpp v15, v15, v15 row_ror:2 row_mask:0xf bank_mask:0xf bound_ctrl:1
	ds_read_b128 v[120:123], v48 offset:11008
	ds_write2st64_b32 v50, v25, v27 offset0:24 offset1:28
	v_add_f32_dpp v30, v15, v15 row_ror:1 row_mask:0xf bank_mask:0xf bound_ctrl:1
	s_waitcnt lgkmcnt(4)
	v_pk_fma_f32 v[10:11], v[80:81], v[30:31], v[16:17] op_sel_hi:[1,0,1] neg_lo:[0,1,0] neg_hi:[0,1,0]
	v_pk_fma_f32 v[8:9], v[82:83], v[30:31], v[18:19] op_sel_hi:[1,0,1] neg_lo:[0,1,0] neg_hi:[0,1,0]
	v_pk_mul_f32 v[24:25], v[10:11], v[84:85] op_sel:[0,0] op_sel_hi:[0,1]
	v_pk_fma_f32 v[24:25], v[10:11], v[86:87], v[24:25] op_sel:[1,0,0] op_sel_hi:[1,1,1]
	v_pk_fma_f32 v[24:25], v[8:9], v[88:89], v[24:25] op_sel:[0,0,0] op_sel_hi:[0,1,1]
	v_pk_fma_f32 v[24:25], v[8:9], v[90:91], v[24:25] op_sel:[1,0,0] op_sel_hi:[1,1,1]
	v_pk_fma_f32 v[16:17], v[92:93], v[156:157], v[10:11] op_sel:[0,1,0] op_sel_hi:[1,1,1]
	v_pk_fma_f32 v[18:19], v[94:95], v[156:157], v[8:9] op_sel:[0,1,0] op_sel_hi:[1,1,1]
	v_add_f32_dpp v15, v24, v24 row_ror:8 row_mask:0xf bank_mask:0xf bound_ctrl:1
	ds_read_b128 v[124:127], v48 offset:11264
	s_nop 0
	v_add_f32_dpp v15, v15, v15 row_ror:4 row_mask:0xf bank_mask:0xf bound_ctrl:1
	ds_read_b128 v[128:131], v48 offset:11520
	ds_read_b128 v[132:135], v48 offset:11776
	v_add_f32_dpp v15, v15, v15 row_ror:2 row_mask:0xf bank_mask:0xf bound_ctrl:1
	ds_read_b128 v[136:139], v48 offset:12032
	ds_read_b128 v[160:163], v49 offset:48
	v_add_f32_dpp v30, v15, v15 row_ror:1 row_mask:0xf bank_mask:0xf bound_ctrl:1
	v_pk_fma_f32 v[10:11], v[96:97], v[30:31], v[16:17] op_sel_hi:[1,0,1] neg_lo:[0,1,0] neg_hi:[0,1,0]
	v_pk_fma_f32 v[8:9], v[98:99], v[30:31], v[18:19] op_sel_hi:[1,0,1] neg_lo:[0,1,0] neg_hi:[0,1,0]
	v_pk_mul_f32 v[26:27], v[10:11], v[100:101] op_sel:[0,0] op_sel_hi:[0,1]
	v_pk_fma_f32 v[26:27], v[10:11], v[102:103], v[26:27] op_sel:[1,0,0] op_sel_hi:[1,1,1]
	v_pk_fma_f32 v[26:27], v[8:9], v[104:105], v[26:27] op_sel:[0,0,0] op_sel_hi:[0,1,1]
	v_pk_fma_f32 v[26:27], v[8:9], v[106:107], v[26:27] op_sel:[1,0,0] op_sel_hi:[1,1,1]
	v_pk_fma_f32 v[16:17], v[108:109], v[158:159], v[10:11] op_sel_hi:[1,0,1]
	v_pk_fma_f32 v[18:19], v[110:111], v[158:159], v[8:9] op_sel_hi:[1,0,1]
	v_add_f32_dpp v15, v26, v26 row_ror:8 row_mask:0xf bank_mask:0xf bound_ctrl:1
	ds_read_b128 v[76:79], v48 offset:12288
	s_nop 0
	v_add_f32_dpp v15, v15, v15 row_ror:4 row_mask:0xf bank_mask:0xf bound_ctrl:1
	ds_read_b128 v[80:83], v48 offset:12544
	ds_read_b128 v[84:87], v48 offset:12800
	v_add_f32_dpp v15, v15, v15 row_ror:2 row_mask:0xf bank_mask:0xf bound_ctrl:1
	ds_read_b128 v[88:91], v48 offset:13056
	ds_write2st64_b32 v50, v25, v27 offset0:32 offset1:36
	v_add_f32_dpp v30, v15, v15 row_ror:1 row_mask:0xf bank_mask:0xf bound_ctrl:1
	s_waitcnt lgkmcnt(4)
	v_pk_fma_f32 v[10:11], v[112:113], v[30:31], v[16:17] op_sel_hi:[1,0,1] neg_lo:[0,1,0] neg_hi:[0,1,0]
	v_pk_fma_f32 v[8:9], v[114:115], v[30:31], v[18:19] op_sel_hi:[1,0,1] neg_lo:[0,1,0] neg_hi:[0,1,0]
	v_pk_mul_f32 v[24:25], v[10:11], v[116:117] op_sel:[0,0] op_sel_hi:[0,1]
	v_pk_fma_f32 v[24:25], v[10:11], v[118:119], v[24:25] op_sel:[1,0,0] op_sel_hi:[1,1,1]
	v_pk_fma_f32 v[24:25], v[8:9], v[120:121], v[24:25] op_sel:[0,0,0] op_sel_hi:[0,1,1]
	v_pk_fma_f32 v[24:25], v[8:9], v[122:123], v[24:25] op_sel:[1,0,0] op_sel_hi:[1,1,1]
	v_pk_fma_f32 v[16:17], v[124:125], v[158:159], v[10:11] op_sel:[0,1,0] op_sel_hi:[1,1,1]
	v_pk_fma_f32 v[18:19], v[126:127], v[158:159], v[8:9] op_sel:[0,1,0] op_sel_hi:[1,1,1]
	v_add_f32_dpp v15, v24, v24 row_ror:8 row_mask:0xf bank_mask:0xf bound_ctrl:1
	ds_read_b128 v[92:95], v48 offset:13312
	s_nop 0
	v_add_f32_dpp v15, v15, v15 row_ror:4 row_mask:0xf bank_mask:0xf bound_ctrl:1
	ds_read_b128 v[96:99], v48 offset:13568
	ds_read_b128 v[100:103], v48 offset:13824
	v_add_f32_dpp v15, v15, v15 row_ror:2 row_mask:0xf bank_mask:0xf bound_ctrl:1
	ds_read_b128 v[104:107], v48 offset:14080
	s_nop 0
	v_add_f32_dpp v30, v15, v15 row_ror:1 row_mask:0xf bank_mask:0xf bound_ctrl:1
	v_pk_fma_f32 v[10:11], v[128:129], v[30:31], v[16:17] op_sel_hi:[1,0,1] neg_lo:[0,1,0] neg_hi:[0,1,0]
	v_pk_fma_f32 v[8:9], v[130:131], v[30:31], v[18:19] op_sel_hi:[1,0,1] neg_lo:[0,1,0] neg_hi:[0,1,0]
	v_pk_mul_f32 v[26:27], v[10:11], v[132:133] op_sel:[0,0] op_sel_hi:[0,1]
	v_pk_fma_f32 v[26:27], v[10:11], v[134:135], v[26:27] op_sel:[1,0,0] op_sel_hi:[1,1,1]
	v_pk_fma_f32 v[26:27], v[8:9], v[136:137], v[26:27] op_sel:[0,0,0] op_sel_hi:[0,1,1]
	v_pk_fma_f32 v[26:27], v[8:9], v[138:139], v[26:27] op_sel:[1,0,0] op_sel_hi:[1,1,1]
	v_pk_fma_f32 v[16:17], v[76:77], v[160:161], v[10:11] op_sel_hi:[1,0,1]
	v_pk_fma_f32 v[18:19], v[78:79], v[160:161], v[8:9] op_sel_hi:[1,0,1]
	v_add_f32_dpp v15, v26, v26 row_ror:8 row_mask:0xf bank_mask:0xf bound_ctrl:1
	ds_read_b128 v[108:111], v48 offset:14336
	s_nop 0
	v_add_f32_dpp v15, v15, v15 row_ror:4 row_mask:0xf bank_mask:0xf bound_ctrl:1
	ds_read_b128 v[112:115], v48 offset:14592
	ds_read_b128 v[116:119], v48 offset:14848
	v_add_f32_dpp v15, v15, v15 row_ror:2 row_mask:0xf bank_mask:0xf bound_ctrl:1
	ds_read_b128 v[120:123], v48 offset:15104
	ds_write2st64_b32 v50, v25, v27 offset0:40 offset1:44
	v_add_f32_dpp v30, v15, v15 row_ror:1 row_mask:0xf bank_mask:0xf bound_ctrl:1
	s_waitcnt lgkmcnt(4)
	v_pk_fma_f32 v[10:11], v[80:81], v[30:31], v[16:17] op_sel_hi:[1,0,1] neg_lo:[0,1,0] neg_hi:[0,1,0]
	v_pk_fma_f32 v[8:9], v[82:83], v[30:31], v[18:19] op_sel_hi:[1,0,1] neg_lo:[0,1,0] neg_hi:[0,1,0]
	v_pk_mul_f32 v[24:25], v[10:11], v[84:85] op_sel:[0,0] op_sel_hi:[0,1]
	v_pk_fma_f32 v[24:25], v[10:11], v[86:87], v[24:25] op_sel:[1,0,0] op_sel_hi:[1,1,1]
	v_pk_fma_f32 v[24:25], v[8:9], v[88:89], v[24:25] op_sel:[0,0,0] op_sel_hi:[0,1,1]
	v_pk_fma_f32 v[24:25], v[8:9], v[90:91], v[24:25] op_sel:[1,0,0] op_sel_hi:[1,1,1]
	v_pk_fma_f32 v[16:17], v[92:93], v[160:161], v[10:11] op_sel:[0,1,0] op_sel_hi:[1,1,1]
	v_pk_fma_f32 v[18:19], v[94:95], v[160:161], v[8:9] op_sel:[0,1,0] op_sel_hi:[1,1,1]
	v_add_f32_dpp v15, v24, v24 row_ror:8 row_mask:0xf bank_mask:0xf bound_ctrl:1
	ds_read_b128 v[124:127], v48 offset:15360
	s_nop 0
	v_add_f32_dpp v15, v15, v15 row_ror:4 row_mask:0xf bank_mask:0xf bound_ctrl:1
	ds_read_b128 v[128:131], v48 offset:15616
	ds_read_b128 v[132:135], v48 offset:15872
	v_add_f32_dpp v15, v15, v15 row_ror:2 row_mask:0xf bank_mask:0xf bound_ctrl:1
	ds_read_b128 v[136:139], v48 offset:16128
	ds_read_b128 v[156:159], v49 offset:64
	v_add_f32_dpp v30, v15, v15 row_ror:1 row_mask:0xf bank_mask:0xf bound_ctrl:1
	v_pk_fma_f32 v[10:11], v[96:97], v[30:31], v[16:17] op_sel_hi:[1,0,1] neg_lo:[0,1,0] neg_hi:[0,1,0]
	v_pk_fma_f32 v[8:9], v[98:99], v[30:31], v[18:19] op_sel_hi:[1,0,1] neg_lo:[0,1,0] neg_hi:[0,1,0]
	v_pk_mul_f32 v[26:27], v[10:11], v[100:101] op_sel:[0,0] op_sel_hi:[0,1]
	v_pk_fma_f32 v[26:27], v[10:11], v[102:103], v[26:27] op_sel:[1,0,0] op_sel_hi:[1,1,1]
	v_pk_fma_f32 v[26:27], v[8:9], v[104:105], v[26:27] op_sel:[0,0,0] op_sel_hi:[0,1,1]
	v_pk_fma_f32 v[26:27], v[8:9], v[106:107], v[26:27] op_sel:[1,0,0] op_sel_hi:[1,1,1]
	v_pk_fma_f32 v[16:17], v[108:109], v[162:163], v[10:11] op_sel_hi:[1,0,1]
	v_pk_fma_f32 v[18:19], v[110:111], v[162:163], v[8:9] op_sel_hi:[1,0,1]
	v_add_f32_dpp v15, v26, v26 row_ror:8 row_mask:0xf bank_mask:0xf bound_ctrl:1
	ds_read_b128 v[76:79], v48 offset:16384
	s_nop 0
	v_add_f32_dpp v15, v15, v15 row_ror:4 row_mask:0xf bank_mask:0xf bound_ctrl:1
	ds_read_b128 v[80:83], v48 offset:16640
	ds_read_b128 v[84:87], v48 offset:16896
	v_add_f32_dpp v15, v15, v15 row_ror:2 row_mask:0xf bank_mask:0xf bound_ctrl:1
	ds_read_b128 v[88:91], v48 offset:17152
	ds_write2st64_b32 v50, v25, v27 offset0:48 offset1:52
	v_add_f32_dpp v30, v15, v15 row_ror:1 row_mask:0xf bank_mask:0xf bound_ctrl:1
	s_waitcnt lgkmcnt(4)
	v_pk_fma_f32 v[10:11], v[112:113], v[30:31], v[16:17] op_sel_hi:[1,0,1] neg_lo:[0,1,0] neg_hi:[0,1,0]
	v_pk_fma_f32 v[8:9], v[114:115], v[30:31], v[18:19] op_sel_hi:[1,0,1] neg_lo:[0,1,0] neg_hi:[0,1,0]
	v_pk_mul_f32 v[24:25], v[10:11], v[116:117] op_sel:[0,0] op_sel_hi:[0,1]
	v_pk_fma_f32 v[24:25], v[10:11], v[118:119], v[24:25] op_sel:[1,0,0] op_sel_hi:[1,1,1]
	v_pk_fma_f32 v[24:25], v[8:9], v[120:121], v[24:25] op_sel:[0,0,0] op_sel_hi:[0,1,1]
	v_pk_fma_f32 v[24:25], v[8:9], v[122:123], v[24:25] op_sel:[1,0,0] op_sel_hi:[1,1,1]
	v_pk_fma_f32 v[16:17], v[124:125], v[162:163], v[10:11] op_sel:[0,1,0] op_sel_hi:[1,1,1]
	v_pk_fma_f32 v[18:19], v[126:127], v[162:163], v[8:9] op_sel:[0,1,0] op_sel_hi:[1,1,1]
	v_add_f32_dpp v15, v24, v24 row_ror:8 row_mask:0xf bank_mask:0xf bound_ctrl:1
	ds_read_b128 v[92:95], v48 offset:17408
	s_nop 0
	v_add_f32_dpp v15, v15, v15 row_ror:4 row_mask:0xf bank_mask:0xf bound_ctrl:1
	ds_read_b128 v[96:99], v48 offset:17664
	ds_read_b128 v[100:103], v48 offset:17920
	v_add_f32_dpp v15, v15, v15 row_ror:2 row_mask:0xf bank_mask:0xf bound_ctrl:1
	ds_read_b128 v[104:107], v48 offset:18176
	s_nop 0
	v_add_f32_dpp v30, v15, v15 row_ror:1 row_mask:0xf bank_mask:0xf bound_ctrl:1
	v_pk_fma_f32 v[10:11], v[128:129], v[30:31], v[16:17] op_sel_hi:[1,0,1] neg_lo:[0,1,0] neg_hi:[0,1,0]
	v_pk_fma_f32 v[8:9], v[130:131], v[30:31], v[18:19] op_sel_hi:[1,0,1] neg_lo:[0,1,0] neg_hi:[0,1,0]
	v_pk_mul_f32 v[26:27], v[10:11], v[132:133] op_sel:[0,0] op_sel_hi:[0,1]
	v_pk_fma_f32 v[26:27], v[10:11], v[134:135], v[26:27] op_sel:[1,0,0] op_sel_hi:[1,1,1]
	v_pk_fma_f32 v[26:27], v[8:9], v[136:137], v[26:27] op_sel:[0,0,0] op_sel_hi:[0,1,1]
	v_pk_fma_f32 v[26:27], v[8:9], v[138:139], v[26:27] op_sel:[1,0,0] op_sel_hi:[1,1,1]
	v_pk_fma_f32 v[16:17], v[76:77], v[156:157], v[10:11] op_sel_hi:[1,0,1]
	v_pk_fma_f32 v[18:19], v[78:79], v[156:157], v[8:9] op_sel_hi:[1,0,1]
	v_add_f32_dpp v15, v26, v26 row_ror:8 row_mask:0xf bank_mask:0xf bound_ctrl:1
	ds_read_b128 v[108:111], v48 offset:18432
	s_nop 0
	v_add_f32_dpp v15, v15, v15 row_ror:4 row_mask:0xf bank_mask:0xf bound_ctrl:1
	ds_read_b128 v[112:115], v48 offset:18688
	ds_read_b128 v[116:119], v48 offset:18944
	v_add_f32_dpp v15, v15, v15 row_ror:2 row_mask:0xf bank_mask:0xf bound_ctrl:1
	ds_read_b128 v[120:123], v48 offset:19200
	ds_write2st64_b32 v50, v25, v27 offset0:56 offset1:60
	v_add_f32_dpp v30, v15, v15 row_ror:1 row_mask:0xf bank_mask:0xf bound_ctrl:1
	s_waitcnt lgkmcnt(4)
	v_pk_fma_f32 v[10:11], v[80:81], v[30:31], v[16:17] op_sel_hi:[1,0,1] neg_lo:[0,1,0] neg_hi:[0,1,0]
	v_pk_fma_f32 v[8:9], v[82:83], v[30:31], v[18:19] op_sel_hi:[1,0,1] neg_lo:[0,1,0] neg_hi:[0,1,0]
	v_pk_mul_f32 v[24:25], v[10:11], v[84:85] op_sel:[0,0] op_sel_hi:[0,1]
	v_pk_fma_f32 v[24:25], v[10:11], v[86:87], v[24:25] op_sel:[1,0,0] op_sel_hi:[1,1,1]
	v_pk_fma_f32 v[24:25], v[8:9], v[88:89], v[24:25] op_sel:[0,0,0] op_sel_hi:[0,1,1]
	v_pk_fma_f32 v[24:25], v[8:9], v[90:91], v[24:25] op_sel:[1,0,0] op_sel_hi:[1,1,1]
	v_pk_fma_f32 v[16:17], v[92:93], v[156:157], v[10:11] op_sel:[0,1,0] op_sel_hi:[1,1,1]
	v_pk_fma_f32 v[18:19], v[94:95], v[156:157], v[8:9] op_sel:[0,1,0] op_sel_hi:[1,1,1]
	v_add_f32_dpp v15, v24, v24 row_ror:8 row_mask:0xf bank_mask:0xf bound_ctrl:1
	ds_read_b128 v[124:127], v48 offset:19456
	s_nop 0
	v_add_f32_dpp v15, v15, v15 row_ror:4 row_mask:0xf bank_mask:0xf bound_ctrl:1
	ds_read_b128 v[128:131], v48 offset:19712
	ds_read_b128 v[132:135], v48 offset:19968
	v_add_f32_dpp v15, v15, v15 row_ror:2 row_mask:0xf bank_mask:0xf bound_ctrl:1
	ds_read_b128 v[136:139], v48 offset:20224
	ds_read_b128 v[160:163], v49 offset:80
	v_add_f32_dpp v30, v15, v15 row_ror:1 row_mask:0xf bank_mask:0xf bound_ctrl:1
	v_pk_fma_f32 v[10:11], v[96:97], v[30:31], v[16:17] op_sel_hi:[1,0,1] neg_lo:[0,1,0] neg_hi:[0,1,0]
	v_pk_fma_f32 v[8:9], v[98:99], v[30:31], v[18:19] op_sel_hi:[1,0,1] neg_lo:[0,1,0] neg_hi:[0,1,0]
	v_pk_mul_f32 v[26:27], v[10:11], v[100:101] op_sel:[0,0] op_sel_hi:[0,1]
	v_pk_fma_f32 v[26:27], v[10:11], v[102:103], v[26:27] op_sel:[1,0,0] op_sel_hi:[1,1,1]
	v_pk_fma_f32 v[26:27], v[8:9], v[104:105], v[26:27] op_sel:[0,0,0] op_sel_hi:[0,1,1]
	v_pk_fma_f32 v[26:27], v[8:9], v[106:107], v[26:27] op_sel:[1,0,0] op_sel_hi:[1,1,1]
	v_pk_fma_f32 v[16:17], v[108:109], v[158:159], v[10:11] op_sel_hi:[1,0,1]
	v_pk_fma_f32 v[18:19], v[110:111], v[158:159], v[8:9] op_sel_hi:[1,0,1]
	v_add_f32_dpp v15, v26, v26 row_ror:8 row_mask:0xf bank_mask:0xf bound_ctrl:1
	ds_read_b128 v[76:79], v48 offset:20480
	s_nop 0
	v_add_f32_dpp v15, v15, v15 row_ror:4 row_mask:0xf bank_mask:0xf bound_ctrl:1
	ds_read_b128 v[80:83], v48 offset:20736
	ds_read_b128 v[84:87], v48 offset:20992
	v_add_f32_dpp v15, v15, v15 row_ror:2 row_mask:0xf bank_mask:0xf bound_ctrl:1
	ds_read_b128 v[88:91], v48 offset:21248
	ds_write2st64_b32 v50, v25, v27 offset0:64 offset1:68
	v_add_f32_dpp v30, v15, v15 row_ror:1 row_mask:0xf bank_mask:0xf bound_ctrl:1
	s_waitcnt lgkmcnt(4)
	v_pk_fma_f32 v[10:11], v[112:113], v[30:31], v[16:17] op_sel_hi:[1,0,1] neg_lo:[0,1,0] neg_hi:[0,1,0]
	v_pk_fma_f32 v[8:9], v[114:115], v[30:31], v[18:19] op_sel_hi:[1,0,1] neg_lo:[0,1,0] neg_hi:[0,1,0]
	v_pk_mul_f32 v[24:25], v[10:11], v[116:117] op_sel:[0,0] op_sel_hi:[0,1]
	v_pk_fma_f32 v[24:25], v[10:11], v[118:119], v[24:25] op_sel:[1,0,0] op_sel_hi:[1,1,1]
	v_pk_fma_f32 v[24:25], v[8:9], v[120:121], v[24:25] op_sel:[0,0,0] op_sel_hi:[0,1,1]
	v_pk_fma_f32 v[24:25], v[8:9], v[122:123], v[24:25] op_sel:[1,0,0] op_sel_hi:[1,1,1]
	v_pk_fma_f32 v[16:17], v[124:125], v[158:159], v[10:11] op_sel:[0,1,0] op_sel_hi:[1,1,1]
	v_pk_fma_f32 v[18:19], v[126:127], v[158:159], v[8:9] op_sel:[0,1,0] op_sel_hi:[1,1,1]
	v_add_f32_dpp v15, v24, v24 row_ror:8 row_mask:0xf bank_mask:0xf bound_ctrl:1
	ds_read_b128 v[92:95], v48 offset:21504
	s_nop 0
	v_add_f32_dpp v15, v15, v15 row_ror:4 row_mask:0xf bank_mask:0xf bound_ctrl:1
	ds_read_b128 v[96:99], v48 offset:21760
	ds_read_b128 v[100:103], v48 offset:22016
	v_add_f32_dpp v15, v15, v15 row_ror:2 row_mask:0xf bank_mask:0xf bound_ctrl:1
	ds_read_b128 v[104:107], v48 offset:22272
	s_nop 0
	v_add_f32_dpp v30, v15, v15 row_ror:1 row_mask:0xf bank_mask:0xf bound_ctrl:1
	v_pk_fma_f32 v[10:11], v[128:129], v[30:31], v[16:17] op_sel_hi:[1,0,1] neg_lo:[0,1,0] neg_hi:[0,1,0]
	v_pk_fma_f32 v[8:9], v[130:131], v[30:31], v[18:19] op_sel_hi:[1,0,1] neg_lo:[0,1,0] neg_hi:[0,1,0]
	v_pk_mul_f32 v[26:27], v[10:11], v[132:133] op_sel:[0,0] op_sel_hi:[0,1]
	v_pk_fma_f32 v[26:27], v[10:11], v[134:135], v[26:27] op_sel:[1,0,0] op_sel_hi:[1,1,1]
	v_pk_fma_f32 v[26:27], v[8:9], v[136:137], v[26:27] op_sel:[0,0,0] op_sel_hi:[0,1,1]
	v_pk_fma_f32 v[26:27], v[8:9], v[138:139], v[26:27] op_sel:[1,0,0] op_sel_hi:[1,1,1]
	v_pk_fma_f32 v[16:17], v[76:77], v[160:161], v[10:11] op_sel_hi:[1,0,1]
	v_pk_fma_f32 v[18:19], v[78:79], v[160:161], v[8:9] op_sel_hi:[1,0,1]
	v_add_f32_dpp v15, v26, v26 row_ror:8 row_mask:0xf bank_mask:0xf bound_ctrl:1
	ds_read_b128 v[108:111], v48 offset:22528
	s_nop 0
	v_add_f32_dpp v15, v15, v15 row_ror:4 row_mask:0xf bank_mask:0xf bound_ctrl:1
	ds_read_b128 v[112:115], v48 offset:22784
	ds_read_b128 v[116:119], v48 offset:23040
	v_add_f32_dpp v15, v15, v15 row_ror:2 row_mask:0xf bank_mask:0xf bound_ctrl:1
	ds_read_b128 v[120:123], v48 offset:23296
	ds_write2st64_b32 v50, v25, v27 offset0:72 offset1:76
	v_add_f32_dpp v30, v15, v15 row_ror:1 row_mask:0xf bank_mask:0xf bound_ctrl:1
	s_waitcnt lgkmcnt(4)
	v_pk_fma_f32 v[10:11], v[80:81], v[30:31], v[16:17] op_sel_hi:[1,0,1] neg_lo:[0,1,0] neg_hi:[0,1,0]
	v_pk_fma_f32 v[8:9], v[82:83], v[30:31], v[18:19] op_sel_hi:[1,0,1] neg_lo:[0,1,0] neg_hi:[0,1,0]
	v_pk_mul_f32 v[24:25], v[10:11], v[84:85] op_sel:[0,0] op_sel_hi:[0,1]
	v_pk_fma_f32 v[24:25], v[10:11], v[86:87], v[24:25] op_sel:[1,0,0] op_sel_hi:[1,1,1]
	v_pk_fma_f32 v[24:25], v[8:9], v[88:89], v[24:25] op_sel:[0,0,0] op_sel_hi:[0,1,1]
	v_pk_fma_f32 v[24:25], v[8:9], v[90:91], v[24:25] op_sel:[1,0,0] op_sel_hi:[1,1,1]
	v_pk_fma_f32 v[16:17], v[92:93], v[160:161], v[10:11] op_sel:[0,1,0] op_sel_hi:[1,1,1]
	v_pk_fma_f32 v[18:19], v[94:95], v[160:161], v[8:9] op_sel:[0,1,0] op_sel_hi:[1,1,1]
	v_add_f32_dpp v15, v24, v24 row_ror:8 row_mask:0xf bank_mask:0xf bound_ctrl:1
	ds_read_b128 v[124:127], v48 offset:23552
	s_nop 0
	v_add_f32_dpp v15, v15, v15 row_ror:4 row_mask:0xf bank_mask:0xf bound_ctrl:1
	ds_read_b128 v[128:131], v48 offset:23808
	ds_read_b128 v[132:135], v48 offset:24064
	v_add_f32_dpp v15, v15, v15 row_ror:2 row_mask:0xf bank_mask:0xf bound_ctrl:1
	ds_read_b128 v[136:139], v48 offset:24320
	ds_read_b128 v[156:159], v49 offset:96
	v_add_f32_dpp v30, v15, v15 row_ror:1 row_mask:0xf bank_mask:0xf bound_ctrl:1
	v_pk_fma_f32 v[10:11], v[96:97], v[30:31], v[16:17] op_sel_hi:[1,0,1] neg_lo:[0,1,0] neg_hi:[0,1,0]
	v_pk_fma_f32 v[8:9], v[98:99], v[30:31], v[18:19] op_sel_hi:[1,0,1] neg_lo:[0,1,0] neg_hi:[0,1,0]
	v_pk_mul_f32 v[26:27], v[10:11], v[100:101] op_sel:[0,0] op_sel_hi:[0,1]
	v_pk_fma_f32 v[26:27], v[10:11], v[102:103], v[26:27] op_sel:[1,0,0] op_sel_hi:[1,1,1]
	v_pk_fma_f32 v[26:27], v[8:9], v[104:105], v[26:27] op_sel:[0,0,0] op_sel_hi:[0,1,1]
	v_pk_fma_f32 v[26:27], v[8:9], v[106:107], v[26:27] op_sel:[1,0,0] op_sel_hi:[1,1,1]
	v_pk_fma_f32 v[16:17], v[108:109], v[162:163], v[10:11] op_sel_hi:[1,0,1]
	v_pk_fma_f32 v[18:19], v[110:111], v[162:163], v[8:9] op_sel_hi:[1,0,1]
	v_add_f32_dpp v15, v26, v26 row_ror:8 row_mask:0xf bank_mask:0xf bound_ctrl:1
	ds_read_b128 v[76:79], v48 offset:24576
	s_nop 0
	v_add_f32_dpp v15, v15, v15 row_ror:4 row_mask:0xf bank_mask:0xf bound_ctrl:1
	ds_read_b128 v[80:83], v48 offset:24832
	ds_read_b128 v[84:87], v48 offset:25088
	v_add_f32_dpp v15, v15, v15 row_ror:2 row_mask:0xf bank_mask:0xf bound_ctrl:1
	ds_read_b128 v[88:91], v48 offset:25344
	ds_write2st64_b32 v50, v25, v27 offset0:80 offset1:84
	v_add_f32_dpp v30, v15, v15 row_ror:1 row_mask:0xf bank_mask:0xf bound_ctrl:1
	s_waitcnt lgkmcnt(4)
	v_pk_fma_f32 v[10:11], v[112:113], v[30:31], v[16:17] op_sel_hi:[1,0,1] neg_lo:[0,1,0] neg_hi:[0,1,0]
	v_pk_fma_f32 v[8:9], v[114:115], v[30:31], v[18:19] op_sel_hi:[1,0,1] neg_lo:[0,1,0] neg_hi:[0,1,0]
	v_pk_mul_f32 v[24:25], v[10:11], v[116:117] op_sel:[0,0] op_sel_hi:[0,1]
	v_pk_fma_f32 v[24:25], v[10:11], v[118:119], v[24:25] op_sel:[1,0,0] op_sel_hi:[1,1,1]
	v_pk_fma_f32 v[24:25], v[8:9], v[120:121], v[24:25] op_sel:[0,0,0] op_sel_hi:[0,1,1]
	v_pk_fma_f32 v[24:25], v[8:9], v[122:123], v[24:25] op_sel:[1,0,0] op_sel_hi:[1,1,1]
	v_pk_fma_f32 v[16:17], v[124:125], v[162:163], v[10:11] op_sel:[0,1,0] op_sel_hi:[1,1,1]
	v_pk_fma_f32 v[18:19], v[126:127], v[162:163], v[8:9] op_sel:[0,1,0] op_sel_hi:[1,1,1]
	v_add_f32_dpp v15, v24, v24 row_ror:8 row_mask:0xf bank_mask:0xf bound_ctrl:1
	ds_read_b128 v[92:95], v48 offset:25600
	s_nop 0
	v_add_f32_dpp v15, v15, v15 row_ror:4 row_mask:0xf bank_mask:0xf bound_ctrl:1
	ds_read_b128 v[96:99], v48 offset:25856
	ds_read_b128 v[100:103], v48 offset:26112
	v_add_f32_dpp v15, v15, v15 row_ror:2 row_mask:0xf bank_mask:0xf bound_ctrl:1
	ds_read_b128 v[104:107], v48 offset:26368
	s_nop 0
	v_add_f32_dpp v30, v15, v15 row_ror:1 row_mask:0xf bank_mask:0xf bound_ctrl:1
	v_pk_fma_f32 v[10:11], v[128:129], v[30:31], v[16:17] op_sel_hi:[1,0,1] neg_lo:[0,1,0] neg_hi:[0,1,0]
	v_pk_fma_f32 v[8:9], v[130:131], v[30:31], v[18:19] op_sel_hi:[1,0,1] neg_lo:[0,1,0] neg_hi:[0,1,0]
	v_pk_mul_f32 v[26:27], v[10:11], v[132:133] op_sel:[0,0] op_sel_hi:[0,1]
	v_pk_fma_f32 v[26:27], v[10:11], v[134:135], v[26:27] op_sel:[1,0,0] op_sel_hi:[1,1,1]
	v_pk_fma_f32 v[26:27], v[8:9], v[136:137], v[26:27] op_sel:[0,0,0] op_sel_hi:[0,1,1]
	v_pk_fma_f32 v[26:27], v[8:9], v[138:139], v[26:27] op_sel:[1,0,0] op_sel_hi:[1,1,1]
	v_pk_fma_f32 v[16:17], v[76:77], v[156:157], v[10:11] op_sel_hi:[1,0,1]
	v_pk_fma_f32 v[18:19], v[78:79], v[156:157], v[8:9] op_sel_hi:[1,0,1]
	v_add_f32_dpp v15, v26, v26 row_ror:8 row_mask:0xf bank_mask:0xf bound_ctrl:1
	ds_read_b128 v[108:111], v48 offset:26624
	s_nop 0
	v_add_f32_dpp v15, v15, v15 row_ror:4 row_mask:0xf bank_mask:0xf bound_ctrl:1
	ds_read_b128 v[112:115], v48 offset:26880
	ds_read_b128 v[116:119], v48 offset:27136
	v_add_f32_dpp v15, v15, v15 row_ror:2 row_mask:0xf bank_mask:0xf bound_ctrl:1
	ds_read_b128 v[120:123], v48 offset:27392
	ds_write2st64_b32 v50, v25, v27 offset0:88 offset1:92
	v_add_f32_dpp v30, v15, v15 row_ror:1 row_mask:0xf bank_mask:0xf bound_ctrl:1
	s_waitcnt lgkmcnt(4)
	v_pk_fma_f32 v[10:11], v[80:81], v[30:31], v[16:17] op_sel_hi:[1,0,1] neg_lo:[0,1,0] neg_hi:[0,1,0]
	v_pk_fma_f32 v[8:9], v[82:83], v[30:31], v[18:19] op_sel_hi:[1,0,1] neg_lo:[0,1,0] neg_hi:[0,1,0]
	v_pk_mul_f32 v[24:25], v[10:11], v[84:85] op_sel:[0,0] op_sel_hi:[0,1]
	v_pk_fma_f32 v[24:25], v[10:11], v[86:87], v[24:25] op_sel:[1,0,0] op_sel_hi:[1,1,1]
	v_pk_fma_f32 v[24:25], v[8:9], v[88:89], v[24:25] op_sel:[0,0,0] op_sel_hi:[0,1,1]
	v_pk_fma_f32 v[24:25], v[8:9], v[90:91], v[24:25] op_sel:[1,0,0] op_sel_hi:[1,1,1]
	v_pk_fma_f32 v[16:17], v[92:93], v[156:157], v[10:11] op_sel:[0,1,0] op_sel_hi:[1,1,1]
	v_pk_fma_f32 v[18:19], v[94:95], v[156:157], v[8:9] op_sel:[0,1,0] op_sel_hi:[1,1,1]
	v_add_f32_dpp v15, v24, v24 row_ror:8 row_mask:0xf bank_mask:0xf bound_ctrl:1
	ds_read_b128 v[124:127], v48 offset:27648
	s_nop 0
	v_add_f32_dpp v15, v15, v15 row_ror:4 row_mask:0xf bank_mask:0xf bound_ctrl:1
	ds_read_b128 v[128:131], v48 offset:27904
	ds_read_b128 v[132:135], v48 offset:28160
	v_add_f32_dpp v15, v15, v15 row_ror:2 row_mask:0xf bank_mask:0xf bound_ctrl:1
	ds_read_b128 v[136:139], v48 offset:28416
	ds_read_b128 v[160:163], v49 offset:112
	v_add_f32_dpp v30, v15, v15 row_ror:1 row_mask:0xf bank_mask:0xf bound_ctrl:1
	v_pk_fma_f32 v[10:11], v[96:97], v[30:31], v[16:17] op_sel_hi:[1,0,1] neg_lo:[0,1,0] neg_hi:[0,1,0]
	v_pk_fma_f32 v[8:9], v[98:99], v[30:31], v[18:19] op_sel_hi:[1,0,1] neg_lo:[0,1,0] neg_hi:[0,1,0]
	v_pk_mul_f32 v[26:27], v[10:11], v[100:101] op_sel:[0,0] op_sel_hi:[0,1]
	v_pk_fma_f32 v[26:27], v[10:11], v[102:103], v[26:27] op_sel:[1,0,0] op_sel_hi:[1,1,1]
	v_pk_fma_f32 v[26:27], v[8:9], v[104:105], v[26:27] op_sel:[0,0,0] op_sel_hi:[0,1,1]
	v_pk_fma_f32 v[26:27], v[8:9], v[106:107], v[26:27] op_sel:[1,0,0] op_sel_hi:[1,1,1]
	v_pk_fma_f32 v[16:17], v[108:109], v[158:159], v[10:11] op_sel_hi:[1,0,1]
	v_pk_fma_f32 v[18:19], v[110:111], v[158:159], v[8:9] op_sel_hi:[1,0,1]
	v_add_f32_dpp v15, v26, v26 row_ror:8 row_mask:0xf bank_mask:0xf bound_ctrl:1
	ds_read_b128 v[76:79], v48 offset:28672
	s_nop 0
	v_add_f32_dpp v15, v15, v15 row_ror:4 row_mask:0xf bank_mask:0xf bound_ctrl:1
	ds_read_b128 v[80:83], v48 offset:28928
	ds_read_b128 v[84:87], v48 offset:29184
	v_add_f32_dpp v15, v15, v15 row_ror:2 row_mask:0xf bank_mask:0xf bound_ctrl:1
	ds_read_b128 v[88:91], v48 offset:29440
	ds_write2st64_b32 v50, v25, v27 offset0:96 offset1:100
	v_add_f32_dpp v30, v15, v15 row_ror:1 row_mask:0xf bank_mask:0xf bound_ctrl:1
	ds_read_b128 v[56:59], v52
	s_waitcnt lgkmcnt(5)
	v_pk_fma_f32 v[10:11], v[112:113], v[30:31], v[16:17] op_sel_hi:[1,0,1] neg_lo:[0,1,0] neg_hi:[0,1,0]
	v_pk_fma_f32 v[8:9], v[114:115], v[30:31], v[18:19] op_sel_hi:[1,0,1] neg_lo:[0,1,0] neg_hi:[0,1,0]
	v_pk_mul_f32 v[24:25], v[10:11], v[116:117] op_sel:[0,0] op_sel_hi:[0,1]
	v_pk_fma_f32 v[24:25], v[10:11], v[118:119], v[24:25] op_sel:[1,0,0] op_sel_hi:[1,1,1]
	v_pk_fma_f32 v[24:25], v[8:9], v[120:121], v[24:25] op_sel:[0,0,0] op_sel_hi:[0,1,1]
	v_pk_fma_f32 v[24:25], v[8:9], v[122:123], v[24:25] op_sel:[1,0,0] op_sel_hi:[1,1,1]
	v_pk_fma_f32 v[16:17], v[124:125], v[158:159], v[10:11] op_sel:[0,1,0] op_sel_hi:[1,1,1]
	v_pk_fma_f32 v[18:19], v[126:127], v[158:159], v[8:9] op_sel:[0,1,0] op_sel_hi:[1,1,1]
	v_add_f32_dpp v15, v24, v24 row_ror:8 row_mask:0xf bank_mask:0xf bound_ctrl:1
	ds_read_b128 v[92:95], v48 offset:29696
	s_nop 0
	v_add_f32_dpp v15, v15, v15 row_ror:4 row_mask:0xf bank_mask:0xf bound_ctrl:1
	ds_read_b128 v[96:99], v48 offset:29952
	ds_read_b128 v[100:103], v48 offset:30208
	v_add_f32_dpp v15, v15, v15 row_ror:2 row_mask:0xf bank_mask:0xf bound_ctrl:1
	ds_read_b128 v[104:107], v48 offset:30464
	s_nop 0
	v_add_f32_dpp v30, v15, v15 row_ror:1 row_mask:0xf bank_mask:0xf bound_ctrl:1
	s_waitcnt lgkmcnt(4)
	v_min_u32_e32 v56, v56, v57
	v_min3_u32 v56, v56, v58, v59
	v_pk_fma_f32 v[10:11], v[128:129], v[30:31], v[16:17] op_sel_hi:[1,0,1] neg_lo:[0,1,0] neg_hi:[0,1,0]
	v_pk_fma_f32 v[8:9], v[130:131], v[30:31], v[18:19] op_sel_hi:[1,0,1] neg_lo:[0,1,0] neg_hi:[0,1,0]
	v_pk_mul_f32 v[26:27], v[10:11], v[132:133] op_sel:[0,0] op_sel_hi:[0,1]
	v_pk_fma_f32 v[26:27], v[10:11], v[134:135], v[26:27] op_sel:[1,0,0] op_sel_hi:[1,1,1]
	v_pk_fma_f32 v[26:27], v[8:9], v[136:137], v[26:27] op_sel:[0,0,0] op_sel_hi:[0,1,1]
	v_pk_fma_f32 v[26:27], v[8:9], v[138:139], v[26:27] op_sel:[1,0,0] op_sel_hi:[1,1,1]
	v_pk_fma_f32 v[16:17], v[76:77], v[160:161], v[10:11] op_sel_hi:[1,0,1]
	v_pk_fma_f32 v[18:19], v[78:79], v[160:161], v[8:9] op_sel_hi:[1,0,1]
	v_add_f32_dpp v15, v26, v26 row_ror:8 row_mask:0xf bank_mask:0xf bound_ctrl:1
	ds_read_b128 v[108:111], v48 offset:30720
	s_nop 0
	v_add_f32_dpp v15, v15, v15 row_ror:4 row_mask:0xf bank_mask:0xf bound_ctrl:1
	ds_read_b128 v[112:115], v48 offset:30976
	ds_read_b128 v[116:119], v48 offset:31232
	v_add_f32_dpp v15, v15, v15 row_ror:2 row_mask:0xf bank_mask:0xf bound_ctrl:1
	ds_read_b128 v[120:123], v48 offset:31488
	ds_read_b128 v[140:143], v48 offset:34560
	ds_write2st64_b32 v50, v25, v27 offset0:104 offset1:108
	v_add_f32_dpp v30, v15, v15 row_ror:1 row_mask:0xf bank_mask:0xf bound_ctrl:1
	s_waitcnt lgkmcnt(5)
	v_pk_fma_f32 v[10:11], v[80:81], v[30:31], v[16:17] op_sel_hi:[1,0,1] neg_lo:[0,1,0] neg_hi:[0,1,0]
	v_pk_fma_f32 v[8:9], v[82:83], v[30:31], v[18:19] op_sel_hi:[1,0,1] neg_lo:[0,1,0] neg_hi:[0,1,0]
	v_pk_mul_f32 v[24:25], v[10:11], v[84:85] op_sel:[0,0] op_sel_hi:[0,1]
	v_pk_fma_f32 v[24:25], v[10:11], v[86:87], v[24:25] op_sel:[1,0,0] op_sel_hi:[1,1,1]
	v_pk_fma_f32 v[24:25], v[8:9], v[88:89], v[24:25] op_sel:[0,0,0] op_sel_hi:[0,1,1]
	v_pk_fma_f32 v[24:25], v[8:9], v[90:91], v[24:25] op_sel:[1,0,0] op_sel_hi:[1,1,1]
	v_pk_fma_f32 v[16:17], v[92:93], v[160:161], v[10:11] op_sel:[0,1,0] op_sel_hi:[1,1,1]
	v_pk_fma_f32 v[18:19], v[94:95], v[160:161], v[8:9] op_sel:[0,1,0] op_sel_hi:[1,1,1]
	v_add_f32_dpp v15, v24, v24 row_ror:8 row_mask:0xf bank_mask:0xf bound_ctrl:1
	ds_read_b128 v[124:127], v48 offset:31744
	s_nop 0
	v_add_f32_dpp v15, v15, v15 row_ror:4 row_mask:0xf bank_mask:0xf bound_ctrl:1
	ds_read_b128 v[128:131], v48 offset:32000
	ds_read_b128 v[132:135], v48 offset:32256
	v_add_f32_dpp v15, v15, v15 row_ror:2 row_mask:0xf bank_mask:0xf bound_ctrl:1
	ds_read_b128 v[136:139], v48 offset:32512
	s_nop 0
	v_add_f32_dpp v30, v15, v15 row_ror:1 row_mask:0xf bank_mask:0xf bound_ctrl:1
	v_readfirstlane_b32 s54, v56
	s_add_u32 s64, s6, 2
	s_cmp_lt_u32 s54, s64
	s_cbranch_scc1 .Lss_spin_1

.Lsc_G:
	v_add_u32_e32 v1, 0xffffff00, v173
	v_lshrrev_b32_e32 v2, 3, v1
	v_and_b32_e32 v3, 7, v1
	s_and_b32 s8, s4, 7
	s_bfe_u32 s10, s4, 0x20003
	s_lshr_b32 s11, s4, 7
	s_bfe_u32 s9, s4, 0x20005
	s_lshl_b32 s9, s9, 13
	v_readlane_b32 s50, v242, 0
	v_readlane_b32 s51, v242, 1
	v_readlane_b32 s16, v242, 62
	s_load_dwordx4 s[12:15], s[50:51], 0x68
	s_add_u32 s36, s90, 0x5e00000
	s_addc_u32 s37, s91, 0
	s_add_u32 s38, s90, 0x7e00000
	s_addc_u32 s39, s91, 0
	s_add_u32 s44, s90, 0x9e00000
	s_addc_u32 s45, s91, 0
	s_add_u32 s46, s90, 0x1c00000
	s_addc_u32 s47, s91, 0
	s_lshl_b32 s68, s11, 25
	s_add_u32 s69, s68, 0x13e00000
	s_add_u32 s40, s90, s69
	s_addc_u32 s41, s91, 0
	s_add_u32 s69, s68, 0x17e00000
	s_add_u32 s42, s90, s69
	s_addc_u32 s43, s91, 0
	s_lshl_b32 s68, s11, 26
	s_add_u32 s68, s68, 0xbe00000
	s_add_u32 s48, s90, s68
	s_addc_u32 s49, s91, 0
	s_cmp_eq_u32 s11, 0
	s_mov_b32 s54, 0x8000
	s_movk_i32 s55, 0x400
	s_mov_b32 s64, 0x10000
	s_cselect_b32 s54, s54, 0xffff8000
	s_cselect_b32 s55, s55, 0xfffffc00
	s_cselect_b32 s64, s64, 0xffff0000
	s_cselect_b64 vcc, -1, 0
	v_sub_u32_e32 v4, 0x1fff, v2
	s_nop 3
	v_cndmask_b32_e32 v4, v4, v2, vcc
	v_add_u32_e32 v4, s9, v4
	s_lshl_b32 s68, s8, 7
	v_lshlrev_b32_e32 v5, 10, v4
	v_lshl_add_u32 v5, v3, 3, v5
	v_add_u32_e32 v5, s68, v5
	s_lshl_b32 s69, s8, 2
	v_lshlrev_b32_e32 v6, 5, v4
	v_add_u32_e32 v6, s69, v6
	s_lshl_b32 s69, s10, 5
	s_add_i32 s69, s69, s68
	v_lshlrev_b32_e32 v9, 10, v4
	v_lshl_add_u32 v9, v3, 2, v9
	v_add_u32_e32 v9, s69, v9
	s_lshl_b32 s65, s69, 1
	v_mul_u32_u24_e32 v8, 1024, v2
	v_lshl_add_u32 v8, v3, 4, v8
	v_add_u32_e32 v138, 512, v8
	v_add_u32_e32 v140, 35328, v8
	v_add_u32_e32 v152, -4, v0
	v_mul_u32_u24_e32 v152, 4608, v152
	v_add_u32_e32 v152, 143936, v152
	v_and_b32_e32 v156, 7, v2
	v_lshlrev_b32_e32 v153, 8, v156
	v_lshl_add_u32 v153, v3, 4, v153
	v_add_u32_e32 v153, v152, v153
	v_and_b32_e32 v154, 63, v1
	v_lshl_add_u32 v154, v154, 2, v152
	v_add_u32_e32 v155, 2048, v154
	v_add_u32_e32 v139, -1, v2
	v_mul_u32_u24_e32 v139, 1024, v139
	v_lshl_add_u32 v139, v3, 4, v139
	v_add_u32_e32 v141, 35328, v139
	v_add_u32_e32 v139, 512, v139
	v_cmp_eq_u32_e32 vcc, 0, v2
	s_nop 1
	v_cndmask_b32_e32 v139, v139, v152, vcc
	v_cndmask_b32_e32 v141, v141, v152, vcc
	v_lshrrev_b32_e32 v158, 3, v2
	v_lshlrev_b32_e32 v158, 8, v158
	v_lshl_add_u32 v158, v3, 4, v158
	v_and_b32_e32 v159, 63, v1
	v_lshlrev_b32_e32 v159, 2, v159
	v_add_u32_e32 v106, -4, v0
	v_lshl_add_u32 v159, v106, 8, v159
	v_add_u32_e32 v159, 33792, v159
	v_add_u32_e32 v106, -4, v0
	v_lshlrev_b32_e32 v162, 2, v106
	v_add_u32_e32 v162, 139808, v162
	v_mov_b32_e32 v163, 139808
	v_and_b32_e32 v181, 63, v1
	v_lshlrev_b32_e32 v181, 2, v181
	v_add_u32_e32 v181, 139840, v181
	v_lshl_add_u32 v180, v106, 8, v181
	v_cmp_gt_u32_e32 vcc, v106, v169
	s_nop 1
	v_cndmask_b32_e64 v174, 0, -1, vcc
	v_mov_b32_e32 v177, 0x7fffffff
	v_cndmask_b32_e32 v177, v177, v169, vcc
	v_cmp_lt_u32_e32 vcc, 1, v106
	s_nop 1
	v_cndmask_b32_e64 v175, 0, -1, vcc
	v_mov_b32_e32 v178, 0x7fffffff
	v_cndmask_b32_e32 v178, v178, v169, vcc
	v_cmp_lt_u32_e32 vcc, 2, v106
	s_nop 1
	v_cndmask_b32_e64 v176, 0, -1, vcc
	v_mov_b32_e32 v179, 0x7fffffff
	v_cndmask_b32_e32 v179, v179, v169, vcc
	v_add_u32_e32 v158, 32768, v158
	v_mul_u32_u24_e32 v142, 288, v3
	v_lshl_add_u32 v142, v2, 2, v142
	v_add_u32_e32 v143, 71936, v142
	v_add_u32_e32 v142, 69632, v142
	s_lshl_b32 s69, s8, 6
	s_add_i32 s69, s69, s16
	v_lshl_add_u32 v106, v3, 2, s69
	v_lshlrev_b32_e32 v106, 2, v106
	s_waitcnt lgkmcnt(0)
	global_load_dwordx4 v[12:15], v106, s[12:13]
	global_load_dwordx4 v[16:19], v106, s[12:13] offset:128
	global_load_dwordx4 v[20:23], v106, s[14:15]
	global_load_dwordx4 v[24:27], v106, s[14:15] offset:128
	global_load_dwordx2 v[28:29], v5, s[36:37]
	global_load_dwordx2 v[30:31], v5, s[36:37] offset:64
	global_load_dwordx2 v[32:33], v5, s[38:39]
	global_load_dwordx2 v[34:35], v5, s[38:39] offset:64
	global_load_dwordx2 v[36:37], v5, s[40:41]
	global_load_dwordx2 v[38:39], v5, s[40:41] offset:64
	global_load_dwordx2 v[40:41], v5, s[42:43]
	global_load_dwordx2 v[42:43], v5, s[42:43] offset:64
	global_load_dword v44, v6, s[46:47]
	global_load_dword v45, v9, s[44:45]
	v_add_u32_e32 v5, s54, v5
	v_add_u32_e32 v6, s55, v6
	v_add_u32_e32 v9, s54, v9
	global_load_dwordx2 v[46:47], v5, s[36:37]
	global_load_dwordx2 v[48:49], v5, s[36:37] offset:64
	global_load_dwordx2 v[50:51], v5, s[38:39]
	global_load_dwordx2 v[52:53], v5, s[38:39] offset:64
	global_load_dwordx2 v[54:55], v5, s[40:41]
	global_load_dwordx2 v[56:57], v5, s[40:41] offset:64
	global_load_dwordx2 v[58:59], v5, s[42:43]
	global_load_dwordx2 v[60:61], v5, s[42:43] offset:64
	global_load_dword v62, v6, s[46:47]
	global_load_dword v63, v9, s[44:45]
	v_add_u32_e32 v5, s54, v5
	v_add_u32_e32 v6, s55, v6
	v_add_u32_e32 v9, s54, v9
	v_and_b32_e32 v166, 15, v1
	v_lshrrev_b32_e32 v167, 4, v1
	v_sub_u32_e32 v4, 0x1fff, v167
	s_cmp_eq_u32 s11, 0
	s_cselect_b64 vcc, -1, 0
	s_nop 3
	v_cndmask_b32_e32 v4, v4, v167, vcc
	v_add_u32_e32 v4, s9, v4
	v_lshlrev_b32_e32 v7, 11, v4
	v_lshl_add_u32 v7, v166, 2, v7
	v_add_u32_e32 v7, s65, v7
	s_ashr_i32 s65, s64, 1
	v_add_u32_e32 v165, s65, v7
	v_lshlrev_b32_e32 v11, 10, v167
	v_lshl_add_u32 v11, v166, 6, v11
	v_add_u32_e32 v11, 74240, v11
	v_lshrrev_b32_e32 v166, 2, v166
	v_add_u32_e32 v2, 0, v166
	v_and_b32_e32 v2, 3, v2
	v_lshl_add_u32 v2, v2, 4, v11
	v_add_u32_e32 v3, 1, v166
	v_and_b32_e32 v3, 3, v3
	v_lshl_add_u32 v3, v3, 4, v11
	v_add_u32_e32 v4, 2, v166
	v_and_b32_e32 v4, 3, v4
	v_lshl_add_u32 v4, v4, 4, v11
	v_add_u32_e32 v10, 3, v166
	v_and_b32_e32 v10, 3, v10
	v_lshl_add_u32 v10, v10, 4, v11
	v_cmp_eq_u32_e64 s[12:13], 0, v156
	v_cmp_eq_u32_e64 s[14:15], 7, v156
	s_mov_b32 s6, 0
	v_mov_b32_e32 v144, 139792
	v_mov_b32_e32 v145, v164
	v_mov_b32_e32 v146, 0
	s_waitcnt vmcnt(10)
	v_lshlrev_b32_e32 v64, 16, v36
	v_and_b32_e32 v65, 0xffff0000, v36
	v_mul_f32_e32 v64, 0x3fb8aa3b, v64
	v_mul_f32_e32 v65, 0x3fb8aa3b, v65
	v_lshlrev_b32_e32 v66, 16, v37
	v_and_b32_e32 v67, 0xffff0000, v37
	v_mul_f32_e32 v66, 0x3fb8aa3b, v66
	v_mul_f32_e32 v67, 0x3fb8aa3b, v67
	v_lshlrev_b32_e32 v68, 16, v38
	v_and_b32_e32 v69, 0xffff0000, v38
	v_mul_f32_e32 v68, 0x3fb8aa3b, v68
	v_mul_f32_e32 v69, 0x3fb8aa3b, v69
	v_lshlrev_b32_e32 v70, 16, v39
	v_and_b32_e32 v71, 0xffff0000, v39
	v_mul_f32_e32 v70, 0x3fb8aa3b, v70
	v_mul_f32_e32 v71, 0x3fb8aa3b, v71
	ds_write_b128 v153, v[64:67]
	ds_write_b128 v153, v[68:71] offset:128
	s_waitcnt lgkmcnt(0)
	ds_read_b32 v124, v154 offset:0
	ds_read_b32 v125, v154 offset:256
	ds_read_b32 v126, v154 offset:512
	ds_read_b32 v127, v154 offset:768
	ds_read_b32 v128, v154 offset:1024
	ds_read_b32 v129, v154 offset:1280
	ds_read_b32 v130, v154 offset:1536
	ds_read_b32 v131, v154 offset:1792
	v_lshlrev_b32_e32 v108, 16, v32
	v_and_b32_e32 v109, 0xffff0000, v32
	v_lshlrev_b32_e32 v110, 16, v40
	v_and_b32_e32 v111, 0xffff0000, v40
	v_lshlrev_b32_e32 v96, 16, v28
	v_and_b32_e32 v97, 0xffff0000, v28
	v_pk_add_f32 v[112:113], v[110:111], -1.0 op_sel_hi:[1,0]
	v_pk_mul_f32 v[114:115], v[12:13], v[108:109]
	v_pk_fma_f32 v[112:113], v[20:21], v[112:113], 1.0 op_sel_hi:[1,1,0]
	v_pk_mul_f32 v[88:89], v[44:45], v[114:115] op_sel_hi:[0,1]
	v_pk_mul_f32 v[72:73], v[112:113], v[108:109]
	v_pk_mul_f32 v[80:81], v[88:89], v[110:111]
	v_lshlrev_b32_e32 v108, 16, v33
	v_and_b32_e32 v109, 0xffff0000, v33
	v_lshlrev_b32_e32 v110, 16, v41
	v_and_b32_e32 v111, 0xffff0000, v41
	v_lshlrev_b32_e32 v98, 16, v29
	v_and_b32_e32 v99, 0xffff0000, v29
	v_pk_add_f32 v[112:113], v[110:111], -1.0 op_sel_hi:[1,0]
	v_pk_mul_f32 v[114:115], v[14:15], v[108:109]
	v_pk_fma_f32 v[112:113], v[22:23], v[112:113], 1.0 op_sel_hi:[1,1,0]
	v_pk_mul_f32 v[90:91], v[44:45], v[114:115] op_sel_hi:[0,1]
	v_pk_mul_f32 v[74:75], v[112:113], v[108:109]
	v_pk_mul_f32 v[82:83], v[90:91], v[110:111]
	v_lshlrev_b32_e32 v108, 16, v34
	v_and_b32_e32 v109, 0xffff0000, v34
	v_lshlrev_b32_e32 v110, 16, v42
	v_and_b32_e32 v111, 0xffff0000, v42
	v_lshlrev_b32_e32 v100, 16, v30
	v_and_b32_e32 v101, 0xffff0000, v30
	v_pk_add_f32 v[112:113], v[110:111], -1.0 op_sel_hi:[1,0]
	v_pk_mul_f32 v[114:115], v[16:17], v[108:109]
	v_pk_fma_f32 v[112:113], v[24:25], v[112:113], 1.0 op_sel_hi:[1,1,0]
	v_pk_mul_f32 v[92:93], v[44:45], v[114:115] op_sel_hi:[0,1]
	v_pk_mul_f32 v[76:77], v[112:113], v[108:109]
	v_pk_mul_f32 v[84:85], v[92:93], v[110:111]
	v_lshlrev_b32_e32 v108, 16, v35
	v_and_b32_e32 v109, 0xffff0000, v35
	v_lshlrev_b32_e32 v110, 16, v43
	v_and_b32_e32 v111, 0xffff0000, v43
	v_lshlrev_b32_e32 v102, 16, v31
	v_and_b32_e32 v103, 0xffff0000, v31
	v_pk_add_f32 v[112:113], v[110:111], -1.0 op_sel_hi:[1,0]
	v_pk_mul_f32 v[114:115], v[18:19], v[108:109]
	v_pk_fma_f32 v[112:113], v[26:27], v[112:113], 1.0 op_sel_hi:[1,1,0]
	v_pk_mul_f32 v[94:95], v[44:45], v[114:115] op_sel_hi:[0,1]
	v_pk_mul_f32 v[78:79], v[112:113], v[108:109]
	v_pk_mul_f32 v[86:87], v[94:95], v[110:111]
	v_lshlrev_b32_e32 v104, 16, v45
	v_and_b32_e32 v105, 0xffff0000, v45
	s_waitcnt lgkmcnt(0)
	v_add_f32_e32 v125, v124, v125
	v_add_f32_e32 v126, v125, v126
	v_add_f32_e32 v127, v126, v127
	v_add_f32_e32 v128, v127, v128
	v_add_f32_e32 v129, v128, v129
	v_add_f32_e32 v130, v129, v130
	v_add_f32_e32 v131, v130, v131
	s_and_b32 s72, s6, 3
	s_lshl_b32 s72, s72, 10
	v_add_u32_e32 v182, s72, v180
	v_add_u32_e32 v183, s72, v181
	ds_write_b32 v182, v131
	v_add_u32_e32 v184, 1, v146
	s_waitcnt lgkmcnt(0)
	ds_write_b32 v162, v184
	s_add_u32 s73, s6, 1
	s_mov_b32 s69, 0x100000
.Lsc_gf_poll1:
	ds_read_b128 v[148:151], v163
	s_waitcnt lgkmcnt(0)
	v_max_u32_e32 v148, v148, v177
	v_max_u32_e32 v149, v149, v178
	v_max_u32_e32 v150, v150, v179
	v_min3_u32 v148, v148, v149, v150
	s_sub_u32 s69, s69, 1
	s_nop 1
	v_readfirstlane_b32 s68, v148
	s_cmp_eq_u32 s69, 0
	s_cbranch_scc1 .Lsc_gf_go1
	s_cmp_lt_u32 s68, s73
	s_cbranch_scc1 .Lsc_gf_poll1
.Lsc_gf_go1:
	ds_read_b32 v185, v183
	ds_read_b32 v186, v183 offset:256
	ds_read_b32 v187, v183 offset:512
	s_waitcnt lgkmcnt(0)
	v_and_b32_e32 v185, v174, v185
	v_and_b32_e32 v186, v175, v186
	v_and_b32_e32 v187, v176, v187
	v_add_f32_e32 v185, v185, v186
	v_add_f32_e32 v185, v185, v187
	v_add_f32_e32 v124, v185, v124
	v_add_f32_e32 v125, v185, v125
	v_add_f32_e32 v126, v185, v126
	v_add_f32_e32 v127, v185, v127
	v_add_f32_e32 v128, v185, v128
	v_add_f32_e32 v129, v185, v129
	v_add_f32_e32 v130, v185, v130
	v_add_f32_e32 v131, v185, v131
	v_exp_f32_e64 v188, -v185
	v_exp_f32_e64 v124, -v124
	v_exp_f32_e64 v125, -v125
	v_exp_f32_e64 v126, -v126
	v_exp_f32_e64 v127, -v127
	v_exp_f32_e64 v128, -v128
	v_exp_f32_e64 v129, -v129
	v_exp_f32_e64 v130, -v130
	v_exp_f32_e64 v131, -v131
	s_nop 0
	ds_write_b32 v155, v188
	ds_write_b32 v155, v124 offset:256
	ds_write_b32 v155, v125 offset:512
	ds_write_b32 v155, v126 offset:768
	ds_write_b32 v155, v127 offset:1024
	ds_write_b32 v155, v128 offset:1280
	ds_write_b32 v155, v129 offset:1536
	ds_write_b32 v155, v130 offset:1792
	ds_write_b32 v155, v131 offset:2048
	v_mov_b32_e32 v161, v131
	s_waitcnt lgkmcnt(0)
	ds_read_b128 v[64:67], v153 offset:2048
	ds_read_b128 v[68:71], v153 offset:2176
	ds_read_b128 v[116:119], v153 offset:2304
	ds_read_b128 v[120:123], v153 offset:2432
	s_waitcnt lgkmcnt(0)
	v_rcp_f32_e32 v124, v116
	v_rcp_f32_e32 v125, v117
	v_rcp_f32_e32 v126, v118
	v_rcp_f32_e32 v127, v119
	v_rcp_f32_e32 v128, v120
	v_rcp_f32_e32 v129, v121
	v_rcp_f32_e32 v130, v122
	v_rcp_f32_e32 v131, v123
	s_nop 1
	v_pk_mul_f32 v[72:73], v[72:73], v[124:125]
	v_pk_mul_f32 v[80:81], v[80:81], v[124:125]
	v_pk_mul_f32 v[88:89], v[88:89], v[64:65]
	v_pk_mul_f32 v[96:97], v[96:97], v[116:117]
	v_pk_mul_f32 v[74:75], v[74:75], v[126:127]
	v_pk_mul_f32 v[82:83], v[82:83], v[126:127]
	v_pk_mul_f32 v[90:91], v[90:91], v[66:67]
	v_pk_mul_f32 v[98:99], v[98:99], v[118:119]
	v_pk_mul_f32 v[76:77], v[76:77], v[128:129]
	v_pk_mul_f32 v[84:85], v[84:85], v[128:129]
	v_pk_mul_f32 v[92:93], v[92:93], v[68:69]
	v_pk_mul_f32 v[100:101], v[100:101], v[120:121]
	v_pk_mul_f32 v[78:79], v[78:79], v[130:131]
	v_pk_mul_f32 v[86:87], v[86:87], v[130:131]
	v_pk_mul_f32 v[94:95], v[94:95], v[70:71]
	v_pk_mul_f32 v[102:103], v[102:103], v[122:123]
	global_load_dwordx2 v[28:29], v5, s[36:37]
	global_load_dwordx2 v[30:31], v5, s[36:37] offset:64
	global_load_dwordx2 v[32:33], v5, s[38:39]
	global_load_dwordx2 v[34:35], v5, s[38:39] offset:64
	global_load_dwordx2 v[36:37], v5, s[40:41]
	global_load_dwordx2 v[38:39], v5, s[40:41] offset:64
	global_load_dwordx2 v[40:41], v5, s[42:43]
	global_load_dwordx2 v[42:43], v5, s[42:43] offset:64
	global_load_dword v44, v6, s[46:47]
	global_load_dword v45, v9, s[44:45]
	v_add_u32_e32 v5, s54, v5
	v_add_u32_e32 v6, s55, v6
	v_add_u32_e32 v9, s54, v9
	ds_write_b32 v159, v161 offset:0
	ds_write_b128 v8, v[72:75] offset:0
	ds_write_b128 v8, v[76:79] offset:128
	ds_write_b128 v8, v[80:83] offset:256
	ds_write_b128 v8, v[84:87] offset:384
	ds_write2_b32 v138, v96, v97 offset0:1 offset1:3
	ds_write2_b32 v139, v88, v89 offset0:0 offset1:2
	ds_write2_b32 v138, v98, v99 offset0:65 offset1:67
	ds_write2_b32 v139, v90, v91 offset0:64 offset1:66
	ds_write2_b32 v138, v100, v101 offset0:33 offset1:35
	ds_write2_b32 v139, v92, v93 offset0:32 offset1:34
	ds_write2_b32 v138, v102, v103 offset0:97 offset1:99
	ds_write2_b32 v139, v94, v95 offset0:96 offset1:98
	ds_write2_b32 v142, v104, v105 offset1:36
	s_and_saveexec_b64 s[68:69], s[12:13]
	ds_write_b128 v158, v[88:91] offset:0
	ds_write_b128 v158, v[92:95] offset:128
	s_mov_b64 exec, s[68:69]
	s_add_i32 s6, s6, 1
	v_add_u32_e32 v146, 1, v146
	s_waitcnt lgkmcnt(0)
	ds_write_b32 v145, v146
	s_waitcnt vmcnt(10)
	v_lshlrev_b32_e32 v64, 16, v54
	v_and_b32_e32 v65, 0xffff0000, v54
	v_mul_f32_e32 v64, 0x3fb8aa3b, v64
	v_mul_f32_e32 v65, 0x3fb8aa3b, v65
	v_lshlrev_b32_e32 v66, 16, v55
	v_and_b32_e32 v67, 0xffff0000, v55
	v_mul_f32_e32 v66, 0x3fb8aa3b, v66
	v_mul_f32_e32 v67, 0x3fb8aa3b, v67
	v_lshlrev_b32_e32 v68, 16, v56
	v_and_b32_e32 v69, 0xffff0000, v56
	v_mul_f32_e32 v68, 0x3fb8aa3b, v68
	v_mul_f32_e32 v69, 0x3fb8aa3b, v69
	v_lshlrev_b32_e32 v70, 16, v57
	v_and_b32_e32 v71, 0xffff0000, v57
	v_mul_f32_e32 v70, 0x3fb8aa3b, v70
	v_mul_f32_e32 v71, 0x3fb8aa3b, v71
	ds_write_b128 v153, v[64:67]
	ds_write_b128 v153, v[68:71] offset:128
	s_waitcnt lgkmcnt(0)
	ds_read_b32 v124, v154 offset:0
	ds_read_b32 v125, v154 offset:256
	ds_read_b32 v126, v154 offset:512
	ds_read_b32 v127, v154 offset:768
	ds_read_b32 v128, v154 offset:1024
	ds_read_b32 v129, v154 offset:1280
	ds_read_b32 v130, v154 offset:1536
	ds_read_b32 v131, v154 offset:1792
	v_lshlrev_b32_e32 v108, 16, v50
	v_and_b32_e32 v109, 0xffff0000, v50
	v_lshlrev_b32_e32 v110, 16, v58
	v_and_b32_e32 v111, 0xffff0000, v58
	v_lshlrev_b32_e32 v96, 16, v46
	v_and_b32_e32 v97, 0xffff0000, v46
	v_pk_add_f32 v[112:113], v[110:111], -1.0 op_sel_hi:[1,0]
	v_pk_mul_f32 v[114:115], v[12:13], v[108:109]
	v_pk_fma_f32 v[112:113], v[20:21], v[112:113], 1.0 op_sel_hi:[1,1,0]
	v_pk_mul_f32 v[88:89], v[62:63], v[114:115] op_sel_hi:[0,1]
	v_pk_mul_f32 v[72:73], v[112:113], v[108:109]
	v_pk_mul_f32 v[80:81], v[88:89], v[110:111]
	v_lshlrev_b32_e32 v108, 16, v51
	v_and_b32_e32 v109, 0xffff0000, v51
	v_lshlrev_b32_e32 v110, 16, v59
	v_and_b32_e32 v111, 0xffff0000, v59
	v_lshlrev_b32_e32 v98, 16, v47
	v_and_b32_e32 v99, 0xffff0000, v47
	v_pk_add_f32 v[112:113], v[110:111], -1.0 op_sel_hi:[1,0]
	v_pk_mul_f32 v[114:115], v[14:15], v[108:109]
	v_pk_fma_f32 v[112:113], v[22:23], v[112:113], 1.0 op_sel_hi:[1,1,0]
	v_pk_mul_f32 v[90:91], v[62:63], v[114:115] op_sel_hi:[0,1]
	v_pk_mul_f32 v[74:75], v[112:113], v[108:109]
	v_pk_mul_f32 v[82:83], v[90:91], v[110:111]
	v_lshlrev_b32_e32 v108, 16, v52
	v_and_b32_e32 v109, 0xffff0000, v52
	v_lshlrev_b32_e32 v110, 16, v60
	v_and_b32_e32 v111, 0xffff0000, v60
	v_lshlrev_b32_e32 v100, 16, v48
	v_and_b32_e32 v101, 0xffff0000, v48
	v_pk_add_f32 v[112:113], v[110:111], -1.0 op_sel_hi:[1,0]
	v_pk_mul_f32 v[114:115], v[16:17], v[108:109]
	v_pk_fma_f32 v[112:113], v[24:25], v[112:113], 1.0 op_sel_hi:[1,1,0]
	v_pk_mul_f32 v[92:93], v[62:63], v[114:115] op_sel_hi:[0,1]
	v_pk_mul_f32 v[76:77], v[112:113], v[108:109]
	v_pk_mul_f32 v[84:85], v[92:93], v[110:111]
	v_lshlrev_b32_e32 v108, 16, v53
	v_and_b32_e32 v109, 0xffff0000, v53
	v_lshlrev_b32_e32 v110, 16, v61
	v_and_b32_e32 v111, 0xffff0000, v61
	v_lshlrev_b32_e32 v102, 16, v49
	v_and_b32_e32 v103, 0xffff0000, v49
	v_pk_add_f32 v[112:113], v[110:111], -1.0 op_sel_hi:[1,0]
	v_pk_mul_f32 v[114:115], v[18:19], v[108:109]
	v_pk_fma_f32 v[112:113], v[26:27], v[112:113], 1.0 op_sel_hi:[1,1,0]
	v_pk_mul_f32 v[94:95], v[62:63], v[114:115] op_sel_hi:[0,1]
	v_pk_mul_f32 v[78:79], v[112:113], v[108:109]
	v_pk_mul_f32 v[86:87], v[94:95], v[110:111]
	v_lshlrev_b32_e32 v104, 16, v63
	v_and_b32_e32 v105, 0xffff0000, v63
	s_waitcnt lgkmcnt(0)
	v_add_f32_e32 v125, v124, v125
	v_add_f32_e32 v126, v125, v126
	v_add_f32_e32 v127, v126, v127
	v_add_f32_e32 v128, v127, v128
	v_add_f32_e32 v129, v128, v129
	v_add_f32_e32 v130, v129, v130
	v_add_f32_e32 v131, v130, v131
	s_and_b32 s72, s6, 3
	s_lshl_b32 s72, s72, 10
	v_add_u32_e32 v182, s72, v180
	v_add_u32_e32 v183, s72, v181
	ds_write_b32 v182, v131
	v_add_u32_e32 v184, 1, v146
	s_waitcnt lgkmcnt(0)
	ds_write_b32 v162, v184
	s_add_u32 s73, s6, 1
	s_mov_b32 s69, 0x100000

.Lsc_gf_go2:
	ds_read_b32 v185, v183
	ds_read_b32 v186, v183 offset:256
	ds_read_b32 v187, v183 offset:512
	s_waitcnt lgkmcnt(0)
	v_and_b32_e32 v185, v174, v185
	v_and_b32_e32 v186, v175, v186
	v_and_b32_e32 v187, v176, v187
	v_add_f32_e32 v185, v185, v186
	v_add_f32_e32 v185, v185, v187
	v_add_f32_e32 v124, v185, v124
	v_add_f32_e32 v125, v185, v125
	v_add_f32_e32 v126, v185, v126
	v_add_f32_e32 v127, v185, v127
	v_add_f32_e32 v128, v185, v128
	v_add_f32_e32 v129, v185, v129
	v_add_f32_e32 v130, v185, v130
	v_add_f32_e32 v131, v185, v131
	v_exp_f32_e64 v188, -v185
	v_exp_f32_e64 v124, -v124
	v_exp_f32_e64 v125, -v125
	v_exp_f32_e64 v126, -v126
	v_exp_f32_e64 v127, -v127
	v_exp_f32_e64 v128, -v128
	v_exp_f32_e64 v129, -v129
	v_exp_f32_e64 v130, -v130
	v_exp_f32_e64 v131, -v131
	s_nop 0
	ds_write_b32 v155, v188
	ds_write_b32 v155, v124 offset:256
	ds_write_b32 v155, v125 offset:512
	ds_write_b32 v155, v126 offset:768
	ds_write_b32 v155, v127 offset:1024
	ds_write_b32 v155, v128 offset:1280
	ds_write_b32 v155, v129 offset:1536
	ds_write_b32 v155, v130 offset:1792
	ds_write_b32 v155, v131 offset:2048
	v_mov_b32_e32 v161, v131
	s_waitcnt lgkmcnt(0)
	ds_read_b128 v[64:67], v153 offset:2048
	ds_read_b128 v[68:71], v153 offset:2176
	ds_read_b128 v[116:119], v153 offset:2304
	ds_read_b128 v[120:123], v153 offset:2432
	s_waitcnt lgkmcnt(0)
	v_rcp_f32_e32 v124, v116
	v_rcp_f32_e32 v125, v117
	v_rcp_f32_e32 v126, v118
	v_rcp_f32_e32 v127, v119
	v_rcp_f32_e32 v128, v120
	v_rcp_f32_e32 v129, v121
	v_rcp_f32_e32 v130, v122
	v_rcp_f32_e32 v131, v123
	s_nop 1
	v_pk_mul_f32 v[72:73], v[72:73], v[124:125]
	v_pk_mul_f32 v[80:81], v[80:81], v[124:125]
	v_pk_mul_f32 v[88:89], v[88:89], v[64:65]
	v_pk_mul_f32 v[96:97], v[96:97], v[116:117]
	v_pk_mul_f32 v[74:75], v[74:75], v[126:127]
	v_pk_mul_f32 v[82:83], v[82:83], v[126:127]
	v_pk_mul_f32 v[90:91], v[90:91], v[66:67]
	v_pk_mul_f32 v[98:99], v[98:99], v[118:119]
	v_pk_mul_f32 v[76:77], v[76:77], v[128:129]
	v_pk_mul_f32 v[84:85], v[84:85], v[128:129]
	v_pk_mul_f32 v[92:93], v[92:93], v[68:69]
	v_pk_mul_f32 v[100:101], v[100:101], v[120:121]
	v_pk_mul_f32 v[78:79], v[78:79], v[130:131]
	v_pk_mul_f32 v[86:87], v[86:87], v[130:131]
	v_pk_mul_f32 v[94:95], v[94:95], v[70:71]
	v_pk_mul_f32 v[102:103], v[102:103], v[122:123]
	global_load_dwordx2 v[46:47], v5, s[36:37]
	global_load_dwordx2 v[48:49], v5, s[36:37] offset:64
	global_load_dwordx2 v[50:51], v5, s[38:39]
	global_load_dwordx2 v[52:53], v5, s[38:39] offset:64
	global_load_dwordx2 v[54:55], v5, s[40:41]
	global_load_dwordx2 v[56:57], v5, s[40:41] offset:64
	global_load_dwordx2 v[58:59], v5, s[42:43]
	global_load_dwordx2 v[60:61], v5, s[42:43] offset:64
	global_load_dword v62, v6, s[46:47]
	global_load_dword v63, v9, s[44:45]
	v_add_u32_e32 v5, s54, v5
	v_add_u32_e32 v6, s55, v6
	v_add_u32_e32 v9, s54, v9
	ds_write_b32 v159, v161 offset:34816
	ds_write_b128 v8, v[72:75] offset:34816
	ds_write_b128 v8, v[76:79] offset:34944
	ds_write_b128 v8, v[80:83] offset:35072
	ds_write_b128 v8, v[84:87] offset:35200
	ds_write2_b32 v140, v96, v97 offset0:1 offset1:3
	ds_write2_b32 v141, v88, v89 offset0:0 offset1:2
	ds_write2_b32 v140, v98, v99 offset0:65 offset1:67
	ds_write2_b32 v141, v90, v91 offset0:64 offset1:66
	ds_write2_b32 v140, v100, v101 offset0:33 offset1:35
	ds_write2_b32 v141, v92, v93 offset0:32 offset1:34
	ds_write2_b32 v140, v102, v103 offset0:97 offset1:99
	ds_write2_b32 v141, v94, v95 offset0:96 offset1:98
	ds_write2_b32 v143, v104, v105 offset1:36
	s_and_saveexec_b64 s[68:69], s[12:13]
	ds_write_b128 v158, v[88:91] offset:34816
	ds_write_b128 v158, v[92:95] offset:34944
	s_mov_b64 exec, s[68:69]
	s_add_i32 s6, s6, 1
	v_add_u32_e32 v146, 1, v146
	s_waitcnt lgkmcnt(0)
	ds_write_b32 v145, v146
.Lsc_G_loop:
	s_waitcnt vmcnt(10)
	v_lshlrev_b32_e32 v64, 16, v36
	v_and_b32_e32 v65, 0xffff0000, v36
	v_mul_f32_e32 v64, 0x3fb8aa3b, v64
	v_mul_f32_e32 v65, 0x3fb8aa3b, v65
	v_lshlrev_b32_e32 v66, 16, v37
	v_and_b32_e32 v67, 0xffff0000, v37
	v_mul_f32_e32 v66, 0x3fb8aa3b, v66
	v_mul_f32_e32 v67, 0x3fb8aa3b, v67
	v_lshlrev_b32_e32 v68, 16, v38
	v_and_b32_e32 v69, 0xffff0000, v38
	v_mul_f32_e32 v68, 0x3fb8aa3b, v68
	v_mul_f32_e32 v69, 0x3fb8aa3b, v69
	v_lshlrev_b32_e32 v70, 16, v39
	v_and_b32_e32 v71, 0xffff0000, v39
	v_mul_f32_e32 v70, 0x3fb8aa3b, v70
	v_mul_f32_e32 v71, 0x3fb8aa3b, v71
	ds_write_b128 v153, v[64:67]
	ds_write_b128 v153, v[68:71] offset:128
	s_waitcnt lgkmcnt(0)
	ds_read_b32 v124, v154 offset:0
	ds_read_b32 v125, v154 offset:256
	ds_read_b32 v126, v154 offset:512
	ds_read_b32 v127, v154 offset:768
	ds_read_b32 v128, v154 offset:1024
	ds_read_b32 v129, v154 offset:1280
	ds_read_b32 v130, v154 offset:1536
	ds_read_b32 v131, v154 offset:1792
	v_lshlrev_b32_e32 v108, 16, v32
	v_and_b32_e32 v109, 0xffff0000, v32
	v_lshlrev_b32_e32 v110, 16, v40
	v_and_b32_e32 v111, 0xffff0000, v40
	v_lshlrev_b32_e32 v96, 16, v28
	v_and_b32_e32 v97, 0xffff0000, v28
	v_pk_add_f32 v[112:113], v[110:111], -1.0 op_sel_hi:[1,0]
	v_pk_mul_f32 v[114:115], v[12:13], v[108:109]
	v_pk_fma_f32 v[112:113], v[20:21], v[112:113], 1.0 op_sel_hi:[1,1,0]
	v_pk_mul_f32 v[88:89], v[44:45], v[114:115] op_sel_hi:[0,1]
	v_pk_mul_f32 v[72:73], v[112:113], v[108:109]
	v_pk_mul_f32 v[80:81], v[88:89], v[110:111]
	v_lshlrev_b32_e32 v108, 16, v33
	v_and_b32_e32 v109, 0xffff0000, v33
	v_lshlrev_b32_e32 v110, 16, v41
	v_and_b32_e32 v111, 0xffff0000, v41
	v_lshlrev_b32_e32 v98, 16, v29
	v_and_b32_e32 v99, 0xffff0000, v29
	v_pk_add_f32 v[112:113], v[110:111], -1.0 op_sel_hi:[1,0]
	v_pk_mul_f32 v[114:115], v[14:15], v[108:109]
	v_pk_fma_f32 v[112:113], v[22:23], v[112:113], 1.0 op_sel_hi:[1,1,0]
	v_pk_mul_f32 v[90:91], v[44:45], v[114:115] op_sel_hi:[0,1]
	v_pk_mul_f32 v[74:75], v[112:113], v[108:109]
	v_pk_mul_f32 v[82:83], v[90:91], v[110:111]
	v_lshlrev_b32_e32 v108, 16, v34
	v_and_b32_e32 v109, 0xffff0000, v34
	v_lshlrev_b32_e32 v110, 16, v42
	v_and_b32_e32 v111, 0xffff0000, v42
	v_lshlrev_b32_e32 v100, 16, v30
	v_and_b32_e32 v101, 0xffff0000, v30
	v_pk_add_f32 v[112:113], v[110:111], -1.0 op_sel_hi:[1,0]
	v_pk_mul_f32 v[114:115], v[16:17], v[108:109]
	v_pk_fma_f32 v[112:113], v[24:25], v[112:113], 1.0 op_sel_hi:[1,1,0]
	v_pk_mul_f32 v[92:93], v[44:45], v[114:115] op_sel_hi:[0,1]
	v_pk_mul_f32 v[76:77], v[112:113], v[108:109]
	v_pk_mul_f32 v[84:85], v[92:93], v[110:111]
	v_lshlrev_b32_e32 v108, 16, v35
	v_and_b32_e32 v109, 0xffff0000, v35
	v_lshlrev_b32_e32 v110, 16, v43
	v_and_b32_e32 v111, 0xffff0000, v43
	v_lshlrev_b32_e32 v102, 16, v31
	v_and_b32_e32 v103, 0xffff0000, v31
	v_pk_add_f32 v[112:113], v[110:111], -1.0 op_sel_hi:[1,0]
	v_pk_mul_f32 v[114:115], v[18:19], v[108:109]
	v_pk_fma_f32 v[112:113], v[26:27], v[112:113], 1.0 op_sel_hi:[1,1,0]
	v_pk_mul_f32 v[94:95], v[44:45], v[114:115] op_sel_hi:[0,1]
	v_pk_mul_f32 v[78:79], v[112:113], v[108:109]
	v_pk_mul_f32 v[86:87], v[94:95], v[110:111]
	v_lshlrev_b32_e32 v104, 16, v45
	v_and_b32_e32 v105, 0xffff0000, v45
	s_waitcnt lgkmcnt(0)
	v_add_f32_e32 v125, v124, v125
	v_add_f32_e32 v126, v125, v126
	v_add_f32_e32 v127, v126, v127
	v_add_f32_e32 v128, v127, v128
	v_add_f32_e32 v129, v128, v129
	v_add_f32_e32 v130, v129, v130
	v_add_f32_e32 v131, v130, v131
	s_and_b32 s72, s6, 3
	s_lshl_b32 s72, s72, 10
	v_add_u32_e32 v182, s72, v180
	v_add_u32_e32 v183, s72, v181
	ds_write_b32 v182, v131
	v_add_u32_e32 v184, 1, v146
	s_waitcnt lgkmcnt(0)
	ds_write_b32 v162, v184
	s_add_u32 s73, s6, 1
	s_mov_b32 s69, 0x100000

.Lsc_gf_go3:
	ds_read_b32 v185, v183
	ds_read_b32 v186, v183 offset:256
	ds_read_b32 v187, v183 offset:512
	s_waitcnt lgkmcnt(0)
	v_and_b32_e32 v185, v174, v185
	v_and_b32_e32 v186, v175, v186
	v_and_b32_e32 v187, v176, v187
	v_add_f32_e32 v185, v185, v186
	v_add_f32_e32 v185, v185, v187
	v_add_f32_e32 v124, v185, v124
	v_add_f32_e32 v125, v185, v125
	v_add_f32_e32 v126, v185, v126
	v_add_f32_e32 v127, v185, v127
	v_add_f32_e32 v128, v185, v128
	v_add_f32_e32 v129, v185, v129
	v_add_f32_e32 v130, v185, v130
	v_add_f32_e32 v131, v185, v131
	v_exp_f32_e64 v188, -v185
	v_exp_f32_e64 v124, -v124
	v_exp_f32_e64 v125, -v125
	v_exp_f32_e64 v126, -v126
	v_exp_f32_e64 v127, -v127
	v_exp_f32_e64 v128, -v128
	v_exp_f32_e64 v129, -v129
	v_exp_f32_e64 v130, -v130
	v_exp_f32_e64 v131, -v131
	s_nop 0
	ds_write_b32 v155, v188
	ds_write_b32 v155, v124 offset:256
	ds_write_b32 v155, v125 offset:512
	ds_write_b32 v155, v126 offset:768
	ds_write_b32 v155, v127 offset:1024
	ds_write_b32 v155, v128 offset:1280
	ds_write_b32 v155, v129 offset:1536
	ds_write_b32 v155, v130 offset:1792
	ds_write_b32 v155, v131 offset:2048
	v_mov_b32_e32 v161, v131
	s_waitcnt lgkmcnt(0)
	ds_read_b128 v[64:67], v153 offset:2048
	ds_read_b128 v[68:71], v153 offset:2176
	ds_read_b128 v[116:119], v153 offset:2304
	ds_read_b128 v[120:123], v153 offset:2432
	s_waitcnt lgkmcnt(0)
	v_rcp_f32_e32 v124, v116
	v_rcp_f32_e32 v125, v117
	v_rcp_f32_e32 v126, v118
	v_rcp_f32_e32 v127, v119
	v_rcp_f32_e32 v128, v120
	v_rcp_f32_e32 v129, v121
	v_rcp_f32_e32 v130, v122
	v_rcp_f32_e32 v131, v123
	s_nop 1
	v_pk_mul_f32 v[72:73], v[72:73], v[124:125]
	v_pk_mul_f32 v[80:81], v[80:81], v[124:125]
	v_pk_mul_f32 v[88:89], v[88:89], v[64:65]
	v_pk_mul_f32 v[96:97], v[96:97], v[116:117]
	v_pk_mul_f32 v[74:75], v[74:75], v[126:127]
	v_pk_mul_f32 v[82:83], v[82:83], v[126:127]
	v_pk_mul_f32 v[90:91], v[90:91], v[66:67]
	v_pk_mul_f32 v[98:99], v[98:99], v[118:119]
	v_pk_mul_f32 v[76:77], v[76:77], v[128:129]
	v_pk_mul_f32 v[84:85], v[84:85], v[128:129]
	v_pk_mul_f32 v[92:93], v[92:93], v[68:69]
	v_pk_mul_f32 v[100:101], v[100:101], v[120:121]
	v_pk_mul_f32 v[78:79], v[78:79], v[130:131]
	v_pk_mul_f32 v[86:87], v[86:87], v[130:131]
	v_pk_mul_f32 v[94:95], v[94:95], v[70:71]
	v_pk_mul_f32 v[102:103], v[102:103], v[122:123]
	global_load_dwordx2 v[28:29], v5, s[36:37]
	global_load_dwordx2 v[30:31], v5, s[36:37] offset:64
	global_load_dwordx2 v[32:33], v5, s[38:39]
	global_load_dwordx2 v[34:35], v5, s[38:39] offset:64
	global_load_dwordx2 v[36:37], v5, s[40:41]
	global_load_dwordx2 v[38:39], v5, s[40:41] offset:64
	global_load_dwordx2 v[40:41], v5, s[42:43]
	global_load_dwordx2 v[42:43], v5, s[42:43] offset:64
	global_load_dword v44, v6, s[46:47]
	global_load_dword v45, v9, s[44:45]
	v_add_u32_e32 v5, s54, v5
	v_add_u32_e32 v6, s55, v6
	v_add_u32_e32 v9, s54, v9
	s_sub_u32 s65, s6, 1
	ds_read_b128 v[148:151], v144
	s_waitcnt lgkmcnt(0)
	v_min_u32_e32 v148, v148, v149
	v_min3_u32 v148, v148, v150, v151
	s_nop 1
	v_readfirstlane_b32 s68, v148
	s_cmp_ge_u32 s68, s65
	s_cbranch_scc1 .Lsc_G_gom0
	s_mov_b32 s69, 0x100000

.Lsc_G_gom0:
	ds_write_b32 v159, v161 offset:0
	ds_write_b128 v8, v[72:75] offset:0
	ds_write_b128 v8, v[76:79] offset:128
	ds_write_b128 v8, v[80:83] offset:256
	ds_write_b128 v8, v[84:87] offset:384
	ds_write2_b32 v138, v96, v97 offset0:1 offset1:3
	ds_write2_b32 v139, v88, v89 offset0:0 offset1:2
	ds_write2_b32 v138, v98, v99 offset0:65 offset1:67
	ds_write2_b32 v139, v90, v91 offset0:64 offset1:66
	ds_write2_b32 v138, v100, v101 offset0:33 offset1:35
	ds_write2_b32 v139, v92, v93 offset0:32 offset1:34
	ds_write2_b32 v138, v102, v103 offset0:97 offset1:99
	ds_write2_b32 v139, v94, v95 offset0:96 offset1:98
	ds_write2_b32 v142, v104, v105 offset1:36
	s_and_saveexec_b64 s[68:69], s[12:13]
	ds_write_b128 v158, v[88:91] offset:0
	ds_write_b128 v158, v[92:95] offset:128
	s_mov_b64 exec, s[68:69]
	ds_read_b128 v[106:109], v2 offset:0
	ds_read_b128 v[122:125], v2 offset:16384
	ds_read_b128 v[110:113], v3 offset:0
	ds_read_b128 v[126:129], v3 offset:16384
	ds_read_b128 v[114:117], v4 offset:0
	ds_read_b128 v[130:133], v4 offset:16384
	ds_read_b128 v[118:121], v10 offset:0
	ds_read_b128 v[134:137], v10 offset:16384
	s_waitcnt lgkmcnt(0)
	v_pk_add_f32 v[106:107], v[106:107], v[108:109]
	v_pk_add_f32 v[110:111], v[110:111], v[112:113]
	v_pk_add_f32 v[114:115], v[114:115], v[116:117]
	v_pk_add_f32 v[118:119], v[118:119], v[120:121]
	v_pk_add_f32 v[106:107], v[106:107], v[110:111]
	v_pk_add_f32 v[114:115], v[114:115], v[118:119]
	v_pk_add_f32 v[106:107], v[106:107], v[114:115]
	v_add_f32_e32 v64, v106, v107
	v_pk_add_f32 v[122:123], v[122:123], v[124:125]
	v_pk_add_f32 v[126:127], v[126:127], v[128:129]
	v_pk_add_f32 v[130:131], v[130:131], v[132:133]
	v_pk_add_f32 v[134:135], v[134:135], v[136:137]
	v_pk_add_f32 v[122:123], v[122:123], v[126:127]
	v_pk_add_f32 v[130:131], v[130:131], v[134:135]
	v_pk_add_f32 v[122:123], v[122:123], v[130:131]
	v_add_f32_e32 v65, v122, v123
	global_store_dword v7, v64, s[48:49]
	global_store_dword v165, v65, s[48:49]
	v_add_u32_e32 v7, s64, v7
	v_add_u32_e32 v165, s64, v165
	s_add_i32 s6, s6, 1
	v_add_u32_e32 v146, 1, v146
	s_waitcnt lgkmcnt(0)
	ds_write_b32 v145, v146
	s_waitcnt vmcnt(10)
	v_lshlrev_b32_e32 v64, 16, v54
	v_and_b32_e32 v65, 0xffff0000, v54
	v_mul_f32_e32 v64, 0x3fb8aa3b, v64
	v_mul_f32_e32 v65, 0x3fb8aa3b, v65
	v_lshlrev_b32_e32 v66, 16, v55
	v_and_b32_e32 v67, 0xffff0000, v55
	v_mul_f32_e32 v66, 0x3fb8aa3b, v66
	v_mul_f32_e32 v67, 0x3fb8aa3b, v67
	v_lshlrev_b32_e32 v68, 16, v56
	v_and_b32_e32 v69, 0xffff0000, v56
	v_mul_f32_e32 v68, 0x3fb8aa3b, v68
	v_mul_f32_e32 v69, 0x3fb8aa3b, v69
	v_lshlrev_b32_e32 v70, 16, v57
	v_and_b32_e32 v71, 0xffff0000, v57
	v_mul_f32_e32 v70, 0x3fb8aa3b, v70
	v_mul_f32_e32 v71, 0x3fb8aa3b, v71
	ds_write_b128 v153, v[64:67]
	ds_write_b128 v153, v[68:71] offset:128
	s_waitcnt lgkmcnt(0)
	ds_read_b32 v124, v154 offset:0
	ds_read_b32 v125, v154 offset:256
	ds_read_b32 v126, v154 offset:512
	ds_read_b32 v127, v154 offset:768
	ds_read_b32 v128, v154 offset:1024
	ds_read_b32 v129, v154 offset:1280
	ds_read_b32 v130, v154 offset:1536
	ds_read_b32 v131, v154 offset:1792
	v_lshlrev_b32_e32 v108, 16, v50
	v_and_b32_e32 v109, 0xffff0000, v50
	v_lshlrev_b32_e32 v110, 16, v58
	v_and_b32_e32 v111, 0xffff0000, v58
	v_lshlrev_b32_e32 v96, 16, v46
	v_and_b32_e32 v97, 0xffff0000, v46
	v_pk_add_f32 v[112:113], v[110:111], -1.0 op_sel_hi:[1,0]
	v_pk_mul_f32 v[114:115], v[12:13], v[108:109]
	v_pk_fma_f32 v[112:113], v[20:21], v[112:113], 1.0 op_sel_hi:[1,1,0]
	v_pk_mul_f32 v[88:89], v[62:63], v[114:115] op_sel_hi:[0,1]
	v_pk_mul_f32 v[72:73], v[112:113], v[108:109]
	v_pk_mul_f32 v[80:81], v[88:89], v[110:111]
	v_lshlrev_b32_e32 v108, 16, v51
	v_and_b32_e32 v109, 0xffff0000, v51
	v_lshlrev_b32_e32 v110, 16, v59
	v_and_b32_e32 v111, 0xffff0000, v59
	v_lshlrev_b32_e32 v98, 16, v47
	v_and_b32_e32 v99, 0xffff0000, v47
	v_pk_add_f32 v[112:113], v[110:111], -1.0 op_sel_hi:[1,0]
	v_pk_mul_f32 v[114:115], v[14:15], v[108:109]
	v_pk_fma_f32 v[112:113], v[22:23], v[112:113], 1.0 op_sel_hi:[1,1,0]
	v_pk_mul_f32 v[90:91], v[62:63], v[114:115] op_sel_hi:[0,1]
	v_pk_mul_f32 v[74:75], v[112:113], v[108:109]
	v_pk_mul_f32 v[82:83], v[90:91], v[110:111]
	v_lshlrev_b32_e32 v108, 16, v52
	v_and_b32_e32 v109, 0xffff0000, v52
	v_lshlrev_b32_e32 v110, 16, v60
	v_and_b32_e32 v111, 0xffff0000, v60
	v_lshlrev_b32_e32 v100, 16, v48
	v_and_b32_e32 v101, 0xffff0000, v48
	v_pk_add_f32 v[112:113], v[110:111], -1.0 op_sel_hi:[1,0]
	v_pk_mul_f32 v[114:115], v[16:17], v[108:109]
	v_pk_fma_f32 v[112:113], v[24:25], v[112:113], 1.0 op_sel_hi:[1,1,0]
	v_pk_mul_f32 v[92:93], v[62:63], v[114:115] op_sel_hi:[0,1]
	v_pk_mul_f32 v[76:77], v[112:113], v[108:109]
	v_pk_mul_f32 v[84:85], v[92:93], v[110:111]
	v_lshlrev_b32_e32 v108, 16, v53
	v_and_b32_e32 v109, 0xffff0000, v53
	v_lshlrev_b32_e32 v110, 16, v61
	v_and_b32_e32 v111, 0xffff0000, v61
	v_lshlrev_b32_e32 v102, 16, v49
	v_and_b32_e32 v103, 0xffff0000, v49
	v_pk_add_f32 v[112:113], v[110:111], -1.0 op_sel_hi:[1,0]
	v_pk_mul_f32 v[114:115], v[18:19], v[108:109]
	v_pk_fma_f32 v[112:113], v[26:27], v[112:113], 1.0 op_sel_hi:[1,1,0]
	v_pk_mul_f32 v[94:95], v[62:63], v[114:115] op_sel_hi:[0,1]
	v_pk_mul_f32 v[78:79], v[112:113], v[108:109]
	v_pk_mul_f32 v[86:87], v[94:95], v[110:111]
	v_lshlrev_b32_e32 v104, 16, v63
	v_and_b32_e32 v105, 0xffff0000, v63
	s_waitcnt lgkmcnt(0)
	v_add_f32_e32 v125, v124, v125
	v_add_f32_e32 v126, v125, v126
	v_add_f32_e32 v127, v126, v127
	v_add_f32_e32 v128, v127, v128
	v_add_f32_e32 v129, v128, v129
	v_add_f32_e32 v130, v129, v130
	v_add_f32_e32 v131, v130, v131
	s_and_b32 s72, s6, 3
	s_lshl_b32 s72, s72, 10
	v_add_u32_e32 v182, s72, v180
	v_add_u32_e32 v183, s72, v181
	ds_write_b32 v182, v131
	v_add_u32_e32 v184, 1, v146
	s_waitcnt lgkmcnt(0)
	ds_write_b32 v162, v184
	s_add_u32 s73, s6, 1
	s_mov_b32 s69, 0x100000

.Lsc_gf_go4:
	ds_read_b32 v185, v183
	ds_read_b32 v186, v183 offset:256
	ds_read_b32 v187, v183 offset:512
	s_waitcnt lgkmcnt(0)
	v_and_b32_e32 v185, v174, v185
	v_and_b32_e32 v186, v175, v186
	v_and_b32_e32 v187, v176, v187
	v_add_f32_e32 v185, v185, v186
	v_add_f32_e32 v185, v185, v187
	v_add_f32_e32 v124, v185, v124
	v_add_f32_e32 v125, v185, v125
	v_add_f32_e32 v126, v185, v126
	v_add_f32_e32 v127, v185, v127
	v_add_f32_e32 v128, v185, v128
	v_add_f32_e32 v129, v185, v129
	v_add_f32_e32 v130, v185, v130
	v_add_f32_e32 v131, v185, v131
	v_exp_f32_e64 v188, -v185
	v_exp_f32_e64 v124, -v124
	v_exp_f32_e64 v125, -v125
	v_exp_f32_e64 v126, -v126
	v_exp_f32_e64 v127, -v127
	v_exp_f32_e64 v128, -v128
	v_exp_f32_e64 v129, -v129
	v_exp_f32_e64 v130, -v130
	v_exp_f32_e64 v131, -v131
	s_nop 0
	ds_write_b32 v155, v188
	ds_write_b32 v155, v124 offset:256
	ds_write_b32 v155, v125 offset:512
	ds_write_b32 v155, v126 offset:768
	ds_write_b32 v155, v127 offset:1024
	ds_write_b32 v155, v128 offset:1280
	ds_write_b32 v155, v129 offset:1536
	ds_write_b32 v155, v130 offset:1792
	ds_write_b32 v155, v131 offset:2048
	v_mov_b32_e32 v161, v131
	s_waitcnt lgkmcnt(0)
	ds_read_b128 v[64:67], v153 offset:2048
	ds_read_b128 v[68:71], v153 offset:2176
	ds_read_b128 v[116:119], v153 offset:2304
	ds_read_b128 v[120:123], v153 offset:2432
	s_waitcnt lgkmcnt(0)
	v_rcp_f32_e32 v124, v116
	v_rcp_f32_e32 v125, v117
	v_rcp_f32_e32 v126, v118
	v_rcp_f32_e32 v127, v119
	v_rcp_f32_e32 v128, v120
	v_rcp_f32_e32 v129, v121
	v_rcp_f32_e32 v130, v122
	v_rcp_f32_e32 v131, v123
	s_nop 1
	v_pk_mul_f32 v[72:73], v[72:73], v[124:125]
	v_pk_mul_f32 v[80:81], v[80:81], v[124:125]
	v_pk_mul_f32 v[88:89], v[88:89], v[64:65]
	v_pk_mul_f32 v[96:97], v[96:97], v[116:117]
	v_pk_mul_f32 v[74:75], v[74:75], v[126:127]
	v_pk_mul_f32 v[82:83], v[82:83], v[126:127]
	v_pk_mul_f32 v[90:91], v[90:91], v[66:67]
	v_pk_mul_f32 v[98:99], v[98:99], v[118:119]
	v_pk_mul_f32 v[76:77], v[76:77], v[128:129]
	v_pk_mul_f32 v[84:85], v[84:85], v[128:129]
	v_pk_mul_f32 v[92:93], v[92:93], v[68:69]
	v_pk_mul_f32 v[100:101], v[100:101], v[120:121]
	v_pk_mul_f32 v[78:79], v[78:79], v[130:131]
	v_pk_mul_f32 v[86:87], v[86:87], v[130:131]
	v_pk_mul_f32 v[94:95], v[94:95], v[70:71]
	v_pk_mul_f32 v[102:103], v[102:103], v[122:123]
	global_load_dwordx2 v[46:47], v5, s[36:37]
	global_load_dwordx2 v[48:49], v5, s[36:37] offset:64
	global_load_dwordx2 v[50:51], v5, s[38:39]
	global_load_dwordx2 v[52:53], v5, s[38:39] offset:64
	global_load_dwordx2 v[54:55], v5, s[40:41]
	global_load_dwordx2 v[56:57], v5, s[40:41] offset:64
	global_load_dwordx2 v[58:59], v5, s[42:43]
	global_load_dwordx2 v[60:61], v5, s[42:43] offset:64
	global_load_dword v62, v6, s[46:47]
	global_load_dword v63, v9, s[44:45]
	v_add_u32_e32 v5, s54, v5
	v_add_u32_e32 v6, s55, v6
	v_add_u32_e32 v9, s54, v9
	s_sub_u32 s65, s6, 1
	ds_read_b128 v[148:151], v144
	s_waitcnt lgkmcnt(0)
	v_min_u32_e32 v148, v148, v149
	v_min3_u32 v148, v148, v150, v151
	s_nop 1
	v_readfirstlane_b32 s68, v148
	s_cmp_ge_u32 s68, s65
	s_cbranch_scc1 .Lsc_G_gom1
	s_mov_b32 s69, 0x100000

.Lsc_G_gom1:
	ds_write_b32 v159, v161 offset:34816
	ds_write_b128 v8, v[72:75] offset:34816
	ds_write_b128 v8, v[76:79] offset:34944
	ds_write_b128 v8, v[80:83] offset:35072
	ds_write_b128 v8, v[84:87] offset:35200
	ds_write2_b32 v140, v96, v97 offset0:1 offset1:3
	ds_write2_b32 v141, v88, v89 offset0:0 offset1:2
	ds_write2_b32 v140, v98, v99 offset0:65 offset1:67
	ds_write2_b32 v141, v90, v91 offset0:64 offset1:66
	ds_write2_b32 v140, v100, v101 offset0:33 offset1:35
	ds_write2_b32 v141, v92, v93 offset0:32 offset1:34
	ds_write2_b32 v140, v102, v103 offset0:97 offset1:99
	ds_write2_b32 v141, v94, v95 offset0:96 offset1:98
	ds_write2_b32 v143, v104, v105 offset1:36
	s_and_saveexec_b64 s[68:69], s[12:13]
	ds_write_b128 v158, v[88:91] offset:34816
	ds_write_b128 v158, v[92:95] offset:34944
	s_mov_b64 exec, s[68:69]
	ds_read_b128 v[106:109], v2 offset:32768
	ds_read_b128 v[122:125], v2 offset:49152
	ds_read_b128 v[110:113], v3 offset:32768
	ds_read_b128 v[126:129], v3 offset:49152
	ds_read_b128 v[114:117], v4 offset:32768
	ds_read_b128 v[130:133], v4 offset:49152
	ds_read_b128 v[118:121], v10 offset:32768
	ds_read_b128 v[134:137], v10 offset:49152
	s_waitcnt lgkmcnt(0)
	v_pk_add_f32 v[106:107], v[106:107], v[108:109]
	v_pk_add_f32 v[110:111], v[110:111], v[112:113]
	v_pk_add_f32 v[114:115], v[114:115], v[116:117]
	v_pk_add_f32 v[118:119], v[118:119], v[120:121]
	v_pk_add_f32 v[106:107], v[106:107], v[110:111]
	v_pk_add_f32 v[114:115], v[114:115], v[118:119]
	v_pk_add_f32 v[106:107], v[106:107], v[114:115]
	v_add_f32_e32 v64, v106, v107
	v_pk_add_f32 v[122:123], v[122:123], v[124:125]
	v_pk_add_f32 v[126:127], v[126:127], v[128:129]
	v_pk_add_f32 v[130:131], v[130:131], v[132:133]
	v_pk_add_f32 v[134:135], v[134:135], v[136:137]
	v_pk_add_f32 v[122:123], v[122:123], v[126:127]
	v_pk_add_f32 v[130:131], v[130:131], v[134:135]
	v_pk_add_f32 v[122:123], v[122:123], v[130:131]
	v_add_f32_e32 v65, v122, v123
	global_store_dword v7, v64, s[48:49]
	global_store_dword v165, v65, s[48:49]
	v_add_u32_e32 v7, s64, v7
	v_add_u32_e32 v165, s64, v165
	s_add_i32 s6, s6, 1
	v_add_u32_e32 v146, 1, v146
	s_waitcnt lgkmcnt(0)
	ds_write_b32 v145, v146
	s_cmp_lt_u32 s6, 0xfe
	s_cbranch_scc1 .Lsc_G_loop
	s_waitcnt vmcnt(10)
	v_lshlrev_b32_e32 v64, 16, v36
	v_and_b32_e32 v65, 0xffff0000, v36
	v_mul_f32_e32 v64, 0x3fb8aa3b, v64
	v_mul_f32_e32 v65, 0x3fb8aa3b, v65
	v_lshlrev_b32_e32 v66, 16, v37
	v_and_b32_e32 v67, 0xffff0000, v37
	v_mul_f32_e32 v66, 0x3fb8aa3b, v66
	v_mul_f32_e32 v67, 0x3fb8aa3b, v67
	v_lshlrev_b32_e32 v68, 16, v38
	v_and_b32_e32 v69, 0xffff0000, v38
	v_mul_f32_e32 v68, 0x3fb8aa3b, v68
	v_mul_f32_e32 v69, 0x3fb8aa3b, v69
	v_lshlrev_b32_e32 v70, 16, v39
	v_and_b32_e32 v71, 0xffff0000, v39
	v_mul_f32_e32 v70, 0x3fb8aa3b, v70
	v_mul_f32_e32 v71, 0x3fb8aa3b, v71
	ds_write_b128 v153, v[64:67]
	ds_write_b128 v153, v[68:71] offset:128
	s_waitcnt lgkmcnt(0)
	ds_read_b32 v124, v154 offset:0
	ds_read_b32 v125, v154 offset:256
	ds_read_b32 v126, v154 offset:512
	ds_read_b32 v127, v154 offset:768
	ds_read_b32 v128, v154 offset:1024
	ds_read_b32 v129, v154 offset:1280
	ds_read_b32 v130, v154 offset:1536
	ds_read_b32 v131, v154 offset:1792
	v_lshlrev_b32_e32 v108, 16, v32
	v_and_b32_e32 v109, 0xffff0000, v32
	v_lshlrev_b32_e32 v110, 16, v40
	v_and_b32_e32 v111, 0xffff0000, v40
	v_lshlrev_b32_e32 v96, 16, v28
	v_and_b32_e32 v97, 0xffff0000, v28
	v_pk_add_f32 v[112:113], v[110:111], -1.0 op_sel_hi:[1,0]
	v_pk_mul_f32 v[114:115], v[12:13], v[108:109]
	v_pk_fma_f32 v[112:113], v[20:21], v[112:113], 1.0 op_sel_hi:[1,1,0]
	v_pk_mul_f32 v[88:89], v[44:45], v[114:115] op_sel_hi:[0,1]
	v_pk_mul_f32 v[72:73], v[112:113], v[108:109]
	v_pk_mul_f32 v[80:81], v[88:89], v[110:111]
	v_lshlrev_b32_e32 v108, 16, v33
	v_and_b32_e32 v109, 0xffff0000, v33
	v_lshlrev_b32_e32 v110, 16, v41
	v_and_b32_e32 v111, 0xffff0000, v41
	v_lshlrev_b32_e32 v98, 16, v29
	v_and_b32_e32 v99, 0xffff0000, v29
	v_pk_add_f32 v[112:113], v[110:111], -1.0 op_sel_hi:[1,0]
	v_pk_mul_f32 v[114:115], v[14:15], v[108:109]
	v_pk_fma_f32 v[112:113], v[22:23], v[112:113], 1.0 op_sel_hi:[1,1,0]
	v_pk_mul_f32 v[90:91], v[44:45], v[114:115] op_sel_hi:[0,1]
	v_pk_mul_f32 v[74:75], v[112:113], v[108:109]
	v_pk_mul_f32 v[82:83], v[90:91], v[110:111]
	v_lshlrev_b32_e32 v108, 16, v34
	v_and_b32_e32 v109, 0xffff0000, v34
	v_lshlrev_b32_e32 v110, 16, v42
	v_and_b32_e32 v111, 0xffff0000, v42
	v_lshlrev_b32_e32 v100, 16, v30
	v_and_b32_e32 v101, 0xffff0000, v30
	v_pk_add_f32 v[112:113], v[110:111], -1.0 op_sel_hi:[1,0]
	v_pk_mul_f32 v[114:115], v[16:17], v[108:109]
	v_pk_fma_f32 v[112:113], v[24:25], v[112:113], 1.0 op_sel_hi:[1,1,0]
	v_pk_mul_f32 v[92:93], v[44:45], v[114:115] op_sel_hi:[0,1]
	v_pk_mul_f32 v[76:77], v[112:113], v[108:109]
	v_pk_mul_f32 v[84:85], v[92:93], v[110:111]
	v_lshlrev_b32_e32 v108, 16, v35
	v_and_b32_e32 v109, 0xffff0000, v35
	v_lshlrev_b32_e32 v110, 16, v43
	v_and_b32_e32 v111, 0xffff0000, v43
	v_lshlrev_b32_e32 v102, 16, v31
	v_and_b32_e32 v103, 0xffff0000, v31
	v_pk_add_f32 v[112:113], v[110:111], -1.0 op_sel_hi:[1,0]
	v_pk_mul_f32 v[114:115], v[18:19], v[108:109]
	v_pk_fma_f32 v[112:113], v[26:27], v[112:113], 1.0 op_sel_hi:[1,1,0]
	v_pk_mul_f32 v[94:95], v[44:45], v[114:115] op_sel_hi:[0,1]
	v_pk_mul_f32 v[78:79], v[112:113], v[108:109]
	v_pk_mul_f32 v[86:87], v[94:95], v[110:111]
	v_lshlrev_b32_e32 v104, 16, v45
	v_and_b32_e32 v105, 0xffff0000, v45
	s_waitcnt lgkmcnt(0)
	v_add_f32_e32 v125, v124, v125
	v_add_f32_e32 v126, v125, v126
	v_add_f32_e32 v127, v126, v127
	v_add_f32_e32 v128, v127, v128
	v_add_f32_e32 v129, v128, v129
	v_add_f32_e32 v130, v129, v130
	v_add_f32_e32 v131, v130, v131
	s_and_b32 s72, s6, 3
	s_lshl_b32 s72, s72, 10
	v_add_u32_e32 v182, s72, v180
	v_add_u32_e32 v183, s72, v181
	ds_write_b32 v182, v131
	v_add_u32_e32 v184, 1, v146
	s_waitcnt lgkmcnt(0)
	ds_write_b32 v162, v184
	s_add_u32 s73, s6, 1
	s_mov_b32 s69, 0x100000

.Lsc_gf_go5:
	ds_read_b32 v185, v183
	ds_read_b32 v186, v183 offset:256
	ds_read_b32 v187, v183 offset:512
	s_waitcnt lgkmcnt(0)
	v_and_b32_e32 v185, v174, v185
	v_and_b32_e32 v186, v175, v186
	v_and_b32_e32 v187, v176, v187
	v_add_f32_e32 v185, v185, v186
	v_add_f32_e32 v185, v185, v187
	v_add_f32_e32 v124, v185, v124
	v_add_f32_e32 v125, v185, v125
	v_add_f32_e32 v126, v185, v126
	v_add_f32_e32 v127, v185, v127
	v_add_f32_e32 v128, v185, v128
	v_add_f32_e32 v129, v185, v129
	v_add_f32_e32 v130, v185, v130
	v_add_f32_e32 v131, v185, v131
	v_exp_f32_e64 v188, -v185
	v_exp_f32_e64 v124, -v124
	v_exp_f32_e64 v125, -v125
	v_exp_f32_e64 v126, -v126
	v_exp_f32_e64 v127, -v127
	v_exp_f32_e64 v128, -v128
	v_exp_f32_e64 v129, -v129
	v_exp_f32_e64 v130, -v130
	v_exp_f32_e64 v131, -v131
	s_nop 0
	ds_write_b32 v155, v188
	ds_write_b32 v155, v124 offset:256
	ds_write_b32 v155, v125 offset:512
	ds_write_b32 v155, v126 offset:768
	ds_write_b32 v155, v127 offset:1024
	ds_write_b32 v155, v128 offset:1280
	ds_write_b32 v155, v129 offset:1536
	ds_write_b32 v155, v130 offset:1792
	ds_write_b32 v155, v131 offset:2048
	v_mov_b32_e32 v161, v131
	s_waitcnt lgkmcnt(0)
	ds_read_b128 v[64:67], v153 offset:2048
	ds_read_b128 v[68:71], v153 offset:2176
	ds_read_b128 v[116:119], v153 offset:2304
	ds_read_b128 v[120:123], v153 offset:2432
	s_waitcnt lgkmcnt(0)
	v_rcp_f32_e32 v124, v116
	v_rcp_f32_e32 v125, v117
	v_rcp_f32_e32 v126, v118
	v_rcp_f32_e32 v127, v119
	v_rcp_f32_e32 v128, v120
	v_rcp_f32_e32 v129, v121
	v_rcp_f32_e32 v130, v122
	v_rcp_f32_e32 v131, v123
	s_nop 1
	v_pk_mul_f32 v[72:73], v[72:73], v[124:125]
	v_pk_mul_f32 v[80:81], v[80:81], v[124:125]
	v_pk_mul_f32 v[88:89], v[88:89], v[64:65]
	v_pk_mul_f32 v[96:97], v[96:97], v[116:117]
	v_pk_mul_f32 v[74:75], v[74:75], v[126:127]
	v_pk_mul_f32 v[82:83], v[82:83], v[126:127]
	v_pk_mul_f32 v[90:91], v[90:91], v[66:67]
	v_pk_mul_f32 v[98:99], v[98:99], v[118:119]
	v_pk_mul_f32 v[76:77], v[76:77], v[128:129]
	v_pk_mul_f32 v[84:85], v[84:85], v[128:129]
	v_pk_mul_f32 v[92:93], v[92:93], v[68:69]
	v_pk_mul_f32 v[100:101], v[100:101], v[120:121]
	v_pk_mul_f32 v[78:79], v[78:79], v[130:131]
	v_pk_mul_f32 v[86:87], v[86:87], v[130:131]
	v_pk_mul_f32 v[94:95], v[94:95], v[70:71]
	v_pk_mul_f32 v[102:103], v[102:103], v[122:123]
	s_sub_u32 s65, s6, 1
	ds_read_b128 v[148:151], v144
	s_waitcnt lgkmcnt(0)
	v_min_u32_e32 v148, v148, v149
	v_min3_u32 v148, v148, v150, v151
	s_nop 1
	v_readfirstlane_b32 s68, v148
	s_cmp_ge_u32 s68, s65
	s_cbranch_scc1 .Lsc_G_goz0
	s_mov_b32 s69, 0x100000

.Lsc_G_goz0:
	ds_write_b32 v159, v161 offset:0
	ds_write_b128 v8, v[72:75] offset:0
	ds_write_b128 v8, v[76:79] offset:128
	ds_write_b128 v8, v[80:83] offset:256
	ds_write_b128 v8, v[84:87] offset:384
	ds_write2_b32 v138, v96, v97 offset0:1 offset1:3
	ds_write2_b32 v139, v88, v89 offset0:0 offset1:2
	ds_write2_b32 v138, v98, v99 offset0:65 offset1:67
	ds_write2_b32 v139, v90, v91 offset0:64 offset1:66
	ds_write2_b32 v138, v100, v101 offset0:33 offset1:35
	ds_write2_b32 v139, v92, v93 offset0:32 offset1:34
	ds_write2_b32 v138, v102, v103 offset0:97 offset1:99
	ds_write2_b32 v139, v94, v95 offset0:96 offset1:98
	ds_write2_b32 v142, v104, v105 offset1:36
	s_and_saveexec_b64 s[68:69], s[12:13]
	ds_write_b128 v158, v[88:91] offset:0
	ds_write_b128 v158, v[92:95] offset:128
	s_mov_b64 exec, s[68:69]
	ds_read_b128 v[106:109], v2 offset:0
	ds_read_b128 v[122:125], v2 offset:16384
	ds_read_b128 v[110:113], v3 offset:0
	ds_read_b128 v[126:129], v3 offset:16384
	ds_read_b128 v[114:117], v4 offset:0
	ds_read_b128 v[130:133], v4 offset:16384
	ds_read_b128 v[118:121], v10 offset:0
	ds_read_b128 v[134:137], v10 offset:16384
	s_waitcnt lgkmcnt(0)
	v_pk_add_f32 v[106:107], v[106:107], v[108:109]
	v_pk_add_f32 v[110:111], v[110:111], v[112:113]
	v_pk_add_f32 v[114:115], v[114:115], v[116:117]
	v_pk_add_f32 v[118:119], v[118:119], v[120:121]
	v_pk_add_f32 v[106:107], v[106:107], v[110:111]
	v_pk_add_f32 v[114:115], v[114:115], v[118:119]
	v_pk_add_f32 v[106:107], v[106:107], v[114:115]
	v_add_f32_e32 v64, v106, v107
	v_pk_add_f32 v[122:123], v[122:123], v[124:125]
	v_pk_add_f32 v[126:127], v[126:127], v[128:129]
	v_pk_add_f32 v[130:131], v[130:131], v[132:133]
	v_pk_add_f32 v[134:135], v[134:135], v[136:137]
	v_pk_add_f32 v[122:123], v[122:123], v[126:127]
	v_pk_add_f32 v[130:131], v[130:131], v[134:135]
	v_pk_add_f32 v[122:123], v[122:123], v[130:131]
	v_add_f32_e32 v65, v122, v123
	global_store_dword v7, v64, s[48:49]
	global_store_dword v165, v65, s[48:49]
	v_add_u32_e32 v7, s64, v7
	v_add_u32_e32 v165, s64, v165
	s_add_i32 s6, s6, 1
	v_add_u32_e32 v146, 1, v146
	s_waitcnt lgkmcnt(0)
	ds_write_b32 v145, v146
	s_waitcnt vmcnt(0)
	v_lshlrev_b32_e32 v64, 16, v54
	v_and_b32_e32 v65, 0xffff0000, v54
	v_mul_f32_e32 v64, 0x3fb8aa3b, v64
	v_mul_f32_e32 v65, 0x3fb8aa3b, v65
	v_lshlrev_b32_e32 v66, 16, v55
	v_and_b32_e32 v67, 0xffff0000, v55
	v_mul_f32_e32 v66, 0x3fb8aa3b, v66
	v_mul_f32_e32 v67, 0x3fb8aa3b, v67
	v_lshlrev_b32_e32 v68, 16, v56
	v_and_b32_e32 v69, 0xffff0000, v56
	v_mul_f32_e32 v68, 0x3fb8aa3b, v68
	v_mul_f32_e32 v69, 0x3fb8aa3b, v69
	v_lshlrev_b32_e32 v70, 16, v57
	v_and_b32_e32 v71, 0xffff0000, v57
	v_mul_f32_e32 v70, 0x3fb8aa3b, v70
	v_mul_f32_e32 v71, 0x3fb8aa3b, v71
	ds_write_b128 v153, v[64:67]
	ds_write_b128 v153, v[68:71] offset:128
	s_waitcnt lgkmcnt(0)
	ds_read_b32 v124, v154 offset:0
	ds_read_b32 v125, v154 offset:256
	ds_read_b32 v126, v154 offset:512
	ds_read_b32 v127, v154 offset:768
	ds_read_b32 v128, v154 offset:1024
	ds_read_b32 v129, v154 offset:1280
	ds_read_b32 v130, v154 offset:1536
	ds_read_b32 v131, v154 offset:1792
	v_lshlrev_b32_e32 v108, 16, v50
	v_and_b32_e32 v109, 0xffff0000, v50
	v_lshlrev_b32_e32 v110, 16, v58
	v_and_b32_e32 v111, 0xffff0000, v58
	v_lshlrev_b32_e32 v96, 16, v46
	v_and_b32_e32 v97, 0xffff0000, v46
	v_pk_add_f32 v[112:113], v[110:111], -1.0 op_sel_hi:[1,0]
	v_pk_mul_f32 v[114:115], v[12:13], v[108:109]
	v_pk_fma_f32 v[112:113], v[20:21], v[112:113], 1.0 op_sel_hi:[1,1,0]
	v_pk_mul_f32 v[88:89], v[62:63], v[114:115] op_sel_hi:[0,1]
	v_pk_mul_f32 v[72:73], v[112:113], v[108:109]
	v_pk_mul_f32 v[80:81], v[88:89], v[110:111]
	v_lshlrev_b32_e32 v108, 16, v51
	v_and_b32_e32 v109, 0xffff0000, v51
	v_lshlrev_b32_e32 v110, 16, v59
	v_and_b32_e32 v111, 0xffff0000, v59
	v_lshlrev_b32_e32 v98, 16, v47
	v_and_b32_e32 v99, 0xffff0000, v47
	v_pk_add_f32 v[112:113], v[110:111], -1.0 op_sel_hi:[1,0]
	v_pk_mul_f32 v[114:115], v[14:15], v[108:109]
	v_pk_fma_f32 v[112:113], v[22:23], v[112:113], 1.0 op_sel_hi:[1,1,0]
	v_pk_mul_f32 v[90:91], v[62:63], v[114:115] op_sel_hi:[0,1]
	v_pk_mul_f32 v[74:75], v[112:113], v[108:109]
	v_pk_mul_f32 v[82:83], v[90:91], v[110:111]
	v_lshlrev_b32_e32 v108, 16, v52
	v_and_b32_e32 v109, 0xffff0000, v52
	v_lshlrev_b32_e32 v110, 16, v60
	v_and_b32_e32 v111, 0xffff0000, v60
	v_lshlrev_b32_e32 v100, 16, v48
	v_and_b32_e32 v101, 0xffff0000, v48
	v_pk_add_f32 v[112:113], v[110:111], -1.0 op_sel_hi:[1,0]
	v_pk_mul_f32 v[114:115], v[16:17], v[108:109]
	v_pk_fma_f32 v[112:113], v[24:25], v[112:113], 1.0 op_sel_hi:[1,1,0]
	v_pk_mul_f32 v[92:93], v[62:63], v[114:115] op_sel_hi:[0,1]
	v_pk_mul_f32 v[76:77], v[112:113], v[108:109]
	v_pk_mul_f32 v[84:85], v[92:93], v[110:111]
	v_lshlrev_b32_e32 v108, 16, v53
	v_and_b32_e32 v109, 0xffff0000, v53
	v_lshlrev_b32_e32 v110, 16, v61
	v_and_b32_e32 v111, 0xffff0000, v61
	v_lshlrev_b32_e32 v102, 16, v49
	v_and_b32_e32 v103, 0xffff0000, v49
	v_pk_add_f32 v[112:113], v[110:111], -1.0 op_sel_hi:[1,0]
	v_pk_mul_f32 v[114:115], v[18:19], v[108:109]
	v_pk_fma_f32 v[112:113], v[26:27], v[112:113], 1.0 op_sel_hi:[1,1,0]
	v_pk_mul_f32 v[94:95], v[62:63], v[114:115] op_sel_hi:[0,1]
	v_pk_mul_f32 v[78:79], v[112:113], v[108:109]
	v_pk_mul_f32 v[86:87], v[94:95], v[110:111]
	v_lshlrev_b32_e32 v104, 16, v63
	v_and_b32_e32 v105, 0xffff0000, v63
	s_waitcnt lgkmcnt(0)
	v_add_f32_e32 v125, v124, v125
	v_add_f32_e32 v126, v125, v126
	v_add_f32_e32 v127, v126, v127
	v_add_f32_e32 v128, v127, v128
	v_add_f32_e32 v129, v128, v129
	v_add_f32_e32 v130, v129, v130
	v_add_f32_e32 v131, v130, v131
	s_and_b32 s72, s6, 3
	s_lshl_b32 s72, s72, 10
	v_add_u32_e32 v182, s72, v180
	v_add_u32_e32 v183, s72, v181
	ds_write_b32 v182, v131
	v_add_u32_e32 v184, 1, v146
	s_waitcnt lgkmcnt(0)
	ds_write_b32 v162, v184
	s_add_u32 s73, s6, 1
	s_mov_b32 s69, 0x100000
